# MLA loop: waves 4-7 run a staggered stream (tile write + barrier between the QK/softmax part and the PV part), waves 0-3 unchanged
# speedup vs baseline: 1.0273x; 1.0118x over previous
; #define SLOAD() do { vs0 = *(const bf16x8*)(Vh + voff); vs1 = *(const bf16x8*)(Vh + voff + 32u * (unsigned)ldv); \
;     ks0 = *(const bf16x8*)(Kh + koff); ks1 = *(const bf16x8*)(Kh + koff + 32u * (unsigned)ldk); \
;     if constexpr (NR > 0) { kr = *(const bf16x8*)(Krh + kroff); kroff += 64u * 64u; } voff += 64u * (unsigned)ldv; koff += 64u * (unsigned)ldk; } while (0)
; #define SWRITE(b) do { *(bf16x8*)(V_lds + (b) * SHM_V + vst0) = vs0; *(bf16x8*)(V_lds + (b) * SHM_V + vst1) = vs1; const int kc = sc * 2;  \
;     *(bf16x8*)(K_lds + (b) * SHM_K + KSWZ(sr, kc)) = ks0; *(bf16x8*)(K_lds + (b) * SHM_K + KSWZ(32 + sr, kc)) = ks1; \
;     if constexpr (NR > 0) *(bf16x8*)(Kr_lds + (b) * SHM_KR + krst) = kr; } while (0)
; __device__ __forceinline__ v8i32 cat8(v4i32 a, v4i32 b) { return (v8i32){a[0], a[1], a[2], a[3], b[0], b[1], b[2], b[3]}; }
; __device__ __forceinline__ void attn_unit7(const unsigned char* __restrict__ Q8, int ldq, const unsigned char* __restrict__ Kn8, int ldk, const unsigned char* __restrict__ Kr8, ...
;     ...
;   float m_reg = 0.f, l_reg = 0; f32x16 o[4] = {}; v8i32 qf[3];
;   { const unsigned char* Qw = Q8 + (unsigned)((wid * 32 + r32) * ldq + hi * 32);
; #pragma unroll
;     for (int s = 0; s < 3; ++s) qf[s] = cat8(*reinterpret_cast<const v4i32*>(Qw + s * 64), *reinterpret_cast<const v4i32*>(Qw + s * 64 + 16)); }
;   const int vtr = tid >> 2, vtc = tid & 3, vtst = vtr * 64 + ((vtc ^ ((vtr >> 2) & 3)) << 4);
;   const int knr = tid >> 3, knc = tid & 7, knst = KN8SW(knr, knc);
;   const int krr = (tid >> 2) & 63, krc = tid & 3, krst = KR8SW(krr, krc);
;   const bool krw = tid < 256;
;   unsigned vtoff = (unsigned)(tid * 16), knoff = (unsigned)(knr * ldk + knc * 16), kroff = (unsigned)(krr * 64 + krc * 16);
;   v4i32 vt, kn, kr;
;     ...
;   f32x16 pA0, pA1, pB0, pB1; float alA, alB; v8i32 p8;
;   SLOAD(); SWRITE(0); __syncthreads();
;   SLOAD();
;   qkt9(pA0, pA1, Kn_lds, Kr_lds, qf, 7.0f - m_reg, r32, hi); partialSM9(pA0, pA1, m_reg, alA, thr_raw);
;   SWRITE(1); __syncthreads();
;   for (int j = 1; j + 1 < NT; j += 2) {
;     SLOAD();
;     qkt9(pB0, pB1, Kn_lds + 8192, Kr_lds + 4096, qf, 7.0f - m_reg, r32, hi);
;     finishSM9(pA0, pA1, alA, l_reg, p8);
;     pv8(o, Vt_lds, p8, r32, hi); partialSM9(pB0, pB1, m_reg, alB, thr_raw);
.LBB0_1320:
	s_or_b64 exec, exec, s[20:21]
	v_and_b32_e32 v0, 0x3fffffc0, v12
	s_mov_b32 s20, 0x60000
	v_lshl_add_u32 v187, v0, 2, 0
	v_add3_u32 v178, v13, v14, s20
	v_add_u32_e32 v0, v15, v16
	v_mov_b32_e32 v14, v1
	v_mov_b32_e32 v15, v1
	v_and_b32_e32 v184, 63, v12
	v_lshl_add_u64 v[180:181], s[12:13], 0, v[0:1]
	v_mov_b32_e32 v0, v1
	v_mov_b32_e32 v2, v1
	v_mov_b32_e32 v3, v1
	v_mov_b32_e32 v4, v1
	v_mov_b32_e32 v5, v1
	v_mov_b32_e32 v6, v1
	v_mov_b32_e32 v7, v1
	v_mov_b32_e32 v8, v1
	v_mov_b32_e32 v9, v1
	v_mov_b32_e32 v10, v1
	v_mov_b32_e32 v11, v1
	v_mov_b32_e32 v12, v1
	v_mov_b32_e32 v13, v1
	v_mov_b64_e32 v[64:65], v[14:15]
	v_mov_b64_e32 v[48:49], v[14:15]
	v_mov_b64_e32 v[32:33], v[14:15]
	v_mov_b64_e32 v[62:63], v[12:13]
	v_mov_b64_e32 v[60:61], v[10:11]
	v_mov_b64_e32 v[58:59], v[8:9]
	v_mov_b64_e32 v[56:57], v[6:7]
	v_mov_b64_e32 v[54:55], v[4:5]
	v_mov_b64_e32 v[52:53], v[2:3]
	v_mov_b64_e32 v[50:51], v[0:1]
	v_mov_b64_e32 v[46:47], v[12:13]
	v_mov_b64_e32 v[44:45], v[10:11]
	v_mov_b64_e32 v[42:43], v[8:9]
	v_mov_b64_e32 v[40:41], v[6:7]
	v_mov_b64_e32 v[38:39], v[4:5]
	v_mov_b64_e32 v[36:37], v[2:3]
	v_mov_b64_e32 v[34:35], v[0:1]
	v_mov_b64_e32 v[30:31], v[12:13]
	v_mov_b64_e32 v[28:29], v[10:11]
	v_mov_b64_e32 v[26:27], v[8:9]
	v_mov_b64_e32 v[24:25], v[6:7]
	v_mov_b64_e32 v[22:23], v[4:5]
	v_mov_b64_e32 v[20:21], v[2:3]
	v_mov_b64_e32 v[18:19], v[0:1]
	v_mov_b64_e32 v[16:17], v[14:15]
	s_lshl_b32 s29, s29, 8
	v_cmp_gt_u32_e64 s[40:41], 32, v184
	v_lshl_add_u32 v208, v183, 2, v187
	v_lshlrev_b32_e32 v207, 4, v175
	v_add_u32_e32 v176, 0x6000, v174
	v_mov_b32_e32 v209, 0
	s_mov_b32 s30, -1
	v_mov_b64_e32 v[14:15], v[12:13]
	v_mov_b64_e32 v[12:13], v[10:11]
	v_mov_b64_e32 v[10:11], v[8:9]
	v_mov_b64_e32 v[8:9], v[6:7]
	v_mov_b64_e32 v[6:7], v[4:5]
	v_mov_b64_e32 v[4:5], v[2:3]
	v_mov_b64_e32 v[2:3], v[0:1]
	v_add_u32_e32 v176, 0xffffe000, v176
	v_add_u32_e32 v178, 0xfffe0000, v178
	v_sub_f32_e32 v230, 0x40e00000, v217
	v_mov_b32_e32 v231, v230
	v_mov_b32_e32 v232, v230
	v_mov_b32_e32 v233, v230
	v_mov_b32_e32 v234, v230
	v_mov_b32_e32 v235, v230
	v_mov_b32_e32 v236, v230
	v_mov_b32_e32 v237, v230
	v_mov_b32_e32 v238, v230
	v_mov_b32_e32 v239, v230
	v_mov_b32_e32 v240, v230
	v_mov_b32_e32 v241, v230
	v_mov_b32_e32 v242, v230
	v_mov_b32_e32 v243, v230
	v_mov_b32_e32 v244, v230
	v_mov_b32_e32 v245, v230
	s_mov_b32 s30, 0
	s_waitcnt lgkmcnt(0)
	s_barrier
	s_cmp_eq_u64 s[42:43], 0
	s_cbranch_scc1 .Lmla_stag_entry
.LBB0_1321:
	global_load_dwordx4 v[158:161], v176, s[18:19]
	global_load_dwordx4 v[162:165], v178, s[16:17]
	global_load_dwordx4 v[154:157], v[180:181], off
	ds_read_b128 v[114:117], v215 offset:24576
	ds_read_b128 v[118:121], v216 offset:24576
	ds_read_b128 v[222:225], v215 offset:28672
	ds_read_b128 v[226:229], v216 offset:28672
	v_add_u32_e32 v176, 0x2000, v176
	v_add_u32_e32 v178, 0x20000, v178
	s_mov_b64 s[20:21], 0x1000
	v_lshl_add_u64 v[180:181], v[180:181], 0, s[20:21]
	v_exp_f32_e32 v0, v82
	v_exp_f32_e32 v177, v83
	v_exp_f32_e32 v179, v84
	v_exp_f32_e32 v254, v85
	v_add_f32_e32 v219, v0, v177
	v_cvt_pk_fp8_f32 v246, v0, v177
	v_add_f32_e32 v219, v179, v219
	v_add_f32_e32 v219, v254, v219
	v_cvt_pk_fp8_f32 v246, v179, v254 op_sel:[0,0,1]
	s_waitcnt lgkmcnt(2)
	v_mfma_scale_f32_32x32x64_f8f6f4 v[114:129], v[114:121], v[146:153], v[230:245], v194, v193 op_sel_hi:[0,0,0]
	v_exp_f32_e32 v0, v86
	v_exp_f32_e32 v177, v87
	v_exp_f32_e32 v179, v88
	v_exp_f32_e32 v254, v89
	v_add_f32_e32 v219, v0, v219
	v_add_f32_e32 v219, v177, v219
	v_cvt_pk_fp8_f32 v247, v0, v177
	v_add_f32_e32 v219, v179, v219
	v_add_f32_e32 v219, v254, v219
	v_cvt_pk_fp8_f32 v247, v179, v254 op_sel:[0,0,1]
	ds_read_b128 v[82:85], v213 offset:24576
	ds_read_b128 v[86:89], v214 offset:24576
	s_waitcnt lgkmcnt(2)
	v_mfma_scale_f32_32x32x64_f8f6f4 v[98:113], v[222:229], v[146:153], v[230:245], v194, v193 op_sel_hi:[0,0,0]
	ds_read_b128 v[222:225], v213 offset:28672
	ds_read_b128 v[226:229], v214 offset:28672
	v_exp_f32_e32 v0, v90
	v_exp_f32_e32 v177, v91
	v_exp_f32_e32 v179, v92
	v_exp_f32_e32 v254, v93
	v_add_f32_e32 v219, v0, v219
	v_add_f32_e32 v219, v177, v219
	v_cvt_pk_fp8_f32 v248, v0, v177
	v_add_f32_e32 v219, v179, v219
	v_add_f32_e32 v219, v254, v219
	v_cvt_pk_fp8_f32 v248, v179, v254 op_sel:[0,0,1]
	v_exp_f32_e32 v0, v94
	v_exp_f32_e32 v177, v95
	v_exp_f32_e32 v179, v96
	v_exp_f32_e32 v254, v97
	v_add_f32_e32 v219, v0, v219
	v_add_f32_e32 v219, v177, v219
	v_cvt_pk_fp8_f32 v249, v0, v177
	v_add_f32_e32 v219, v179, v219
	v_add_f32_e32 v219, v254, v219
	v_cvt_pk_fp8_f32 v249, v179, v254 op_sel:[0,0,1]
	ds_read_b128 v[90:93], v185 offset:36864
	ds_read_b128 v[94:97], v186 offset:36864
	s_waitcnt lgkmcnt(4)
	v_mfma_scale_f32_32x32x64_f8f6f4 v[114:129], v[82:89], v[138:145], v[114:129], v194, v193 op_sel_hi:[0,0,0]
	v_exp_f32_e32 v0, v66
	v_exp_f32_e32 v177, v67
	v_exp_f32_e32 v179, v68
	v_exp_f32_e32 v254, v69
	v_add_f32_e32 v219, v0, v219
	v_add_f32_e32 v219, v177, v219
	v_cvt_pk_fp8_f32 v250, v0, v177
	v_add_f32_e32 v219, v179, v219
	v_add_f32_e32 v219, v254, v219
	v_cvt_pk_fp8_f32 v250, v179, v254 op_sel:[0,0,1]
	s_waitcnt lgkmcnt(2)
	v_mfma_scale_f32_32x32x64_f8f6f4 v[98:113], v[222:229], v[138:145], v[98:113], v194, v193 op_sel_hi:[0,0,0]
	ds_read_b128 v[222:225], v185 offset:38912
	ds_read_b128 v[226:229], v186 offset:38912
	v_exp_f32_e32 v0, v70
	v_exp_f32_e32 v177, v71
	v_exp_f32_e32 v179, v72
	v_exp_f32_e32 v254, v73
	v_add_f32_e32 v219, v0, v219
	v_add_f32_e32 v219, v177, v219
	v_cvt_pk_fp8_f32 v251, v0, v177
	v_add_f32_e32 v219, v179, v219
	v_add_f32_e32 v219, v254, v219
	v_cvt_pk_fp8_f32 v251, v179, v254 op_sel:[0,0,1]
	v_exp_f32_e32 v0, v74
	v_exp_f32_e32 v177, v75
	v_exp_f32_e32 v179, v76
	v_exp_f32_e32 v254, v77
	v_add_f32_e32 v219, v0, v219
	v_add_f32_e32 v219, v177, v219
	v_cvt_pk_fp8_f32 v252, v0, v177
	v_add_f32_e32 v219, v179, v219
	v_add_f32_e32 v219, v254, v219
	v_cvt_pk_fp8_f32 v252, v179, v254 op_sel:[0,0,1]
	s_waitcnt lgkmcnt(2)
; #define SLOAD() do { vs0 = *(const bf16x8*)(Vh + voff); vs1 = *(const bf16x8*)(Vh + voff + 32u * (unsigned)ldv); \
;     ks0 = *(const bf16x8*)(Kh + koff); ks1 = *(const bf16x8*)(Kh + koff + 32u * (unsigned)ldk); \
;     if constexpr (NR > 0) { kr = *(const bf16x8*)(Krh + kroff); kroff += 64u * 64u; } voff += 64u * (unsigned)ldv; koff += 64u * (unsigned)ldk; } while (0)
; #define SWRITE(b) do { *(bf16x8*)(V_lds + (b) * SHM_V + vst0) = vs0; *(bf16x8*)(V_lds + (b) * SHM_V + vst1) = vs1; const int kc = sc * 2;  \
;     *(bf16x8*)(K_lds + (b) * SHM_K + KSWZ(sr, kc)) = ks0; *(bf16x8*)(K_lds + (b) * SHM_K + KSWZ(32 + sr, kc)) = ks1; \
;     if constexpr (NR > 0) *(bf16x8*)(Kr_lds + (b) * SHM_KR + krst) = kr; } while (0)
; #define SLOAD() do { vs0 = *(const bf16x8*)(Vh + voff); vs1 = *(const bf16x8*)(Vh + voff + 32u * (unsigned)ldv); \
;     ks0 = *(const bf16x8*)(Kh + voff); ks1 = *(const bf16x8*)(Kh + voff + 32u * (unsigned)ldv); \
;     if constexpr (NR > 0) { kr = *(const bf16x8*)(Krh + kroff); kroff += 64u * 64u; } voff += 64u * (unsigned)ldv; } while (0)
; #define SWRITE(b) do { *(bf16x8*)(V_lds + (b) * SHM_V + vst0) = vs0; *(bf16x8*)(V_lds + (b) * SHM_V + vst0 + 8192) = vs1;  \
;     *(bf16x8*)(K_lds + (b) * SHM_K + kst0) = ks0; *(bf16x8*)(K_lds + (b) * SHM_K + kst0 + 8192) = ks1; \
;     if constexpr (NR > 0) *(bf16x8*)(Kr_lds + (b) * SHM_KR + krst) = kr; } while (0)
; #define SWRITE(b) do { *(v4i32*)(Vt_lds + (b) * 8192 + vtst) = vt; *(v4i32*)(Kn_lds + (b) * 8192 + knst) = kn; if (krw) *(v4i32*)(Kr_lds + (b) * 4096 + krst) = kr; } while (0)
; __device__ __forceinline__ void attn_unit7(const unsigned char* __restrict__ Q8, int ldq, const unsigned char* __restrict__ Kn8, int ldk, const unsigned char* __restrict__ Kr8, ...
;     ...
;   for (int j = 1; j + 1 < NT; j += 2) {
;     SLOAD();
;     qkt9(pB0, pB1, Kn_lds + 8192, Kr_lds + 4096, qf, 7.0f - m_reg, r32, hi);
;     finishSM9(pA0, pA1, alA, l_reg, p8);
;     pv8(o, Vt_lds, p8, r32, hi); partialSM9(pB0, pB1, m_reg, alB, thr_raw);
;     __syncthreads(); SWRITE(0);
;     RESC(alB); __syncthreads();
;     if (j + 2 < NT) SLOAD();
;     qkt9(pA0, pA1, Kn_lds, Kr_lds, qf, 7.0f - m_reg, r32, hi);
;     finishSM9(pB0, pB1, alB, l_reg, p8);
;     pv8(o, Vt_lds + 8192, p8, r32, hi); partialSM9(pA0, pA1, m_reg, alA, thr_raw);
;     __syncthreads(); if (j + 2 < NT) SWRITE(1);
;     RESC(alA); __syncthreads();
	v_mfma_scale_f32_32x32x64_f8f6f4 v[114:129], v[90:97], v[130:137], v[114:129], v194, v193 op_sel_hi:[0,0,0]
	v_exp_f32_e32 v0, v78
	v_exp_f32_e32 v177, v79
	v_exp_f32_e32 v179, v80
	v_exp_f32_e32 v254, v81
	v_add_f32_e32 v219, v0, v219
	v_add_f32_e32 v219, v177, v219
	v_cvt_pk_fp8_f32 v253, v0, v177
	v_add_f32_e32 v219, v179, v219
	v_add_f32_e32 v219, v254, v219
	v_cvt_pk_fp8_f32 v253, v179, v254 op_sel:[0,0,1]
	ds_read_b128 v[90:93], v185 offset:0
	ds_read_b128 v[94:97], v186 offset:0
	ds_read_b128 v[82:85], v185 offset:2048
	ds_read_b128 v[86:89], v186 offset:2048
	ds_read_b128 v[74:77], v185 offset:4096
	ds_read_b128 v[78:81], v186 offset:4096
	ds_read_b128 v[66:69], v185 offset:6144
	ds_read_b128 v[70:73], v186 offset:6144
	s_waitcnt lgkmcnt(8)
	v_mfma_scale_f32_32x32x64_f8f6f4 v[98:113], v[222:229], v[130:137], v[98:113], v194, v193 op_sel_hi:[0,0,0]
	v_mov_b32_e32 v0, v219
	s_nop 1
	v_permlane32_swap_b32_e32 v219, v0
	v_add_f32_e32 v219, v219, v0
	v_fma_f32 v209, v209, v218, v219
	v_max_f32_e32 v177, v114, v115
	v_max3_f32 v177, v177, v116, v117
	v_max3_f32 v177, v177, v118, v119
	v_max3_f32 v177, v177, v120, v121
	v_max3_f32 v177, v177, v122, v123
	v_max3_f32 v177, v177, v124, v125
	v_max3_f32 v177, v177, v126, v127
	v_max3_f32 v177, v177, v128, v129
	s_waitcnt lgkmcnt(6)
	v_mfma_scale_f32_32x32x64_f8f6f4 v[50:65], v[246:253], v[90:97], v[50:65], v194, v194 op_sel_hi:[0,0,0]
	s_waitcnt lgkmcnt(4)
	v_mfma_scale_f32_32x32x64_f8f6f4 v[34:49], v[246:253], v[82:89], v[34:49], v194, v194 op_sel_hi:[0,0,0]
	s_waitcnt lgkmcnt(2)
	v_mfma_scale_f32_32x32x64_f8f6f4 v[18:33], v[246:253], v[74:81], v[18:33], v194, v194 op_sel_hi:[0,0,0]
	s_waitcnt lgkmcnt(0)
	v_mfma_scale_f32_32x32x64_f8f6f4 v[2:17], v[246:253], v[66:73], v[2:17], v194, v194 op_sel_hi:[0,0,0]
	s_waitcnt vmcnt(0)
	ds_write_b128 v210, v[158:161] offset:43008
	ds_write_b128 v211, v[162:165] offset:51200
	ds_write_b128 v212, v[154:157] offset:59392
	v_max_f32_e32 v0, v98, v99
	v_max3_f32 v0, v0, v100, v101
	v_max3_f32 v0, v0, v102, v103
	v_max3_f32 v0, v0, v104, v105
	v_max3_f32 v0, v0, v106, v107
	v_max3_f32 v0, v0, v108, v109
	v_max3_f32 v0, v0, v110, v111
	v_max3_f32 v0, v0, v112, v113
	v_max_f32_e32 v177, v177, v0
	v_mov_b32_e32 v0, v177
	v_mov_b32_e32 v221, 1.0
	s_nop 0
	v_permlane32_swap_b32_e32 v177, v0
	v_max_f32_e32 v177, v177, v0
	v_cmp_ge_f32_e32 vcc, s90, v177
	s_cmp_eq_u64 vcc, exec
	s_cbranch_scc0 .Lmla_h0_newmax
.Lmla_h0_cont:
	s_waitcnt lgkmcnt(0)
	s_barrier
	global_load_dwordx4 v[158:161], v176, s[18:19]
	global_load_dwordx4 v[162:165], v178, s[16:17]
	global_load_dwordx4 v[154:157], v[180:181], off
	ds_read_b128 v[82:85], v215 offset:51200
	ds_read_b128 v[86:89], v216 offset:51200
	ds_read_b128 v[222:225], v215 offset:55296
	ds_read_b128 v[226:229], v216 offset:55296
	v_add_u32_e32 v176, 0x2000, v176
	v_add_u32_e32 v178, 0x20000, v178
	s_mov_b64 s[20:21], 0x1000
	v_lshl_add_u64 v[180:181], v[180:181], 0, s[20:21]
	v_exp_f32_e32 v0, v114
	v_exp_f32_e32 v177, v115
	v_exp_f32_e32 v179, v116
	v_exp_f32_e32 v254, v117
	v_add_f32_e32 v219, v0, v177
	v_cvt_pk_fp8_f32 v246, v0, v177
	v_add_f32_e32 v219, v179, v219
	v_add_f32_e32 v219, v254, v219
	v_cvt_pk_fp8_f32 v246, v179, v254 op_sel:[0,0,1]
	s_waitcnt lgkmcnt(2)
	v_mfma_scale_f32_32x32x64_f8f6f4 v[82:97], v[82:89], v[146:153], v[230:245], v194, v193 op_sel_hi:[0,0,0]
	v_exp_f32_e32 v0, v118
	v_exp_f32_e32 v177, v119
	v_exp_f32_e32 v179, v120
	v_exp_f32_e32 v254, v121
	v_add_f32_e32 v219, v0, v219
	v_add_f32_e32 v219, v177, v219
	v_cvt_pk_fp8_f32 v247, v0, v177
	v_add_f32_e32 v219, v179, v219
	v_add_f32_e32 v219, v254, v219
	v_cvt_pk_fp8_f32 v247, v179, v254 op_sel:[0,0,1]
	ds_read_b128 v[114:117], v213 offset:51200
	ds_read_b128 v[118:121], v214 offset:51200
	s_waitcnt lgkmcnt(2)
	v_mfma_scale_f32_32x32x64_f8f6f4 v[66:81], v[222:229], v[146:153], v[230:245], v194, v193 op_sel_hi:[0,0,0]
	ds_read_b128 v[222:225], v213 offset:55296
	ds_read_b128 v[226:229], v214 offset:55296
	v_exp_f32_e32 v0, v122
	v_exp_f32_e32 v177, v123
	v_exp_f32_e32 v179, v124
	v_exp_f32_e32 v254, v125
	v_add_f32_e32 v219, v0, v219
	v_add_f32_e32 v219, v177, v219
	v_cvt_pk_fp8_f32 v248, v0, v177
	v_add_f32_e32 v219, v179, v219
	v_add_f32_e32 v219, v254, v219
	v_cvt_pk_fp8_f32 v248, v179, v254 op_sel:[0,0,1]
	v_exp_f32_e32 v0, v126
	v_exp_f32_e32 v177, v127
	v_exp_f32_e32 v179, v128
	v_exp_f32_e32 v254, v129
	v_add_f32_e32 v219, v0, v219
	v_add_f32_e32 v219, v177, v219
	v_cvt_pk_fp8_f32 v249, v0, v177
	v_add_f32_e32 v219, v179, v219
	v_add_f32_e32 v219, v254, v219
	v_cvt_pk_fp8_f32 v249, v179, v254 op_sel:[0,0,1]
	ds_read_b128 v[122:125], v185 offset:59392
	ds_read_b128 v[126:129], v186 offset:59392
	s_waitcnt lgkmcnt(4)
	v_mfma_scale_f32_32x32x64_f8f6f4 v[82:97], v[114:121], v[138:145], v[82:97], v194, v193 op_sel_hi:[0,0,0]
	v_exp_f32_e32 v0, v98
	v_exp_f32_e32 v177, v99
	v_exp_f32_e32 v179, v100
	v_exp_f32_e32 v254, v101
	v_add_f32_e32 v219, v0, v219
	v_add_f32_e32 v219, v177, v219
	v_cvt_pk_fp8_f32 v250, v0, v177
	v_add_f32_e32 v219, v179, v219
	v_add_f32_e32 v219, v254, v219
	v_cvt_pk_fp8_f32 v250, v179, v254 op_sel:[0,0,1]
	s_waitcnt lgkmcnt(2)
	v_mfma_scale_f32_32x32x64_f8f6f4 v[66:81], v[222:229], v[138:145], v[66:81], v194, v193 op_sel_hi:[0,0,0]
	ds_read_b128 v[222:225], v185 offset:61440
	ds_read_b128 v[226:229], v186 offset:61440
	v_exp_f32_e32 v0, v102
	v_exp_f32_e32 v177, v103
	v_exp_f32_e32 v179, v104
	v_exp_f32_e32 v254, v105
	v_add_f32_e32 v219, v0, v219
	v_add_f32_e32 v219, v177, v219
	v_cvt_pk_fp8_f32 v251, v0, v177
	v_add_f32_e32 v219, v179, v219
	v_add_f32_e32 v219, v254, v219
	v_cvt_pk_fp8_f32 v251, v179, v254 op_sel:[0,0,1]
	v_exp_f32_e32 v0, v106
	v_exp_f32_e32 v177, v107
	v_exp_f32_e32 v179, v108
	v_exp_f32_e32 v254, v109
	v_add_f32_e32 v219, v0, v219
	v_add_f32_e32 v219, v177, v219
	v_cvt_pk_fp8_f32 v252, v0, v177
	v_add_f32_e32 v219, v179, v219
	v_add_f32_e32 v219, v254, v219
	v_cvt_pk_fp8_f32 v252, v179, v254 op_sel:[0,0,1]
	s_waitcnt lgkmcnt(2)
; #define SLOAD() do { vs0 = *(const bf16x8*)(Vh + voff); vs1 = *(const bf16x8*)(Vh + voff + 32u * (unsigned)ldv); \
;     ks0 = *(const bf16x8*)(Kh + koff); ks1 = *(const bf16x8*)(Kh + koff + 32u * (unsigned)ldk); \
;     if constexpr (NR > 0) { kr = *(const bf16x8*)(Krh + kroff); kroff += 64u * 64u; } voff += 64u * (unsigned)ldv; koff += 64u * (unsigned)ldk; } while (0)
; #define SWRITE(b) do { *(bf16x8*)(V_lds + (b) * SHM_V + vst0) = vs0; *(bf16x8*)(V_lds + (b) * SHM_V + vst1) = vs1; const int kc = sc * 2;  \
;     *(bf16x8*)(K_lds + (b) * SHM_K + KSWZ(sr, kc)) = ks0; *(bf16x8*)(K_lds + (b) * SHM_K + KSWZ(32 + sr, kc)) = ks1; \
;     if constexpr (NR > 0) *(bf16x8*)(Kr_lds + (b) * SHM_KR + krst) = kr; } while (0)
; #define SLOAD() do { vs0 = *(const bf16x8*)(Vh + voff); vs1 = *(const bf16x8*)(Vh + voff + 32u * (unsigned)ldv); \
;     ks0 = *(const bf16x8*)(Kh + voff); ks1 = *(const bf16x8*)(Kh + voff + 32u * (unsigned)ldv); \
;     if constexpr (NR > 0) { kr = *(const bf16x8*)(Krh + kroff); kroff += 64u * 64u; } voff += 64u * (unsigned)ldv; } while (0)
; #define SWRITE(b) do { *(bf16x8*)(V_lds + (b) * SHM_V + vst0) = vs0; *(bf16x8*)(V_lds + (b) * SHM_V + vst0 + 8192) = vs1;  \
;     *(bf16x8*)(K_lds + (b) * SHM_K + kst0) = ks0; *(bf16x8*)(K_lds + (b) * SHM_K + kst0 + 8192) = ks1; \
;     if constexpr (NR > 0) *(bf16x8*)(Kr_lds + (b) * SHM_KR + krst) = kr; } while (0)
; #define SWRITE(b) do { *(v4i32*)(Vt_lds + (b) * 8192 + vtst) = vt; *(v4i32*)(Kn_lds + (b) * 8192 + knst) = kn; if (krw) *(v4i32*)(Kr_lds + (b) * 4096 + krst) = kr; } while (0)
; __device__ __forceinline__ void attn_unit7(const unsigned char* __restrict__ Q8, int ldq, const unsigned char* __restrict__ Kn8, int ldk, const unsigned char* __restrict__ Kr8, ...
;     ...
;   for (int j = 1; j + 1 < NT; j += 2) {
;     SLOAD();
;     qkt9(pB0, pB1, Kn_lds + 8192, Kr_lds + 4096, qf, 7.0f - m_reg, r32, hi);
;     finishSM9(pA0, pA1, alA, l_reg, p8);
;     pv8(o, Vt_lds, p8, r32, hi); partialSM9(pB0, pB1, m_reg, alB, thr_raw);
;     __syncthreads(); SWRITE(0);
;     RESC(alB); __syncthreads();
;     if (j + 2 < NT) SLOAD();
;     qkt9(pA0, pA1, Kn_lds, Kr_lds, qf, 7.0f - m_reg, r32, hi);
;     finishSM9(pB0, pB1, alB, l_reg, p8);
;     pv8(o, Vt_lds + 8192, p8, r32, hi); partialSM9(pA0, pA1, m_reg, alA, thr_raw);
;     __syncthreads(); if (j + 2 < NT) SWRITE(1);
;     RESC(alA); __syncthreads();
	v_mfma_scale_f32_32x32x64_f8f6f4 v[82:97], v[122:129], v[130:137], v[82:97], v194, v193 op_sel_hi:[0,0,0]
	v_exp_f32_e32 v0, v110
	v_exp_f32_e32 v177, v111
	v_exp_f32_e32 v179, v112
	v_exp_f32_e32 v254, v113
	v_add_f32_e32 v219, v0, v219
	v_add_f32_e32 v219, v177, v219
	v_cvt_pk_fp8_f32 v253, v0, v177
	v_add_f32_e32 v219, v179, v219
	v_add_f32_e32 v219, v254, v219
	v_cvt_pk_fp8_f32 v253, v179, v254 op_sel:[0,0,1]
	ds_read_b128 v[122:125], v185 offset:8192
	ds_read_b128 v[126:129], v186 offset:8192
	ds_read_b128 v[114:117], v185 offset:10240
	ds_read_b128 v[118:121], v186 offset:10240
	ds_read_b128 v[106:109], v185 offset:12288
	ds_read_b128 v[110:113], v186 offset:12288
	ds_read_b128 v[98:101], v185 offset:14336
	ds_read_b128 v[102:105], v186 offset:14336
	s_waitcnt lgkmcnt(8)
	v_mfma_scale_f32_32x32x64_f8f6f4 v[66:81], v[222:229], v[130:137], v[66:81], v194, v193 op_sel_hi:[0,0,0]
	v_mov_b32_e32 v0, v219
	s_nop 1
	v_permlane32_swap_b32_e32 v219, v0
	v_add_f32_e32 v219, v219, v0
	v_fma_f32 v209, v209, v221, v219
	v_max_f32_e32 v177, v82, v83
	v_max3_f32 v177, v177, v84, v85
	v_max3_f32 v177, v177, v86, v87
	v_max3_f32 v177, v177, v88, v89
	v_max3_f32 v177, v177, v90, v91
	v_max3_f32 v177, v177, v92, v93
	v_max3_f32 v177, v177, v94, v95
	v_max3_f32 v177, v177, v96, v97
	s_waitcnt lgkmcnt(6)
	v_mfma_scale_f32_32x32x64_f8f6f4 v[50:65], v[246:253], v[122:129], v[50:65], v194, v194 op_sel_hi:[0,0,0]
	s_waitcnt lgkmcnt(4)
	v_mfma_scale_f32_32x32x64_f8f6f4 v[34:49], v[246:253], v[114:121], v[34:49], v194, v194 op_sel_hi:[0,0,0]
	s_waitcnt lgkmcnt(2)
	v_mfma_scale_f32_32x32x64_f8f6f4 v[18:33], v[246:253], v[106:113], v[18:33], v194, v194 op_sel_hi:[0,0,0]
	s_waitcnt lgkmcnt(0)
	v_mfma_scale_f32_32x32x64_f8f6f4 v[2:17], v[246:253], v[98:105], v[2:17], v194, v194 op_sel_hi:[0,0,0]
	s_waitcnt vmcnt(0)
	ds_write_b128 v210, v[158:161]
	ds_write_b128 v211, v[162:165] offset:16384
	ds_write_b128 v212, v[154:157] offset:32768
	v_max_f32_e32 v0, v66, v67
	v_max3_f32 v0, v0, v68, v69
	v_max3_f32 v0, v0, v70, v71
	v_max3_f32 v0, v0, v72, v73
	v_max3_f32 v0, v0, v74, v75
	v_max3_f32 v0, v0, v76, v77
	v_max3_f32 v0, v0, v78, v79
	v_max3_f32 v0, v0, v80, v81
	v_max_f32_e32 v177, v177, v0
	v_mov_b32_e32 v0, v177
	v_mov_b32_e32 v218, 1.0
	s_nop 0
	v_permlane32_swap_b32_e32 v177, v0
	v_max_f32_e32 v177, v177, v0
	v_cmp_ge_f32_e32 vcc, s90, v177
	s_cmp_eq_u64 vcc, exec
	s_cbranch_scc0 .Lmla_h1_newmax
.Lmla_h1_cont:
	s_waitcnt lgkmcnt(0)
	s_barrier
	global_load_dwordx4 v[158:161], v176, s[18:19]
	global_load_dwordx4 v[162:165], v178, s[16:17]
	global_load_dwordx4 v[154:157], v[180:181], off
	ds_read_b128 v[114:117], v215 offset:16384
	ds_read_b128 v[118:121], v216 offset:16384
	ds_read_b128 v[222:225], v215 offset:20480
	ds_read_b128 v[226:229], v216 offset:20480
	v_add_u32_e32 v176, 0x2000, v176
	v_add_u32_e32 v178, 0x20000, v178
	s_mov_b64 s[20:21], 0x1000
	v_lshl_add_u64 v[180:181], v[180:181], 0, s[20:21]
	v_exp_f32_e32 v0, v82
	v_exp_f32_e32 v177, v83
	v_exp_f32_e32 v179, v84
	v_exp_f32_e32 v254, v85
	v_add_f32_e32 v219, v0, v177
	v_cvt_pk_fp8_f32 v246, v0, v177
	v_add_f32_e32 v219, v179, v219
	v_add_f32_e32 v219, v254, v219
	v_cvt_pk_fp8_f32 v246, v179, v254 op_sel:[0,0,1]
	s_waitcnt lgkmcnt(2)
	v_mfma_scale_f32_32x32x64_f8f6f4 v[114:129], v[114:121], v[146:153], v[230:245], v194, v193 op_sel_hi:[0,0,0]
	v_exp_f32_e32 v0, v86
	v_exp_f32_e32 v177, v87
	v_exp_f32_e32 v179, v88
	v_exp_f32_e32 v254, v89
	v_add_f32_e32 v219, v0, v219
	v_add_f32_e32 v219, v177, v219
	v_cvt_pk_fp8_f32 v247, v0, v177
	v_add_f32_e32 v219, v179, v219
	v_add_f32_e32 v219, v254, v219
	v_cvt_pk_fp8_f32 v247, v179, v254 op_sel:[0,0,1]
	ds_read_b128 v[82:85], v213 offset:16384
	ds_read_b128 v[86:89], v214 offset:16384
	s_waitcnt lgkmcnt(2)
	v_mfma_scale_f32_32x32x64_f8f6f4 v[98:113], v[222:229], v[146:153], v[230:245], v194, v193 op_sel_hi:[0,0,0]
	ds_read_b128 v[222:225], v213 offset:20480
	ds_read_b128 v[226:229], v214 offset:20480
	v_exp_f32_e32 v0, v90
	v_exp_f32_e32 v177, v91
	v_exp_f32_e32 v179, v92
	v_exp_f32_e32 v254, v93
	v_add_f32_e32 v219, v0, v219
	v_add_f32_e32 v219, v177, v219
	v_cvt_pk_fp8_f32 v248, v0, v177
	v_add_f32_e32 v219, v179, v219
	v_add_f32_e32 v219, v254, v219
	v_cvt_pk_fp8_f32 v248, v179, v254 op_sel:[0,0,1]
	v_exp_f32_e32 v0, v94
	v_exp_f32_e32 v177, v95
	v_exp_f32_e32 v179, v96
	v_exp_f32_e32 v254, v97
	v_add_f32_e32 v219, v0, v219
	v_add_f32_e32 v219, v177, v219
	v_cvt_pk_fp8_f32 v249, v0, v177
	v_add_f32_e32 v219, v179, v219
	v_add_f32_e32 v219, v254, v219
	v_cvt_pk_fp8_f32 v249, v179, v254 op_sel:[0,0,1]
	ds_read_b128 v[90:93], v185 offset:32768
	ds_read_b128 v[94:97], v186 offset:32768
	s_waitcnt lgkmcnt(4)
	v_mfma_scale_f32_32x32x64_f8f6f4 v[114:129], v[82:89], v[138:145], v[114:129], v194, v193 op_sel_hi:[0,0,0]
	v_exp_f32_e32 v0, v66
	v_exp_f32_e32 v177, v67
	v_exp_f32_e32 v179, v68
	v_exp_f32_e32 v254, v69
	v_add_f32_e32 v219, v0, v219
	v_add_f32_e32 v219, v177, v219
	v_cvt_pk_fp8_f32 v250, v0, v177
	v_add_f32_e32 v219, v179, v219
	v_add_f32_e32 v219, v254, v219
	v_cvt_pk_fp8_f32 v250, v179, v254 op_sel:[0,0,1]
	s_waitcnt lgkmcnt(2)
	v_mfma_scale_f32_32x32x64_f8f6f4 v[98:113], v[222:229], v[138:145], v[98:113], v194, v193 op_sel_hi:[0,0,0]
	ds_read_b128 v[222:225], v185 offset:34816
	ds_read_b128 v[226:229], v186 offset:34816
	v_exp_f32_e32 v0, v70
	v_exp_f32_e32 v177, v71
	v_exp_f32_e32 v179, v72
	v_exp_f32_e32 v254, v73
	v_add_f32_e32 v219, v0, v219
	v_add_f32_e32 v219, v177, v219
	v_cvt_pk_fp8_f32 v251, v0, v177
	v_add_f32_e32 v219, v179, v219
	v_add_f32_e32 v219, v254, v219
	v_cvt_pk_fp8_f32 v251, v179, v254 op_sel:[0,0,1]
	v_exp_f32_e32 v0, v74
	v_exp_f32_e32 v177, v75
	v_exp_f32_e32 v179, v76
	v_exp_f32_e32 v254, v77
	v_add_f32_e32 v219, v0, v219
	v_add_f32_e32 v219, v177, v219
	v_cvt_pk_fp8_f32 v252, v0, v177
	v_add_f32_e32 v219, v179, v219
	v_add_f32_e32 v219, v254, v219
	v_cvt_pk_fp8_f32 v252, v179, v254 op_sel:[0,0,1]
	s_waitcnt lgkmcnt(2)
; #define SLOAD() do { vs0 = *(const bf16x8*)(Vh + voff); vs1 = *(const bf16x8*)(Vh + voff + 32u * (unsigned)ldv); \
;     ks0 = *(const bf16x8*)(Kh + koff); ks1 = *(const bf16x8*)(Kh + koff + 32u * (unsigned)ldk); \
;     if constexpr (NR > 0) { kr = *(const bf16x8*)(Krh + kroff); kroff += 64u * 64u; } voff += 64u * (unsigned)ldv; koff += 64u * (unsigned)ldk; } while (0)
; #define SWRITE(b) do { *(bf16x8*)(V_lds + (b) * SHM_V + vst0) = vs0; *(bf16x8*)(V_lds + (b) * SHM_V + vst1) = vs1; const int kc = sc * 2;  \
;     *(bf16x8*)(K_lds + (b) * SHM_K + KSWZ(sr, kc)) = ks0; *(bf16x8*)(K_lds + (b) * SHM_K + KSWZ(32 + sr, kc)) = ks1; \
;     if constexpr (NR > 0) *(bf16x8*)(Kr_lds + (b) * SHM_KR + krst) = kr; } while (0)
; #define SLOAD() do { vs0 = *(const bf16x8*)(Vh + voff); vs1 = *(const bf16x8*)(Vh + voff + 32u * (unsigned)ldv); \
;     ks0 = *(const bf16x8*)(Kh + voff); ks1 = *(const bf16x8*)(Kh + voff + 32u * (unsigned)ldv); \
;     if constexpr (NR > 0) { kr = *(const bf16x8*)(Krh + kroff); kroff += 64u * 64u; } voff += 64u * (unsigned)ldv; } while (0)
; #define SWRITE(b) do { *(bf16x8*)(V_lds + (b) * SHM_V + vst0) = vs0; *(bf16x8*)(V_lds + (b) * SHM_V + vst0 + 8192) = vs1;  \
;     *(bf16x8*)(K_lds + (b) * SHM_K + kst0) = ks0; *(bf16x8*)(K_lds + (b) * SHM_K + kst0 + 8192) = ks1; \
;     if constexpr (NR > 0) *(bf16x8*)(Kr_lds + (b) * SHM_KR + krst) = kr; } while (0)
; #define SWRITE(b) do { *(v4i32*)(Vt_lds + (b) * 8192 + vtst) = vt; *(v4i32*)(Kn_lds + (b) * 8192 + knst) = kn; if (krw) *(v4i32*)(Kr_lds + (b) * 4096 + krst) = kr; } while (0)
; __device__ __forceinline__ void attn_unit7(const unsigned char* __restrict__ Q8, int ldq, const unsigned char* __restrict__ Kn8, int ldk, const unsigned char* __restrict__ Kr8, ...
;     ...
;   for (int j = 1; j + 1 < NT; j += 2) {
;     SLOAD();
;     qkt9(pB0, pB1, Kn_lds + 8192, Kr_lds + 4096, qf, 7.0f - m_reg, r32, hi);
;     finishSM9(pA0, pA1, alA, l_reg, p8);
;     pv8(o, Vt_lds, p8, r32, hi); partialSM9(pB0, pB1, m_reg, alB, thr_raw);
;     __syncthreads(); SWRITE(0);
;     RESC(alB); __syncthreads();
;     if (j + 2 < NT) SLOAD();
;     qkt9(pA0, pA1, Kn_lds, Kr_lds, qf, 7.0f - m_reg, r32, hi);
;     finishSM9(pB0, pB1, alB, l_reg, p8);
;     pv8(o, Vt_lds + 8192, p8, r32, hi); partialSM9(pA0, pA1, m_reg, alA, thr_raw);
;     __syncthreads(); if (j + 2 < NT) SWRITE(1);
;     RESC(alA); __syncthreads();
	v_mfma_scale_f32_32x32x64_f8f6f4 v[114:129], v[90:97], v[130:137], v[114:129], v194, v193 op_sel_hi:[0,0,0]
	v_exp_f32_e32 v0, v78
	v_exp_f32_e32 v177, v79
	v_exp_f32_e32 v179, v80
	v_exp_f32_e32 v254, v81
	v_add_f32_e32 v219, v0, v219
	v_add_f32_e32 v219, v177, v219
	v_cvt_pk_fp8_f32 v253, v0, v177
	v_add_f32_e32 v219, v179, v219
	v_add_f32_e32 v219, v254, v219
	v_cvt_pk_fp8_f32 v253, v179, v254 op_sel:[0,0,1]
	ds_read_b128 v[90:93], v185 offset:43008
	ds_read_b128 v[94:97], v186 offset:43008
	ds_read_b128 v[82:85], v185 offset:45056
	ds_read_b128 v[86:89], v186 offset:45056
	ds_read_b128 v[74:77], v185 offset:47104
	ds_read_b128 v[78:81], v186 offset:47104
	ds_read_b128 v[66:69], v185 offset:49152
	ds_read_b128 v[70:73], v186 offset:49152
	s_waitcnt lgkmcnt(8)
	v_mfma_scale_f32_32x32x64_f8f6f4 v[98:113], v[222:229], v[130:137], v[98:113], v194, v193 op_sel_hi:[0,0,0]
	v_mov_b32_e32 v0, v219
	s_nop 1
	v_permlane32_swap_b32_e32 v219, v0
	v_add_f32_e32 v219, v219, v0
	v_fma_f32 v209, v209, v218, v219
	v_max_f32_e32 v177, v114, v115
	v_max3_f32 v177, v177, v116, v117
	v_max3_f32 v177, v177, v118, v119
	v_max3_f32 v177, v177, v120, v121
	v_max3_f32 v177, v177, v122, v123
	v_max3_f32 v177, v177, v124, v125
	v_max3_f32 v177, v177, v126, v127
	v_max3_f32 v177, v177, v128, v129
	s_waitcnt lgkmcnt(6)
	v_mfma_scale_f32_32x32x64_f8f6f4 v[50:65], v[246:253], v[90:97], v[50:65], v194, v194 op_sel_hi:[0,0,0]
	s_waitcnt lgkmcnt(4)
	v_mfma_scale_f32_32x32x64_f8f6f4 v[34:49], v[246:253], v[82:89], v[34:49], v194, v194 op_sel_hi:[0,0,0]
	s_waitcnt lgkmcnt(2)
	v_mfma_scale_f32_32x32x64_f8f6f4 v[18:33], v[246:253], v[74:81], v[18:33], v194, v194 op_sel_hi:[0,0,0]
	s_waitcnt lgkmcnt(0)
	v_mfma_scale_f32_32x32x64_f8f6f4 v[2:17], v[246:253], v[66:73], v[2:17], v194, v194 op_sel_hi:[0,0,0]
	s_waitcnt vmcnt(0)
	ds_write_b128 v210, v[158:161] offset:8192
	ds_write_b128 v211, v[162:165] offset:24576
	ds_write_b128 v212, v[154:157] offset:36864
	v_max_f32_e32 v0, v98, v99
	v_max3_f32 v0, v0, v100, v101
	v_max3_f32 v0, v0, v102, v103
	v_max3_f32 v0, v0, v104, v105
	v_max3_f32 v0, v0, v106, v107
	v_max3_f32 v0, v0, v108, v109
	v_max3_f32 v0, v0, v110, v111
	v_max3_f32 v0, v0, v112, v113
	v_max_f32_e32 v177, v177, v0
	v_mov_b32_e32 v0, v177
	v_mov_b32_e32 v221, 1.0
	s_nop 0
	v_permlane32_swap_b32_e32 v177, v0
	v_max_f32_e32 v177, v177, v0
	v_cmp_ge_f32_e32 vcc, s90, v177
	s_cmp_eq_u64 vcc, exec
	s_cbranch_scc0 .Lmla_h2_newmax
.Lmla_h2_cont:
	s_waitcnt lgkmcnt(0)
	s_barrier
	global_load_dwordx4 v[158:161], v176, s[18:19]
	global_load_dwordx4 v[162:165], v178, s[16:17]
	global_load_dwordx4 v[154:157], v[180:181], off
	ds_read_b128 v[82:85], v215 offset:24576
	ds_read_b128 v[86:89], v216 offset:24576
	ds_read_b128 v[222:225], v215 offset:28672
	ds_read_b128 v[226:229], v216 offset:28672
	v_add_u32_e32 v176, 0x2000, v176
	v_add_u32_e32 v178, 0x20000, v178
	s_mov_b64 s[20:21], 0x1000
	v_lshl_add_u64 v[180:181], v[180:181], 0, s[20:21]
	v_exp_f32_e32 v0, v114
	v_exp_f32_e32 v177, v115
	v_exp_f32_e32 v179, v116
	v_exp_f32_e32 v254, v117
	v_add_f32_e32 v219, v0, v177
	v_cvt_pk_fp8_f32 v246, v0, v177
	v_add_f32_e32 v219, v179, v219
	v_add_f32_e32 v219, v254, v219
	v_cvt_pk_fp8_f32 v246, v179, v254 op_sel:[0,0,1]
	s_waitcnt lgkmcnt(2)
	v_mfma_scale_f32_32x32x64_f8f6f4 v[82:97], v[82:89], v[146:153], v[230:245], v194, v193 op_sel_hi:[0,0,0]
	v_exp_f32_e32 v0, v118
	v_exp_f32_e32 v177, v119
	v_exp_f32_e32 v179, v120
	v_exp_f32_e32 v254, v121
	v_add_f32_e32 v219, v0, v219
	v_add_f32_e32 v219, v177, v219
	v_cvt_pk_fp8_f32 v247, v0, v177
	v_add_f32_e32 v219, v179, v219
	v_add_f32_e32 v219, v254, v219
	v_cvt_pk_fp8_f32 v247, v179, v254 op_sel:[0,0,1]
	ds_read_b128 v[114:117], v213 offset:24576
	ds_read_b128 v[118:121], v214 offset:24576
	s_waitcnt lgkmcnt(2)
	v_mfma_scale_f32_32x32x64_f8f6f4 v[66:81], v[222:229], v[146:153], v[230:245], v194, v193 op_sel_hi:[0,0,0]
	ds_read_b128 v[222:225], v213 offset:28672
	ds_read_b128 v[226:229], v214 offset:28672
	v_exp_f32_e32 v0, v122
	v_exp_f32_e32 v177, v123
	v_exp_f32_e32 v179, v124
	v_exp_f32_e32 v254, v125
	v_add_f32_e32 v219, v0, v219
	v_add_f32_e32 v219, v177, v219
	v_cvt_pk_fp8_f32 v248, v0, v177
	v_add_f32_e32 v219, v179, v219
	v_add_f32_e32 v219, v254, v219
	v_cvt_pk_fp8_f32 v248, v179, v254 op_sel:[0,0,1]
	v_exp_f32_e32 v0, v126
	v_exp_f32_e32 v177, v127
	v_exp_f32_e32 v179, v128
	v_exp_f32_e32 v254, v129
	v_add_f32_e32 v219, v0, v219
	v_add_f32_e32 v219, v177, v219
	v_cvt_pk_fp8_f32 v249, v0, v177
	v_add_f32_e32 v219, v179, v219
	v_add_f32_e32 v219, v254, v219
	v_cvt_pk_fp8_f32 v249, v179, v254 op_sel:[0,0,1]
	ds_read_b128 v[122:125], v185 offset:36864
	ds_read_b128 v[126:129], v186 offset:36864
	s_waitcnt lgkmcnt(4)
	v_mfma_scale_f32_32x32x64_f8f6f4 v[82:97], v[114:121], v[138:145], v[82:97], v194, v193 op_sel_hi:[0,0,0]
	v_exp_f32_e32 v0, v98
	v_exp_f32_e32 v177, v99
	v_exp_f32_e32 v179, v100
	v_exp_f32_e32 v254, v101
	v_add_f32_e32 v219, v0, v219
	v_add_f32_e32 v219, v177, v219
	v_cvt_pk_fp8_f32 v250, v0, v177
	v_add_f32_e32 v219, v179, v219
	v_add_f32_e32 v219, v254, v219
	v_cvt_pk_fp8_f32 v250, v179, v254 op_sel:[0,0,1]
	s_waitcnt lgkmcnt(2)
	v_mfma_scale_f32_32x32x64_f8f6f4 v[66:81], v[222:229], v[138:145], v[66:81], v194, v193 op_sel_hi:[0,0,0]
	ds_read_b128 v[222:225], v185 offset:38912
	ds_read_b128 v[226:229], v186 offset:38912
	v_exp_f32_e32 v0, v102
	v_exp_f32_e32 v177, v103
	v_exp_f32_e32 v179, v104
	v_exp_f32_e32 v254, v105
	v_add_f32_e32 v219, v0, v219
	v_add_f32_e32 v219, v177, v219
	v_cvt_pk_fp8_f32 v251, v0, v177
	v_add_f32_e32 v219, v179, v219
	v_add_f32_e32 v219, v254, v219
	v_cvt_pk_fp8_f32 v251, v179, v254 op_sel:[0,0,1]
	v_exp_f32_e32 v0, v106
	v_exp_f32_e32 v177, v107
	v_exp_f32_e32 v179, v108
	v_exp_f32_e32 v254, v109
	v_add_f32_e32 v219, v0, v219
	v_add_f32_e32 v219, v177, v219
	v_cvt_pk_fp8_f32 v252, v0, v177
	v_add_f32_e32 v219, v179, v219
	v_add_f32_e32 v219, v254, v219
	v_cvt_pk_fp8_f32 v252, v179, v254 op_sel:[0,0,1]
	s_waitcnt lgkmcnt(2)
; #define SLOAD() do { vs0 = *(const bf16x8*)(Vh + voff); vs1 = *(const bf16x8*)(Vh + voff + 32u * (unsigned)ldv); \
;     ks0 = *(const bf16x8*)(Kh + koff); ks1 = *(const bf16x8*)(Kh + koff + 32u * (unsigned)ldk); \
;     if constexpr (NR > 0) { kr = *(const bf16x8*)(Krh + kroff); kroff += 64u * 64u; } voff += 64u * (unsigned)ldv; koff += 64u * (unsigned)ldk; } while (0)
; #define SWRITE(b) do { *(bf16x8*)(V_lds + (b) * SHM_V + vst0) = vs0; *(bf16x8*)(V_lds + (b) * SHM_V + vst1) = vs1; const int kc = sc * 2;  \
;     *(bf16x8*)(K_lds + (b) * SHM_K + KSWZ(sr, kc)) = ks0; *(bf16x8*)(K_lds + (b) * SHM_K + KSWZ(32 + sr, kc)) = ks1; \
;     if constexpr (NR > 0) *(bf16x8*)(Kr_lds + (b) * SHM_KR + krst) = kr; } while (0)
; #define SLOAD() do { vs0 = *(const bf16x8*)(Vh + voff); vs1 = *(const bf16x8*)(Vh + voff + 32u * (unsigned)ldv); \
;     ks0 = *(const bf16x8*)(Kh + voff); ks1 = *(const bf16x8*)(Kh + voff + 32u * (unsigned)ldv); \
;     if constexpr (NR > 0) { kr = *(const bf16x8*)(Krh + kroff); kroff += 64u * 64u; } voff += 64u * (unsigned)ldv; } while (0)
; #define SWRITE(b) do { *(bf16x8*)(V_lds + (b) * SHM_V + vst0) = vs0; *(bf16x8*)(V_lds + (b) * SHM_V + vst0 + 8192) = vs1;  \
;     *(bf16x8*)(K_lds + (b) * SHM_K + kst0) = ks0; *(bf16x8*)(K_lds + (b) * SHM_K + kst0 + 8192) = ks1; \
;     if constexpr (NR > 0) *(bf16x8*)(Kr_lds + (b) * SHM_KR + krst) = kr; } while (0)
; #define SWRITE(b) do { *(v4i32*)(Vt_lds + (b) * 8192 + vtst) = vt; *(v4i32*)(Kn_lds + (b) * 8192 + knst) = kn; if (krw) *(v4i32*)(Kr_lds + (b) * 4096 + krst) = kr; } while (0)
; __device__ __forceinline__ void attn_unit7(const unsigned char* __restrict__ Q8, int ldq, const unsigned char* __restrict__ Kn8, int ldk, const unsigned char* __restrict__ Kr8, ...
;     ...
;   for (int j = 1; j + 1 < NT; j += 2) {
;     SLOAD();
;     qkt9(pB0, pB1, Kn_lds + 8192, Kr_lds + 4096, qf, 7.0f - m_reg, r32, hi);
;     finishSM9(pA0, pA1, alA, l_reg, p8);
;     pv8(o, Vt_lds, p8, r32, hi); partialSM9(pB0, pB1, m_reg, alB, thr_raw);
;     __syncthreads(); SWRITE(0);
;     RESC(alB); __syncthreads();
;     if (j + 2 < NT) SLOAD();
;     qkt9(pA0, pA1, Kn_lds, Kr_lds, qf, 7.0f - m_reg, r32, hi);
;     finishSM9(pB0, pB1, alB, l_reg, p8);
;     pv8(o, Vt_lds + 8192, p8, r32, hi); partialSM9(pA0, pA1, m_reg, alA, thr_raw);
;     __syncthreads(); if (j + 2 < NT) SWRITE(1);
;     RESC(alA); __syncthreads();
	v_mfma_scale_f32_32x32x64_f8f6f4 v[82:97], v[122:129], v[130:137], v[82:97], v194, v193 op_sel_hi:[0,0,0]
	v_exp_f32_e32 v0, v110
	v_exp_f32_e32 v177, v111
	v_exp_f32_e32 v179, v112
	v_exp_f32_e32 v254, v113
	v_add_f32_e32 v219, v0, v219
	v_add_f32_e32 v219, v177, v219
	v_cvt_pk_fp8_f32 v253, v0, v177
	v_add_f32_e32 v219, v179, v219
	v_add_f32_e32 v219, v254, v219
	v_cvt_pk_fp8_f32 v253, v179, v254 op_sel:[0,0,1]
	ds_read_b128 v[122:125], v185 offset:0
	ds_read_b128 v[126:129], v186 offset:0
	ds_read_b128 v[114:117], v185 offset:2048
	ds_read_b128 v[118:121], v186 offset:2048
	ds_read_b128 v[106:109], v185 offset:4096
	ds_read_b128 v[110:113], v186 offset:4096
	ds_read_b128 v[98:101], v185 offset:6144
	ds_read_b128 v[102:105], v186 offset:6144
	s_waitcnt lgkmcnt(8)
	v_mfma_scale_f32_32x32x64_f8f6f4 v[66:81], v[222:229], v[130:137], v[66:81], v194, v193 op_sel_hi:[0,0,0]
	v_mov_b32_e32 v0, v219
	s_nop 1
	v_permlane32_swap_b32_e32 v219, v0
	v_add_f32_e32 v219, v219, v0
	v_fma_f32 v209, v209, v221, v219
	v_max_f32_e32 v177, v82, v83
	v_max3_f32 v177, v177, v84, v85
	v_max3_f32 v177, v177, v86, v87
	v_max3_f32 v177, v177, v88, v89
	v_max3_f32 v177, v177, v90, v91
	v_max3_f32 v177, v177, v92, v93
	v_max3_f32 v177, v177, v94, v95
	v_max3_f32 v177, v177, v96, v97
	s_waitcnt lgkmcnt(6)
	v_mfma_scale_f32_32x32x64_f8f6f4 v[50:65], v[246:253], v[122:129], v[50:65], v194, v194 op_sel_hi:[0,0,0]
	s_waitcnt lgkmcnt(4)
	v_mfma_scale_f32_32x32x64_f8f6f4 v[34:49], v[246:253], v[114:121], v[34:49], v194, v194 op_sel_hi:[0,0,0]
	s_waitcnt lgkmcnt(2)
	v_mfma_scale_f32_32x32x64_f8f6f4 v[18:33], v[246:253], v[106:113], v[18:33], v194, v194 op_sel_hi:[0,0,0]
	s_waitcnt lgkmcnt(0)
	v_mfma_scale_f32_32x32x64_f8f6f4 v[2:17], v[246:253], v[98:105], v[2:17], v194, v194 op_sel_hi:[0,0,0]
	s_waitcnt vmcnt(0)
	ds_write_b128 v210, v[158:161] offset:43008
	ds_write_b128 v211, v[162:165] offset:51200
	ds_write_b128 v212, v[154:157] offset:59392
	v_max_f32_e32 v0, v66, v67
	v_max3_f32 v0, v0, v68, v69
	v_max3_f32 v0, v0, v70, v71
	v_max3_f32 v0, v0, v72, v73
	v_max3_f32 v0, v0, v74, v75
	v_max3_f32 v0, v0, v76, v77
	v_max3_f32 v0, v0, v78, v79
	v_max3_f32 v0, v0, v80, v81
	v_max_f32_e32 v177, v177, v0
	v_mov_b32_e32 v0, v177
	v_mov_b32_e32 v218, 1.0
	s_nop 0
	v_permlane32_swap_b32_e32 v177, v0
	v_max_f32_e32 v177, v177, v0
	v_cmp_ge_f32_e32 vcc, s90, v177
	s_cmp_eq_u64 vcc, exec
	s_cbranch_scc0 .Lmla_h3_newmax
.Lmla_h3_cont:
	s_waitcnt lgkmcnt(0)
	s_barrier
	global_load_dwordx4 v[158:161], v176, s[18:19]
	global_load_dwordx4 v[162:165], v178, s[16:17]
	global_load_dwordx4 v[154:157], v[180:181], off
	ds_read_b128 v[114:117], v215 offset:51200
	ds_read_b128 v[118:121], v216 offset:51200
	ds_read_b128 v[222:225], v215 offset:55296
	ds_read_b128 v[226:229], v216 offset:55296
	v_add_u32_e32 v176, 0x2000, v176
	v_add_u32_e32 v178, 0x20000, v178
	s_mov_b64 s[20:21], 0x1000
	v_lshl_add_u64 v[180:181], v[180:181], 0, s[20:21]
	v_exp_f32_e32 v0, v82
	v_exp_f32_e32 v177, v83
	v_exp_f32_e32 v179, v84
	v_exp_f32_e32 v254, v85
	v_add_f32_e32 v219, v0, v177
	v_cvt_pk_fp8_f32 v246, v0, v177
	v_add_f32_e32 v219, v179, v219
	v_add_f32_e32 v219, v254, v219
	v_cvt_pk_fp8_f32 v246, v179, v254 op_sel:[0,0,1]
	s_waitcnt lgkmcnt(2)
	v_mfma_scale_f32_32x32x64_f8f6f4 v[114:129], v[114:121], v[146:153], v[230:245], v194, v193 op_sel_hi:[0,0,0]
	v_exp_f32_e32 v0, v86
	v_exp_f32_e32 v177, v87
	v_exp_f32_e32 v179, v88
	v_exp_f32_e32 v254, v89
	v_add_f32_e32 v219, v0, v219
	v_add_f32_e32 v219, v177, v219
	v_cvt_pk_fp8_f32 v247, v0, v177
	v_add_f32_e32 v219, v179, v219
	v_add_f32_e32 v219, v254, v219
	v_cvt_pk_fp8_f32 v247, v179, v254 op_sel:[0,0,1]
	ds_read_b128 v[82:85], v213 offset:51200
	ds_read_b128 v[86:89], v214 offset:51200
	s_waitcnt lgkmcnt(2)
	v_mfma_scale_f32_32x32x64_f8f6f4 v[98:113], v[222:229], v[146:153], v[230:245], v194, v193 op_sel_hi:[0,0,0]
	ds_read_b128 v[222:225], v213 offset:55296
	ds_read_b128 v[226:229], v214 offset:55296
	v_exp_f32_e32 v0, v90
	v_exp_f32_e32 v177, v91
	v_exp_f32_e32 v179, v92
	v_exp_f32_e32 v254, v93
	v_add_f32_e32 v219, v0, v219
	v_add_f32_e32 v219, v177, v219
	v_cvt_pk_fp8_f32 v248, v0, v177
	v_add_f32_e32 v219, v179, v219
	v_add_f32_e32 v219, v254, v219
	v_cvt_pk_fp8_f32 v248, v179, v254 op_sel:[0,0,1]
	v_exp_f32_e32 v0, v94
	v_exp_f32_e32 v177, v95
	v_exp_f32_e32 v179, v96
	v_exp_f32_e32 v254, v97
	v_add_f32_e32 v219, v0, v219
	v_add_f32_e32 v219, v177, v219
	v_cvt_pk_fp8_f32 v249, v0, v177
	v_add_f32_e32 v219, v179, v219
	v_add_f32_e32 v219, v254, v219
	v_cvt_pk_fp8_f32 v249, v179, v254 op_sel:[0,0,1]
	ds_read_b128 v[90:93], v185 offset:59392
	ds_read_b128 v[94:97], v186 offset:59392
	s_waitcnt lgkmcnt(4)
	v_mfma_scale_f32_32x32x64_f8f6f4 v[114:129], v[82:89], v[138:145], v[114:129], v194, v193 op_sel_hi:[0,0,0]
	v_exp_f32_e32 v0, v66
	v_exp_f32_e32 v177, v67
	v_exp_f32_e32 v179, v68
	v_exp_f32_e32 v254, v69
	v_add_f32_e32 v219, v0, v219
	v_add_f32_e32 v219, v177, v219
	v_cvt_pk_fp8_f32 v250, v0, v177
	v_add_f32_e32 v219, v179, v219
	v_add_f32_e32 v219, v254, v219
	v_cvt_pk_fp8_f32 v250, v179, v254 op_sel:[0,0,1]
	s_waitcnt lgkmcnt(2)
	v_mfma_scale_f32_32x32x64_f8f6f4 v[98:113], v[222:229], v[138:145], v[98:113], v194, v193 op_sel_hi:[0,0,0]
	ds_read_b128 v[222:225], v185 offset:61440
	ds_read_b128 v[226:229], v186 offset:61440
	v_exp_f32_e32 v0, v70
	v_exp_f32_e32 v177, v71
	v_exp_f32_e32 v179, v72
	v_exp_f32_e32 v254, v73
	v_add_f32_e32 v219, v0, v219
	v_add_f32_e32 v219, v177, v219
	v_cvt_pk_fp8_f32 v251, v0, v177
	v_add_f32_e32 v219, v179, v219
	v_add_f32_e32 v219, v254, v219
	v_cvt_pk_fp8_f32 v251, v179, v254 op_sel:[0,0,1]
	v_exp_f32_e32 v0, v74
	v_exp_f32_e32 v177, v75
	v_exp_f32_e32 v179, v76
	v_exp_f32_e32 v254, v77
	v_add_f32_e32 v219, v0, v219
	v_add_f32_e32 v219, v177, v219
	v_cvt_pk_fp8_f32 v252, v0, v177
	v_add_f32_e32 v219, v179, v219
	v_add_f32_e32 v219, v254, v219
	v_cvt_pk_fp8_f32 v252, v179, v254 op_sel:[0,0,1]
	s_waitcnt lgkmcnt(2)
; #define SLOAD() do { vs0 = *(const bf16x8*)(Vh + voff); vs1 = *(const bf16x8*)(Vh + voff + 32u * (unsigned)ldv); \
;     ks0 = *(const bf16x8*)(Kh + koff); ks1 = *(const bf16x8*)(Kh + koff + 32u * (unsigned)ldk); \
;     if constexpr (NR > 0) { kr = *(const bf16x8*)(Krh + kroff); kroff += 64u * 64u; } voff += 64u * (unsigned)ldv; koff += 64u * (unsigned)ldk; } while (0)
; #define SWRITE(b) do { *(bf16x8*)(V_lds + (b) * SHM_V + vst0) = vs0; *(bf16x8*)(V_lds + (b) * SHM_V + vst1) = vs1; const int kc = sc * 2;  \
;     *(bf16x8*)(K_lds + (b) * SHM_K + KSWZ(sr, kc)) = ks0; *(bf16x8*)(K_lds + (b) * SHM_K + KSWZ(32 + sr, kc)) = ks1; \
;     if constexpr (NR > 0) *(bf16x8*)(Kr_lds + (b) * SHM_KR + krst) = kr; } while (0)
; #define SLOAD() do { vs0 = *(const bf16x8*)(Vh + voff); vs1 = *(const bf16x8*)(Vh + voff + 32u * (unsigned)ldv); \
;     ks0 = *(const bf16x8*)(Kh + voff); ks1 = *(const bf16x8*)(Kh + voff + 32u * (unsigned)ldv); \
;     if constexpr (NR > 0) { kr = *(const bf16x8*)(Krh + kroff); kroff += 64u * 64u; } voff += 64u * (unsigned)ldv; } while (0)
; #define SWRITE(b) do { *(bf16x8*)(V_lds + (b) * SHM_V + vst0) = vs0; *(bf16x8*)(V_lds + (b) * SHM_V + vst0 + 8192) = vs1;  \
;     *(bf16x8*)(K_lds + (b) * SHM_K + kst0) = ks0; *(bf16x8*)(K_lds + (b) * SHM_K + kst0 + 8192) = ks1; \
;     if constexpr (NR > 0) *(bf16x8*)(Kr_lds + (b) * SHM_KR + krst) = kr; } while (0)
; #define SWRITE(b) do { *(v4i32*)(Vt_lds + (b) * 8192 + vtst) = vt; *(v4i32*)(Kn_lds + (b) * 8192 + knst) = kn; if (krw) *(v4i32*)(Kr_lds + (b) * 4096 + krst) = kr; } while (0)
; __device__ __forceinline__ void attn_unit7(const unsigned char* __restrict__ Q8, int ldq, const unsigned char* __restrict__ Kn8, int ldk, const unsigned char* __restrict__ Kr8, ...
;     ...
;   for (int j = 1; j + 1 < NT; j += 2) {
;     SLOAD();
;     qkt9(pB0, pB1, Kn_lds + 8192, Kr_lds + 4096, qf, 7.0f - m_reg, r32, hi);
;     finishSM9(pA0, pA1, alA, l_reg, p8);
;     pv8(o, Vt_lds, p8, r32, hi); partialSM9(pB0, pB1, m_reg, alB, thr_raw);
;     __syncthreads(); SWRITE(0);
;     RESC(alB); __syncthreads();
;     if (j + 2 < NT) SLOAD();
;     qkt9(pA0, pA1, Kn_lds, Kr_lds, qf, 7.0f - m_reg, r32, hi);
;     finishSM9(pB0, pB1, alB, l_reg, p8);
;     pv8(o, Vt_lds + 8192, p8, r32, hi); partialSM9(pA0, pA1, m_reg, alA, thr_raw);
;     __syncthreads(); if (j + 2 < NT) SWRITE(1);
;     RESC(alA); __syncthreads();
	v_mfma_scale_f32_32x32x64_f8f6f4 v[114:129], v[90:97], v[130:137], v[114:129], v194, v193 op_sel_hi:[0,0,0]
	v_exp_f32_e32 v0, v78
	v_exp_f32_e32 v177, v79
	v_exp_f32_e32 v179, v80
	v_exp_f32_e32 v254, v81
	v_add_f32_e32 v219, v0, v219
	v_add_f32_e32 v219, v177, v219
	v_cvt_pk_fp8_f32 v253, v0, v177
	v_add_f32_e32 v219, v179, v219
	v_add_f32_e32 v219, v254, v219
	v_cvt_pk_fp8_f32 v253, v179, v254 op_sel:[0,0,1]
	ds_read_b128 v[90:93], v185 offset:8192
	ds_read_b128 v[94:97], v186 offset:8192
	ds_read_b128 v[82:85], v185 offset:10240
	ds_read_b128 v[86:89], v186 offset:10240
	ds_read_b128 v[74:77], v185 offset:12288
	ds_read_b128 v[78:81], v186 offset:12288
	ds_read_b128 v[66:69], v185 offset:14336
	ds_read_b128 v[70:73], v186 offset:14336
	s_waitcnt lgkmcnt(8)
	v_mfma_scale_f32_32x32x64_f8f6f4 v[98:113], v[222:229], v[130:137], v[98:113], v194, v193 op_sel_hi:[0,0,0]
	v_mov_b32_e32 v0, v219
	s_nop 1
	v_permlane32_swap_b32_e32 v219, v0
	v_add_f32_e32 v219, v219, v0
	v_fma_f32 v209, v209, v218, v219
	v_max_f32_e32 v177, v114, v115
	v_max3_f32 v177, v177, v116, v117
	v_max3_f32 v177, v177, v118, v119
	v_max3_f32 v177, v177, v120, v121
	v_max3_f32 v177, v177, v122, v123
	v_max3_f32 v177, v177, v124, v125
	v_max3_f32 v177, v177, v126, v127
	v_max3_f32 v177, v177, v128, v129
	s_waitcnt lgkmcnt(6)
	v_mfma_scale_f32_32x32x64_f8f6f4 v[50:65], v[246:253], v[90:97], v[50:65], v194, v194 op_sel_hi:[0,0,0]
	s_waitcnt lgkmcnt(4)
	v_mfma_scale_f32_32x32x64_f8f6f4 v[34:49], v[246:253], v[82:89], v[34:49], v194, v194 op_sel_hi:[0,0,0]
	s_waitcnt lgkmcnt(2)
	v_mfma_scale_f32_32x32x64_f8f6f4 v[18:33], v[246:253], v[74:81], v[18:33], v194, v194 op_sel_hi:[0,0,0]
	s_waitcnt lgkmcnt(0)
	v_mfma_scale_f32_32x32x64_f8f6f4 v[2:17], v[246:253], v[66:73], v[2:17], v194, v194 op_sel_hi:[0,0,0]
	s_waitcnt vmcnt(0)
	ds_write_b128 v210, v[158:161]
	ds_write_b128 v211, v[162:165] offset:16384
	ds_write_b128 v212, v[154:157] offset:32768
	v_max_f32_e32 v0, v98, v99
	v_max3_f32 v0, v0, v100, v101
	v_max3_f32 v0, v0, v102, v103
	v_max3_f32 v0, v0, v104, v105
	v_max3_f32 v0, v0, v106, v107
	v_max3_f32 v0, v0, v108, v109
	v_max3_f32 v0, v0, v110, v111
	v_max3_f32 v0, v0, v112, v113
	v_max_f32_e32 v177, v177, v0
	v_mov_b32_e32 v0, v177
	v_mov_b32_e32 v221, 1.0
	s_nop 0
	v_permlane32_swap_b32_e32 v177, v0
	v_max_f32_e32 v177, v177, v0
	v_cmp_ge_f32_e32 vcc, s90, v177
	s_cmp_eq_u64 vcc, exec
	s_cbranch_scc0 .Lmla_h4_newmax
.Lmla_h4_cont:
	s_waitcnt lgkmcnt(0)
	s_barrier
	global_load_dwordx4 v[158:161], v176, s[18:19]
	global_load_dwordx4 v[162:165], v178, s[16:17]
	global_load_dwordx4 v[154:157], v[180:181], off
	ds_read_b128 v[82:85], v215 offset:16384
	ds_read_b128 v[86:89], v216 offset:16384
	ds_read_b128 v[222:225], v215 offset:20480
	ds_read_b128 v[226:229], v216 offset:20480
	v_add_u32_e32 v176, 0x2000, v176
	v_add_u32_e32 v178, 0x20000, v178
	s_mov_b64 s[20:21], 0x1000
	v_lshl_add_u64 v[180:181], v[180:181], 0, s[20:21]
	v_exp_f32_e32 v0, v114
	v_exp_f32_e32 v177, v115
	v_exp_f32_e32 v179, v116
	v_exp_f32_e32 v254, v117
	v_add_f32_e32 v219, v0, v177
	v_cvt_pk_fp8_f32 v246, v0, v177
	v_add_f32_e32 v219, v179, v219
	v_add_f32_e32 v219, v254, v219
	v_cvt_pk_fp8_f32 v246, v179, v254 op_sel:[0,0,1]
	s_waitcnt lgkmcnt(2)
	v_mfma_scale_f32_32x32x64_f8f6f4 v[82:97], v[82:89], v[146:153], v[230:245], v194, v193 op_sel_hi:[0,0,0]
	v_exp_f32_e32 v0, v118
	v_exp_f32_e32 v177, v119
	v_exp_f32_e32 v179, v120
	v_exp_f32_e32 v254, v121
	v_add_f32_e32 v219, v0, v219
	v_add_f32_e32 v219, v177, v219
	v_cvt_pk_fp8_f32 v247, v0, v177
	v_add_f32_e32 v219, v179, v219
	v_add_f32_e32 v219, v254, v219
	v_cvt_pk_fp8_f32 v247, v179, v254 op_sel:[0,0,1]
	ds_read_b128 v[114:117], v213 offset:16384
	ds_read_b128 v[118:121], v214 offset:16384
	s_waitcnt lgkmcnt(2)
	v_mfma_scale_f32_32x32x64_f8f6f4 v[66:81], v[222:229], v[146:153], v[230:245], v194, v193 op_sel_hi:[0,0,0]
	ds_read_b128 v[222:225], v213 offset:20480
	ds_read_b128 v[226:229], v214 offset:20480
	v_exp_f32_e32 v0, v122
	v_exp_f32_e32 v177, v123
	v_exp_f32_e32 v179, v124
	v_exp_f32_e32 v254, v125
	v_add_f32_e32 v219, v0, v219
	v_add_f32_e32 v219, v177, v219
	v_cvt_pk_fp8_f32 v248, v0, v177
	v_add_f32_e32 v219, v179, v219
	v_add_f32_e32 v219, v254, v219
	v_cvt_pk_fp8_f32 v248, v179, v254 op_sel:[0,0,1]
	v_exp_f32_e32 v0, v126
	v_exp_f32_e32 v177, v127
	v_exp_f32_e32 v179, v128
	v_exp_f32_e32 v254, v129
	v_add_f32_e32 v219, v0, v219
	v_add_f32_e32 v219, v177, v219
	v_cvt_pk_fp8_f32 v249, v0, v177
	v_add_f32_e32 v219, v179, v219
	v_add_f32_e32 v219, v254, v219
	v_cvt_pk_fp8_f32 v249, v179, v254 op_sel:[0,0,1]
	ds_read_b128 v[122:125], v185 offset:32768
	ds_read_b128 v[126:129], v186 offset:32768
	s_waitcnt lgkmcnt(4)
	v_mfma_scale_f32_32x32x64_f8f6f4 v[82:97], v[114:121], v[138:145], v[82:97], v194, v193 op_sel_hi:[0,0,0]
	v_exp_f32_e32 v0, v98
	v_exp_f32_e32 v177, v99
	v_exp_f32_e32 v179, v100
	v_exp_f32_e32 v254, v101
	v_add_f32_e32 v219, v0, v219
	v_add_f32_e32 v219, v177, v219
	v_cvt_pk_fp8_f32 v250, v0, v177
	v_add_f32_e32 v219, v179, v219
	v_add_f32_e32 v219, v254, v219
	v_cvt_pk_fp8_f32 v250, v179, v254 op_sel:[0,0,1]
	s_waitcnt lgkmcnt(2)
	v_mfma_scale_f32_32x32x64_f8f6f4 v[66:81], v[222:229], v[138:145], v[66:81], v194, v193 op_sel_hi:[0,0,0]
	ds_read_b128 v[222:225], v185 offset:34816
	ds_read_b128 v[226:229], v186 offset:34816
	v_exp_f32_e32 v0, v102
	v_exp_f32_e32 v177, v103
	v_exp_f32_e32 v179, v104
	v_exp_f32_e32 v254, v105
	v_add_f32_e32 v219, v0, v219
	v_add_f32_e32 v219, v177, v219
	v_cvt_pk_fp8_f32 v251, v0, v177
	v_add_f32_e32 v219, v179, v219
	v_add_f32_e32 v219, v254, v219
	v_cvt_pk_fp8_f32 v251, v179, v254 op_sel:[0,0,1]
	v_exp_f32_e32 v0, v106
	v_exp_f32_e32 v177, v107
	v_exp_f32_e32 v179, v108
	v_exp_f32_e32 v254, v109
	v_add_f32_e32 v219, v0, v219
	v_add_f32_e32 v219, v177, v219
	v_cvt_pk_fp8_f32 v252, v0, v177
	v_add_f32_e32 v219, v179, v219
	v_add_f32_e32 v219, v254, v219
	v_cvt_pk_fp8_f32 v252, v179, v254 op_sel:[0,0,1]
	s_waitcnt lgkmcnt(2)
; #define SLOAD() do { vs0 = *(const bf16x8*)(Vh + voff); vs1 = *(const bf16x8*)(Vh + voff + 32u * (unsigned)ldv); \
;     ks0 = *(const bf16x8*)(Kh + koff); ks1 = *(const bf16x8*)(Kh + koff + 32u * (unsigned)ldk); \
;     if constexpr (NR > 0) { kr = *(const bf16x8*)(Krh + kroff); kroff += 64u * 64u; } voff += 64u * (unsigned)ldv; koff += 64u * (unsigned)ldk; } while (0)
; #define SWRITE(b) do { *(bf16x8*)(V_lds + (b) * SHM_V + vst0) = vs0; *(bf16x8*)(V_lds + (b) * SHM_V + vst1) = vs1; const int kc = sc * 2;  \
;     *(bf16x8*)(K_lds + (b) * SHM_K + KSWZ(sr, kc)) = ks0; *(bf16x8*)(K_lds + (b) * SHM_K + KSWZ(32 + sr, kc)) = ks1; \
;     if constexpr (NR > 0) *(bf16x8*)(Kr_lds + (b) * SHM_KR + krst) = kr; } while (0)
; #define SLOAD() do { vs0 = *(const bf16x8*)(Vh + voff); vs1 = *(const bf16x8*)(Vh + voff + 32u * (unsigned)ldv); \
;     ks0 = *(const bf16x8*)(Kh + voff); ks1 = *(const bf16x8*)(Kh + voff + 32u * (unsigned)ldv); \
;     if constexpr (NR > 0) { kr = *(const bf16x8*)(Krh + kroff); kroff += 64u * 64u; } voff += 64u * (unsigned)ldv; } while (0)
; #define SWRITE(b) do { *(bf16x8*)(V_lds + (b) * SHM_V + vst0) = vs0; *(bf16x8*)(V_lds + (b) * SHM_V + vst0 + 8192) = vs1;  \
;     *(bf16x8*)(K_lds + (b) * SHM_K + kst0) = ks0; *(bf16x8*)(K_lds + (b) * SHM_K + kst0 + 8192) = ks1; \
;     if constexpr (NR > 0) *(bf16x8*)(Kr_lds + (b) * SHM_KR + krst) = kr; } while (0)
; #define SWRITE(b) do { *(v4i32*)(Vt_lds + (b) * 8192 + vtst) = vt; *(v4i32*)(Kn_lds + (b) * 8192 + knst) = kn; if (krw) *(v4i32*)(Kr_lds + (b) * 4096 + krst) = kr; } while (0)
; __device__ __forceinline__ void attn_unit7(const unsigned char* __restrict__ Q8, int ldq, const unsigned char* __restrict__ Kn8, int ldk, const unsigned char* __restrict__ Kr8, ...
;     ...
;   for (int j = 1; j + 1 < NT; j += 2) {
;     SLOAD();
;     qkt9(pB0, pB1, Kn_lds + 8192, Kr_lds + 4096, qf, 7.0f - m_reg, r32, hi);
;     finishSM9(pA0, pA1, alA, l_reg, p8);
;     pv8(o, Vt_lds, p8, r32, hi); partialSM9(pB0, pB1, m_reg, alB, thr_raw);
;     __syncthreads(); SWRITE(0);
;     RESC(alB); __syncthreads();
;     if (j + 2 < NT) SLOAD();
;     qkt9(pA0, pA1, Kn_lds, Kr_lds, qf, 7.0f - m_reg, r32, hi);
;     finishSM9(pB0, pB1, alB, l_reg, p8);
;     pv8(o, Vt_lds + 8192, p8, r32, hi); partialSM9(pA0, pA1, m_reg, alA, thr_raw);
;     __syncthreads(); if (j + 2 < NT) SWRITE(1);
;     RESC(alA); __syncthreads();
	v_mfma_scale_f32_32x32x64_f8f6f4 v[82:97], v[122:129], v[130:137], v[82:97], v194, v193 op_sel_hi:[0,0,0]
	v_exp_f32_e32 v0, v110
	v_exp_f32_e32 v177, v111
	v_exp_f32_e32 v179, v112
	v_exp_f32_e32 v254, v113
	v_add_f32_e32 v219, v0, v219
	v_add_f32_e32 v219, v177, v219
	v_cvt_pk_fp8_f32 v253, v0, v177
	v_add_f32_e32 v219, v179, v219
	v_add_f32_e32 v219, v254, v219
	v_cvt_pk_fp8_f32 v253, v179, v254 op_sel:[0,0,1]
	ds_read_b128 v[122:125], v185 offset:43008
	ds_read_b128 v[126:129], v186 offset:43008
	ds_read_b128 v[114:117], v185 offset:45056
	ds_read_b128 v[118:121], v186 offset:45056
	ds_read_b128 v[106:109], v185 offset:47104
	ds_read_b128 v[110:113], v186 offset:47104
	ds_read_b128 v[98:101], v185 offset:49152
	ds_read_b128 v[102:105], v186 offset:49152
	s_waitcnt lgkmcnt(8)
	v_mfma_scale_f32_32x32x64_f8f6f4 v[66:81], v[222:229], v[130:137], v[66:81], v194, v193 op_sel_hi:[0,0,0]
	v_mov_b32_e32 v0, v219
	s_nop 1
	v_permlane32_swap_b32_e32 v219, v0
	v_add_f32_e32 v219, v219, v0
	v_fma_f32 v209, v209, v221, v219
	v_max_f32_e32 v177, v82, v83
	v_max3_f32 v177, v177, v84, v85
	v_max3_f32 v177, v177, v86, v87
	v_max3_f32 v177, v177, v88, v89
	v_max3_f32 v177, v177, v90, v91
	v_max3_f32 v177, v177, v92, v93
	v_max3_f32 v177, v177, v94, v95
	v_max3_f32 v177, v177, v96, v97
	s_waitcnt lgkmcnt(6)
	v_mfma_scale_f32_32x32x64_f8f6f4 v[50:65], v[246:253], v[122:129], v[50:65], v194, v194 op_sel_hi:[0,0,0]
	s_waitcnt lgkmcnt(4)
	v_mfma_scale_f32_32x32x64_f8f6f4 v[34:49], v[246:253], v[114:121], v[34:49], v194, v194 op_sel_hi:[0,0,0]
	s_waitcnt lgkmcnt(2)
	v_mfma_scale_f32_32x32x64_f8f6f4 v[18:33], v[246:253], v[106:113], v[18:33], v194, v194 op_sel_hi:[0,0,0]
	s_waitcnt lgkmcnt(0)
	v_mfma_scale_f32_32x32x64_f8f6f4 v[2:17], v[246:253], v[98:105], v[2:17], v194, v194 op_sel_hi:[0,0,0]
	s_waitcnt vmcnt(0)
	ds_write_b128 v210, v[158:161] offset:8192
	ds_write_b128 v211, v[162:165] offset:24576
	ds_write_b128 v212, v[154:157] offset:36864
	v_max_f32_e32 v0, v66, v67
	v_max3_f32 v0, v0, v68, v69
	v_max3_f32 v0, v0, v70, v71
	v_max3_f32 v0, v0, v72, v73
	v_max3_f32 v0, v0, v74, v75
	v_max3_f32 v0, v0, v76, v77
	v_max3_f32 v0, v0, v78, v79
	v_max3_f32 v0, v0, v80, v81
	v_max_f32_e32 v177, v177, v0
	v_mov_b32_e32 v0, v177
	v_mov_b32_e32 v218, 1.0
	s_nop 0
	v_permlane32_swap_b32_e32 v177, v0
	v_max_f32_e32 v177, v177, v0
	v_cmp_ge_f32_e32 vcc, s90, v177
	s_cmp_eq_u64 vcc, exec
	s_cbranch_scc0 .Lmla_h5_newmax
; #define SLOAD() do { vs0 = *(const bf16x8*)(Vh + voff); vs1 = *(const bf16x8*)(Vh + voff + 32u * (unsigned)ldv); \
;     ks0 = *(const bf16x8*)(Kh + koff); ks1 = *(const bf16x8*)(Kh + koff + 32u * (unsigned)ldk); \
;     if constexpr (NR > 0) { kr = *(const bf16x8*)(Krh + kroff); kroff += 64u * 64u; } voff += 64u * (unsigned)ldv; koff += 64u * (unsigned)ldk; } while (0)
; #define SWRITE(b) do { *(bf16x8*)(V_lds + (b) * SHM_V + vst0) = vs0; *(bf16x8*)(V_lds + (b) * SHM_V + vst1) = vs1; const int kc = sc * 2;  \
;     *(bf16x8*)(K_lds + (b) * SHM_K + KSWZ(sr, kc)) = ks0; *(bf16x8*)(K_lds + (b) * SHM_K + KSWZ(32 + sr, kc)) = ks1; \
;     if constexpr (NR > 0) *(bf16x8*)(Kr_lds + (b) * SHM_KR + krst) = kr; } while (0)
; #define SLOAD() do { vs0 = *(const bf16x8*)(Vh + voff); vs1 = *(const bf16x8*)(Vh + voff + 32u * (unsigned)ldv); \
;     ks0 = *(const bf16x8*)(Kh + voff); ks1 = *(const bf16x8*)(Kh + voff + 32u * (unsigned)ldv); \
;     if constexpr (NR > 0) { kr = *(const bf16x8*)(Krh + kroff); kroff += 64u * 64u; } voff += 64u * (unsigned)ldv; } while (0)
; #define SWRITE(b) do { *(bf16x8*)(V_lds + (b) * SHM_V + vst0) = vs0; *(bf16x8*)(V_lds + (b) * SHM_V + vst0 + 8192) = vs1;  \
;     *(bf16x8*)(K_lds + (b) * SHM_K + kst0) = ks0; *(bf16x8*)(K_lds + (b) * SHM_K + kst0 + 8192) = ks1; \
;     if constexpr (NR > 0) *(bf16x8*)(Kr_lds + (b) * SHM_KR + krst) = kr; } while (0)
; __device__ __forceinline__ void attn_unit7(const unsigned char* __restrict__ Q8, int ldq, const unsigned char* __restrict__ Kn8, int ldk, const unsigned char* __restrict__ Kr8, ...
;     ...
;   for (int j = 1; j + 1 < NT; j += 2) {
;     SLOAD();
;     qkt9(pB0, pB1, Kn_lds + 8192, Kr_lds + 4096, qf, 7.0f - m_reg, r32, hi);
;     finishSM9(pA0, pA1, alA, l_reg, p8);
;     pv8(o, Vt_lds, p8, r32, hi); partialSM9(pB0, pB1, m_reg, alB, thr_raw);
;     __syncthreads(); SWRITE(0);
;     RESC(alB); __syncthreads();
;     if (j + 2 < NT) SLOAD();
;     qkt9(pA0, pA1, Kn_lds, Kr_lds, qf, 7.0f - m_reg, r32, hi);
;     finishSM9(pB0, pB1, alB, l_reg, p8);
;     pv8(o, Vt_lds + 8192, p8, r32, hi); partialSM9(pA0, pA1, m_reg, alA, thr_raw);
;     __syncthreads(); if (j + 2 < NT) SWRITE(1);
;     RESC(alA); __syncthreads();
;   }
;   qkt9(pB0, pB1, Kn_lds + 8192, Kr_lds + 4096, qf, 7.0f - m_reg, r32, hi);
.Lmla_h5_cont:
	s_waitcnt lgkmcnt(0)
	s_barrier
	s_add_i32 s30, s30, 1
	s_cmpk_lt_u32 s30, 42
	s_cbranch_scc1 .LBB0_1321
	global_load_dwordx4 v[158:161], v176, s[18:19]
	global_load_dwordx4 v[162:165], v178, s[16:17]
	global_load_dwordx4 v[154:157], v[180:181], off
	ds_read_b128 v[114:117], v215 offset:24576
	ds_read_b128 v[118:121], v216 offset:24576
	ds_read_b128 v[222:225], v215 offset:28672
	ds_read_b128 v[226:229], v216 offset:28672
	v_add_u32_e32 v176, 0x2000, v176
	v_add_u32_e32 v178, 0x20000, v178
	s_mov_b64 s[20:21], 0x1000
	v_lshl_add_u64 v[180:181], v[180:181], 0, s[20:21]
	v_exp_f32_e32 v0, v82
	v_exp_f32_e32 v177, v83
	v_exp_f32_e32 v179, v84
	v_exp_f32_e32 v254, v85
	v_add_f32_e32 v219, v0, v177
	v_cvt_pk_fp8_f32 v246, v0, v177
	v_add_f32_e32 v219, v179, v219
	v_add_f32_e32 v219, v254, v219
	v_cvt_pk_fp8_f32 v246, v179, v254 op_sel:[0,0,1]
	s_waitcnt lgkmcnt(2)
	v_mfma_scale_f32_32x32x64_f8f6f4 v[114:129], v[114:121], v[146:153], v[230:245], v194, v193 op_sel_hi:[0,0,0]
	v_exp_f32_e32 v0, v86
	v_exp_f32_e32 v177, v87
	v_exp_f32_e32 v179, v88
	v_exp_f32_e32 v254, v89
	v_add_f32_e32 v219, v0, v219
	v_add_f32_e32 v219, v177, v219
	v_cvt_pk_fp8_f32 v247, v0, v177
	v_add_f32_e32 v219, v179, v219
	v_add_f32_e32 v219, v254, v219
	v_cvt_pk_fp8_f32 v247, v179, v254 op_sel:[0,0,1]
	ds_read_b128 v[82:85], v213 offset:24576
	ds_read_b128 v[86:89], v214 offset:24576
	s_waitcnt lgkmcnt(2)
	v_mfma_scale_f32_32x32x64_f8f6f4 v[98:113], v[222:229], v[146:153], v[230:245], v194, v193 op_sel_hi:[0,0,0]
	ds_read_b128 v[222:225], v213 offset:28672
	ds_read_b128 v[226:229], v214 offset:28672
	v_exp_f32_e32 v0, v90
	v_exp_f32_e32 v177, v91
	v_exp_f32_e32 v179, v92
	v_exp_f32_e32 v254, v93
	v_add_f32_e32 v219, v0, v219
	v_add_f32_e32 v219, v177, v219
	v_cvt_pk_fp8_f32 v248, v0, v177
	v_add_f32_e32 v219, v179, v219
	v_add_f32_e32 v219, v254, v219
	v_cvt_pk_fp8_f32 v248, v179, v254 op_sel:[0,0,1]
	v_exp_f32_e32 v0, v94
	v_exp_f32_e32 v177, v95
	v_exp_f32_e32 v179, v96
	v_exp_f32_e32 v254, v97
	v_add_f32_e32 v219, v0, v219
	v_add_f32_e32 v219, v177, v219
	v_cvt_pk_fp8_f32 v249, v0, v177
	v_add_f32_e32 v219, v179, v219
	v_add_f32_e32 v219, v254, v219
	v_cvt_pk_fp8_f32 v249, v179, v254 op_sel:[0,0,1]
	ds_read_b128 v[90:93], v185 offset:36864
	ds_read_b128 v[94:97], v186 offset:36864
	s_waitcnt lgkmcnt(4)
	v_mfma_scale_f32_32x32x64_f8f6f4 v[114:129], v[82:89], v[138:145], v[114:129], v194, v193 op_sel_hi:[0,0,0]
	v_exp_f32_e32 v0, v66
	v_exp_f32_e32 v177, v67
	v_exp_f32_e32 v179, v68
	v_exp_f32_e32 v254, v69
	v_add_f32_e32 v219, v0, v219
	v_add_f32_e32 v219, v177, v219
	v_cvt_pk_fp8_f32 v250, v0, v177
	v_add_f32_e32 v219, v179, v219
	v_add_f32_e32 v219, v254, v219
	v_cvt_pk_fp8_f32 v250, v179, v254 op_sel:[0,0,1]
	s_waitcnt lgkmcnt(2)
	v_mfma_scale_f32_32x32x64_f8f6f4 v[98:113], v[222:229], v[138:145], v[98:113], v194, v193 op_sel_hi:[0,0,0]
	ds_read_b128 v[222:225], v185 offset:38912
	ds_read_b128 v[226:229], v186 offset:38912
	v_exp_f32_e32 v0, v70
	v_exp_f32_e32 v177, v71
	v_exp_f32_e32 v179, v72
	v_exp_f32_e32 v254, v73
	v_add_f32_e32 v219, v0, v219
	v_add_f32_e32 v219, v177, v219
	v_cvt_pk_fp8_f32 v251, v0, v177
	v_add_f32_e32 v219, v179, v219
	v_add_f32_e32 v219, v254, v219
	v_cvt_pk_fp8_f32 v251, v179, v254 op_sel:[0,0,1]
	v_exp_f32_e32 v0, v74
	v_exp_f32_e32 v177, v75
	v_exp_f32_e32 v179, v76
	v_exp_f32_e32 v254, v77
	v_add_f32_e32 v219, v0, v219
	v_add_f32_e32 v219, v177, v219
	v_cvt_pk_fp8_f32 v252, v0, v177
	v_add_f32_e32 v219, v179, v219
	v_add_f32_e32 v219, v254, v219
	v_cvt_pk_fp8_f32 v252, v179, v254 op_sel:[0,0,1]
	s_waitcnt lgkmcnt(2)
	v_mfma_scale_f32_32x32x64_f8f6f4 v[114:129], v[90:97], v[130:137], v[114:129], v194, v193 op_sel_hi:[0,0,0]
	v_exp_f32_e32 v0, v78
	v_exp_f32_e32 v177, v79
	v_exp_f32_e32 v179, v80
	v_exp_f32_e32 v254, v81
	v_add_f32_e32 v219, v0, v219
	v_add_f32_e32 v219, v177, v219
	v_cvt_pk_fp8_f32 v253, v0, v177
	v_add_f32_e32 v219, v179, v219
	v_add_f32_e32 v219, v254, v219
	v_cvt_pk_fp8_f32 v253, v179, v254 op_sel:[0,0,1]
	ds_read_b128 v[90:93], v185 offset:0
	ds_read_b128 v[94:97], v186 offset:0
	ds_read_b128 v[82:85], v185 offset:2048
	ds_read_b128 v[86:89], v186 offset:2048
	ds_read_b128 v[74:77], v185 offset:4096
	ds_read_b128 v[78:81], v186 offset:4096
	ds_read_b128 v[66:69], v185 offset:6144
	ds_read_b128 v[70:73], v186 offset:6144
	s_waitcnt lgkmcnt(8)
	v_mfma_scale_f32_32x32x64_f8f6f4 v[98:113], v[222:229], v[130:137], v[98:113], v194, v193 op_sel_hi:[0,0,0]
	v_mov_b32_e32 v0, v219
	s_nop 1
	v_permlane32_swap_b32_e32 v219, v0
	v_add_f32_e32 v219, v219, v0
	v_fma_f32 v209, v209, v218, v219
	v_max_f32_e32 v177, v114, v115
	v_max3_f32 v177, v177, v116, v117
	v_max3_f32 v177, v177, v118, v119
	v_max3_f32 v177, v177, v120, v121
	v_max3_f32 v177, v177, v122, v123
	v_max3_f32 v177, v177, v124, v125
	v_max3_f32 v177, v177, v126, v127
	v_max3_f32 v177, v177, v128, v129
	s_waitcnt lgkmcnt(6)
	v_mfma_scale_f32_32x32x64_f8f6f4 v[50:65], v[246:253], v[90:97], v[50:65], v194, v194 op_sel_hi:[0,0,0]
	s_waitcnt lgkmcnt(4)
	v_mfma_scale_f32_32x32x64_f8f6f4 v[34:49], v[246:253], v[82:89], v[34:49], v194, v194 op_sel_hi:[0,0,0]
	s_waitcnt lgkmcnt(2)
	v_mfma_scale_f32_32x32x64_f8f6f4 v[18:33], v[246:253], v[74:81], v[18:33], v194, v194 op_sel_hi:[0,0,0]
	s_waitcnt lgkmcnt(0)
	v_mfma_scale_f32_32x32x64_f8f6f4 v[2:17], v[246:253], v[66:73], v[2:17], v194, v194 op_sel_hi:[0,0,0]
	s_waitcnt vmcnt(0)
	ds_write_b128 v210, v[158:161] offset:43008
	ds_write_b128 v211, v[162:165] offset:51200
	ds_write_b128 v212, v[154:157] offset:59392
	v_max_f32_e32 v0, v98, v99
	v_max3_f32 v0, v0, v100, v101
	v_max3_f32 v0, v0, v102, v103
	v_max3_f32 v0, v0, v104, v105
	v_max3_f32 v0, v0, v106, v107
	v_max3_f32 v0, v0, v108, v109
	v_max3_f32 v0, v0, v110, v111
	v_max3_f32 v0, v0, v112, v113
	v_max_f32_e32 v177, v177, v0
	v_mov_b32_e32 v0, v177
	v_mov_b32_e32 v221, 1.0
	s_nop 0
	v_permlane32_swap_b32_e32 v177, v0
	v_max_f32_e32 v177, v177, v0
	v_cmp_ge_f32_e32 vcc, s90, v177
	s_cmp_eq_u64 vcc, exec
	s_cbranch_scc0 .Lmla_p0_newmax

; #define SLOAD() do { vs0 = *(const bf16x8*)(Vh + voff); vs1 = *(const bf16x8*)(Vh + voff + 32u * (unsigned)ldv); \
;     ks0 = *(const bf16x8*)(Kh + koff); ks1 = *(const bf16x8*)(Kh + koff + 32u * (unsigned)ldk); \
;     if constexpr (NR > 0) { kr = *(const bf16x8*)(Krh + kroff); kroff += 64u * 64u; } voff += 64u * (unsigned)ldv; koff += 64u * (unsigned)ldk; } while (0)
; #define SWRITE(b) do { *(bf16x8*)(V_lds + (b) * SHM_V + vst0) = vs0; *(bf16x8*)(V_lds + (b) * SHM_V + vst1) = vs1; const int kc = sc * 2;  \
;     *(bf16x8*)(K_lds + (b) * SHM_K + KSWZ(sr, kc)) = ks0; *(bf16x8*)(K_lds + (b) * SHM_K + KSWZ(32 + sr, kc)) = ks1; \
;     if constexpr (NR > 0) *(bf16x8*)(Kr_lds + (b) * SHM_KR + krst) = kr; } while (0)
; #define SLOAD() do { vs0 = *(const bf16x8*)(Vh + voff); vs1 = *(const bf16x8*)(Vh + voff + 32u * (unsigned)ldv); \
;     ks0 = *(const bf16x8*)(Kh + voff); ks1 = *(const bf16x8*)(Kh + voff + 32u * (unsigned)ldv); \
;     if constexpr (NR > 0) { kr = *(const bf16x8*)(Krh + kroff); kroff += 64u * 64u; } voff += 64u * (unsigned)ldv; } while (0)
; #define SWRITE(b) do { *(bf16x8*)(V_lds + (b) * SHM_V + vst0) = vs0; *(bf16x8*)(V_lds + (b) * SHM_V + vst0 + 8192) = vs1;  \
;     *(bf16x8*)(K_lds + (b) * SHM_K + kst0) = ks0; *(bf16x8*)(K_lds + (b) * SHM_K + kst0 + 8192) = ks1; \
;     if constexpr (NR > 0) *(bf16x8*)(Kr_lds + (b) * SHM_KR + krst) = kr; } while (0)
; #define RESC(a) do { if (__any((a) < 1.f)) { if (hi == 0) al_l[r32] = (a); asm volatile("s_waitcnt lgkmcnt(0)" ::: "memory"); \
;     _Pragma("unroll") for (int d = 0; d < 4; ++d) _Pragma("unroll") for (int r = 0; r < 16; ++r) o[d][r] *= al_l[crow(r, hi)]; } } while (0)
; __device__ __forceinline__ void attn_unit7(const unsigned char* __restrict__ Q8, int ldq, const unsigned char* __restrict__ Kn8, int ldk, const unsigned char* __restrict__ Kr8, ...
;     ...
;   SLOAD(); SWRITE(0); __syncthreads();
;   SLOAD();
;   qkt9(pA0, pA1, Kn_lds, Kr_lds, qf, 7.0f - m_reg, r32, hi); partialSM9(pA0, pA1, m_reg, alA, thr_raw);
;   SWRITE(1); __syncthreads();
;   for (int j = 1; j + 1 < NT; j += 2) {
;     SLOAD();
;     qkt9(pB0, pB1, Kn_lds + 8192, Kr_lds + 4096, qf, 7.0f - m_reg, r32, hi);
;     finishSM9(pA0, pA1, alA, l_reg, p8);
;     pv8(o, Vt_lds, p8, r32, hi); partialSM9(pB0, pB1, m_reg, alB, thr_raw);
;     __syncthreads(); SWRITE(0);
;     RESC(alB); __syncthreads();
.Lmla_stag_entry:
	global_load_dwordx4 v[158:161], v176, s[18:19]
	global_load_dwordx4 v[162:165], v178, s[16:17]
	s_nop 1
	v_add_u32_e32 v176, 0x2000, v176
	v_add_u32_e32 v178, 0x20000, v178
.Lmla_stag_loop:
	ds_read_b128 v[114:117], v215 offset:24576
	ds_read_b128 v[118:121], v216 offset:24576
	ds_read_b128 v[222:225], v215 offset:28672
	ds_read_b128 v[226:229], v216 offset:28672
	v_exp_f32_e32 v0, v82
	v_exp_f32_e32 v177, v83
	v_exp_f32_e32 v179, v84
	v_exp_f32_e32 v254, v85
	v_add_f32_e32 v219, v0, v177
	v_cvt_pk_fp8_f32 v246, v0, v177
	v_add_f32_e32 v219, v179, v219
	v_add_f32_e32 v219, v254, v219
	v_cvt_pk_fp8_f32 v246, v179, v254 op_sel:[0,0,1]
	s_waitcnt lgkmcnt(2)
	v_mfma_scale_f32_32x32x64_f8f6f4 v[114:129], v[114:121], v[146:153], v[230:245], v194, v193 op_sel_hi:[0,0,0]
	v_exp_f32_e32 v0, v86
	v_exp_f32_e32 v177, v87
	v_exp_f32_e32 v179, v88
	v_exp_f32_e32 v254, v89
	v_add_f32_e32 v219, v0, v219
	v_add_f32_e32 v219, v177, v219
	v_cvt_pk_fp8_f32 v247, v0, v177
	v_add_f32_e32 v219, v179, v219
	v_add_f32_e32 v219, v254, v219
	v_cvt_pk_fp8_f32 v247, v179, v254 op_sel:[0,0,1]
	ds_read_b128 v[82:85], v213 offset:24576
	ds_read_b128 v[86:89], v214 offset:24576
	s_waitcnt lgkmcnt(2)
	v_mfma_scale_f32_32x32x64_f8f6f4 v[98:113], v[222:229], v[146:153], v[230:245], v194, v193 op_sel_hi:[0,0,0]
	ds_read_b128 v[222:225], v213 offset:28672
	ds_read_b128 v[226:229], v214 offset:28672
	v_exp_f32_e32 v0, v90
	v_exp_f32_e32 v177, v91
	v_exp_f32_e32 v179, v92
	v_exp_f32_e32 v254, v93
	v_add_f32_e32 v219, v0, v219
	v_add_f32_e32 v219, v177, v219
	v_cvt_pk_fp8_f32 v248, v0, v177
	v_add_f32_e32 v219, v179, v219
	v_add_f32_e32 v219, v254, v219
	v_cvt_pk_fp8_f32 v248, v179, v254 op_sel:[0,0,1]
	v_exp_f32_e32 v0, v94
	v_exp_f32_e32 v177, v95
	v_exp_f32_e32 v179, v96
	v_exp_f32_e32 v254, v97
	v_add_f32_e32 v219, v0, v219
	v_add_f32_e32 v219, v177, v219
	v_cvt_pk_fp8_f32 v249, v0, v177
	v_add_f32_e32 v219, v179, v219
	v_add_f32_e32 v219, v254, v219
	v_cvt_pk_fp8_f32 v249, v179, v254 op_sel:[0,0,1]
	ds_read_b128 v[90:93], v185 offset:36864
	ds_read_b128 v[94:97], v186 offset:36864
	s_waitcnt lgkmcnt(4)
	v_mfma_scale_f32_32x32x64_f8f6f4 v[114:129], v[82:89], v[138:145], v[114:129], v194, v193 op_sel_hi:[0,0,0]
	v_exp_f32_e32 v0, v66
	v_exp_f32_e32 v177, v67
	v_exp_f32_e32 v179, v68
	v_exp_f32_e32 v254, v69
	v_add_f32_e32 v219, v0, v219
	v_add_f32_e32 v219, v177, v219
	v_cvt_pk_fp8_f32 v250, v0, v177
	v_add_f32_e32 v219, v179, v219
	v_add_f32_e32 v219, v254, v219
	v_cvt_pk_fp8_f32 v250, v179, v254 op_sel:[0,0,1]
	s_waitcnt lgkmcnt(2)
	v_mfma_scale_f32_32x32x64_f8f6f4 v[98:113], v[222:229], v[138:145], v[98:113], v194, v193 op_sel_hi:[0,0,0]
	ds_read_b128 v[222:225], v185 offset:38912
	ds_read_b128 v[226:229], v186 offset:38912
	v_exp_f32_e32 v0, v70
	v_exp_f32_e32 v177, v71
	v_exp_f32_e32 v179, v72
	v_exp_f32_e32 v254, v73
	v_add_f32_e32 v219, v0, v219
	v_add_f32_e32 v219, v177, v219
	v_cvt_pk_fp8_f32 v251, v0, v177
	v_add_f32_e32 v219, v179, v219
	v_add_f32_e32 v219, v254, v219
	v_cvt_pk_fp8_f32 v251, v179, v254 op_sel:[0,0,1]
	v_exp_f32_e32 v0, v74
	v_exp_f32_e32 v177, v75
	v_exp_f32_e32 v179, v76
	v_exp_f32_e32 v254, v77
	v_add_f32_e32 v219, v0, v219
	v_add_f32_e32 v219, v177, v219
	v_cvt_pk_fp8_f32 v252, v0, v177
	v_add_f32_e32 v219, v179, v219
	v_add_f32_e32 v219, v254, v219
	v_cvt_pk_fp8_f32 v252, v179, v254 op_sel:[0,0,1]
	s_waitcnt lgkmcnt(2)
	v_mfma_scale_f32_32x32x64_f8f6f4 v[114:129], v[90:97], v[130:137], v[114:129], v194, v193 op_sel_hi:[0,0,0]
	v_exp_f32_e32 v0, v78
	v_exp_f32_e32 v177, v79
	v_exp_f32_e32 v179, v80
	v_exp_f32_e32 v254, v81
	v_add_f32_e32 v219, v0, v219
	v_add_f32_e32 v219, v177, v219
	v_cvt_pk_fp8_f32 v253, v0, v177
	v_add_f32_e32 v219, v179, v219
	v_add_f32_e32 v219, v254, v219
	v_cvt_pk_fp8_f32 v253, v179, v254 op_sel:[0,0,1]
	ds_read_b128 v[90:93], v185 offset:0
	ds_read_b128 v[94:97], v186 offset:0
	ds_read_b128 v[82:85], v185 offset:2048
	ds_read_b128 v[86:89], v186 offset:2048
	ds_read_b128 v[74:77], v185 offset:4096
	ds_read_b128 v[78:81], v186 offset:4096
	ds_read_b128 v[66:69], v185 offset:6144
	ds_read_b128 v[70:73], v186 offset:6144
	s_waitcnt lgkmcnt(8)
	v_mfma_scale_f32_32x32x64_f8f6f4 v[98:113], v[222:229], v[130:137], v[98:113], v194, v193 op_sel_hi:[0,0,0]
	v_mov_b32_e32 v0, v219
	s_nop 1
	v_permlane32_swap_b32_e32 v219, v0
	v_add_f32_e32 v219, v219, v0
	v_fma_f32 v209, v209, v218, v219
	s_waitcnt vmcnt(0)
	ds_write_b128 v210, v[158:161] offset:43008
	ds_write_b128 v211, v[162:165] offset:51200
	s_waitcnt lgkmcnt(0)
	s_barrier
	global_load_dwordx4 v[158:161], v176, s[18:19]
	global_load_dwordx4 v[162:165], v178, s[16:17]
	v_max_f32_e32 v177, v114, v115
	v_max3_f32 v177, v177, v116, v117
	v_max3_f32 v177, v177, v118, v119
	v_max3_f32 v177, v177, v120, v121
	v_max3_f32 v177, v177, v122, v123
	v_max3_f32 v177, v177, v124, v125
	v_max3_f32 v177, v177, v126, v127
	v_max3_f32 v177, v177, v128, v129
	v_add_u32_e32 v176, 0x2000, v176
	v_add_u32_e32 v178, 0x20000, v178
	v_mfma_scale_f32_32x32x64_f8f6f4 v[50:65], v[246:253], v[90:97], v[50:65], v194, v194 op_sel_hi:[0,0,0]
	v_mfma_scale_f32_32x32x64_f8f6f4 v[34:49], v[246:253], v[82:89], v[34:49], v194, v194 op_sel_hi:[0,0,0]
	v_mfma_scale_f32_32x32x64_f8f6f4 v[18:33], v[246:253], v[74:81], v[18:33], v194, v194 op_sel_hi:[0,0,0]
	v_mfma_scale_f32_32x32x64_f8f6f4 v[2:17], v[246:253], v[66:73], v[2:17], v194, v194 op_sel_hi:[0,0,0]
	v_max_f32_e32 v0, v98, v99
	v_max3_f32 v0, v0, v100, v101
	v_max3_f32 v0, v0, v102, v103
	v_max3_f32 v0, v0, v104, v105
	v_max3_f32 v0, v0, v106, v107
	v_max3_f32 v0, v0, v108, v109
	v_max3_f32 v0, v0, v110, v111
	v_max3_f32 v0, v0, v112, v113
	v_max_f32_e32 v177, v177, v0
	v_mov_b32_e32 v0, v177
	v_mov_b32_e32 v221, 1.0
	s_nop 0
	v_permlane32_swap_b32_e32 v177, v0
	v_max_f32_e32 v177, v177, v0
	v_cmp_ge_f32_e32 vcc, s90, v177
	s_cmp_eq_u64 vcc, exec
	s_cbranch_scc0 .Lmla_s0_newmax
; #define SLOAD() do { vs0 = *(const bf16x8*)(Vh + voff); vs1 = *(const bf16x8*)(Vh + voff + 32u * (unsigned)ldv); \
;     ks0 = *(const bf16x8*)(Kh + koff); ks1 = *(const bf16x8*)(Kh + koff + 32u * (unsigned)ldk); \
;     if constexpr (NR > 0) { kr = *(const bf16x8*)(Krh + kroff); kroff += 64u * 64u; } voff += 64u * (unsigned)ldv; koff += 64u * (unsigned)ldk; } while (0)
; #define SWRITE(b) do { *(bf16x8*)(V_lds + (b) * SHM_V + vst0) = vs0; *(bf16x8*)(V_lds + (b) * SHM_V + vst1) = vs1; const int kc = sc * 2;  \
;     *(bf16x8*)(K_lds + (b) * SHM_K + KSWZ(sr, kc)) = ks0; *(bf16x8*)(K_lds + (b) * SHM_K + KSWZ(32 + sr, kc)) = ks1; \
;     if constexpr (NR > 0) *(bf16x8*)(Kr_lds + (b) * SHM_KR + krst) = kr; } while (0)
; #define SLOAD() do { vs0 = *(const bf16x8*)(Vh + voff); vs1 = *(const bf16x8*)(Vh + voff + 32u * (unsigned)ldv); \
;     ks0 = *(const bf16x8*)(Kh + voff); ks1 = *(const bf16x8*)(Kh + voff + 32u * (unsigned)ldv); \
;     if constexpr (NR > 0) { kr = *(const bf16x8*)(Krh + kroff); kroff += 64u * 64u; } voff += 64u * (unsigned)ldv; } while (0)
; #define SWRITE(b) do { *(bf16x8*)(V_lds + (b) * SHM_V + vst0) = vs0; *(bf16x8*)(V_lds + (b) * SHM_V + vst0 + 8192) = vs1;  \
;     *(bf16x8*)(K_lds + (b) * SHM_K + kst0) = ks0; *(bf16x8*)(K_lds + (b) * SHM_K + kst0 + 8192) = ks1; \
;     if constexpr (NR > 0) *(bf16x8*)(Kr_lds + (b) * SHM_KR + krst) = kr; } while (0)
; #define SWRITE(b) do { *(v4i32*)(Vt_lds + (b) * 8192 + vtst) = vt; *(v4i32*)(Kn_lds + (b) * 8192 + knst) = kn; if (krw) *(v4i32*)(Kr_lds + (b) * 4096 + krst) = kr; } while (0)
; __device__ __forceinline__ void attn_unit7(const unsigned char* __restrict__ Q8, int ldq, const unsigned char* __restrict__ Kn8, int ldk, const unsigned char* __restrict__ Kr8, ...
;     ...
;   for (int j = 1; j + 1 < NT; j += 2) {
;     SLOAD();
;     qkt9(pB0, pB1, Kn_lds + 8192, Kr_lds + 4096, qf, 7.0f - m_reg, r32, hi);
;     finishSM9(pA0, pA1, alA, l_reg, p8);
;     pv8(o, Vt_lds, p8, r32, hi); partialSM9(pB0, pB1, m_reg, alB, thr_raw);
;     __syncthreads(); SWRITE(0);
;     RESC(alB); __syncthreads();
;     if (j + 2 < NT) SLOAD();
;     qkt9(pA0, pA1, Kn_lds, Kr_lds, qf, 7.0f - m_reg, r32, hi);
;     finishSM9(pB0, pB1, alB, l_reg, p8);
;     pv8(o, Vt_lds + 8192, p8, r32, hi); partialSM9(pA0, pA1, m_reg, alA, thr_raw);
;     __syncthreads(); if (j + 2 < NT) SWRITE(1);
;     RESC(alA); __syncthreads();
.Lmla_s0_cont:
	ds_read_b128 v[82:85], v215 offset:51200
	ds_read_b128 v[86:89], v216 offset:51200
	ds_read_b128 v[222:225], v215 offset:55296
	ds_read_b128 v[226:229], v216 offset:55296
	v_exp_f32_e32 v0, v114
	v_exp_f32_e32 v177, v115
	v_exp_f32_e32 v179, v116
	v_exp_f32_e32 v254, v117
	v_add_f32_e32 v219, v0, v177
	v_cvt_pk_fp8_f32 v246, v0, v177
	v_add_f32_e32 v219, v179, v219
	v_add_f32_e32 v219, v254, v219
	v_cvt_pk_fp8_f32 v246, v179, v254 op_sel:[0,0,1]
	s_waitcnt lgkmcnt(2)
	v_mfma_scale_f32_32x32x64_f8f6f4 v[82:97], v[82:89], v[146:153], v[230:245], v194, v193 op_sel_hi:[0,0,0]
	v_exp_f32_e32 v0, v118
	v_exp_f32_e32 v177, v119
	v_exp_f32_e32 v179, v120
	v_exp_f32_e32 v254, v121
	v_add_f32_e32 v219, v0, v219
	v_add_f32_e32 v219, v177, v219
	v_cvt_pk_fp8_f32 v247, v0, v177
	v_add_f32_e32 v219, v179, v219
	v_add_f32_e32 v219, v254, v219
	v_cvt_pk_fp8_f32 v247, v179, v254 op_sel:[0,0,1]
	ds_read_b128 v[114:117], v213 offset:51200
	ds_read_b128 v[118:121], v214 offset:51200
	s_waitcnt lgkmcnt(2)
	v_mfma_scale_f32_32x32x64_f8f6f4 v[66:81], v[222:229], v[146:153], v[230:245], v194, v193 op_sel_hi:[0,0,0]
	ds_read_b128 v[222:225], v213 offset:55296
	ds_read_b128 v[226:229], v214 offset:55296
	v_exp_f32_e32 v0, v122
	v_exp_f32_e32 v177, v123
	v_exp_f32_e32 v179, v124
	v_exp_f32_e32 v254, v125
	v_add_f32_e32 v219, v0, v219
	v_add_f32_e32 v219, v177, v219
	v_cvt_pk_fp8_f32 v248, v0, v177
	v_add_f32_e32 v219, v179, v219
	v_add_f32_e32 v219, v254, v219
	v_cvt_pk_fp8_f32 v248, v179, v254 op_sel:[0,0,1]
	v_exp_f32_e32 v0, v126
	v_exp_f32_e32 v177, v127
	v_exp_f32_e32 v179, v128
	v_exp_f32_e32 v254, v129
	v_add_f32_e32 v219, v0, v219
	v_add_f32_e32 v219, v177, v219
	v_cvt_pk_fp8_f32 v249, v0, v177
	v_add_f32_e32 v219, v179, v219
	v_add_f32_e32 v219, v254, v219
	v_cvt_pk_fp8_f32 v249, v179, v254 op_sel:[0,0,1]
	ds_read_b128 v[122:125], v185 offset:59392
	ds_read_b128 v[126:129], v186 offset:59392
	s_waitcnt lgkmcnt(4)
	v_mfma_scale_f32_32x32x64_f8f6f4 v[82:97], v[114:121], v[138:145], v[82:97], v194, v193 op_sel_hi:[0,0,0]
	v_exp_f32_e32 v0, v98
	v_exp_f32_e32 v177, v99
	v_exp_f32_e32 v179, v100
	v_exp_f32_e32 v254, v101
	v_add_f32_e32 v219, v0, v219
	v_add_f32_e32 v219, v177, v219
	v_cvt_pk_fp8_f32 v250, v0, v177
	v_add_f32_e32 v219, v179, v219
	v_add_f32_e32 v219, v254, v219
	v_cvt_pk_fp8_f32 v250, v179, v254 op_sel:[0,0,1]
	s_waitcnt lgkmcnt(2)
	v_mfma_scale_f32_32x32x64_f8f6f4 v[66:81], v[222:229], v[138:145], v[66:81], v194, v193 op_sel_hi:[0,0,0]
	ds_read_b128 v[222:225], v185 offset:61440
	ds_read_b128 v[226:229], v186 offset:61440
	v_exp_f32_e32 v0, v102
	v_exp_f32_e32 v177, v103
	v_exp_f32_e32 v179, v104
	v_exp_f32_e32 v254, v105
	v_add_f32_e32 v219, v0, v219
	v_add_f32_e32 v219, v177, v219
	v_cvt_pk_fp8_f32 v251, v0, v177
	v_add_f32_e32 v219, v179, v219
	v_add_f32_e32 v219, v254, v219
	v_cvt_pk_fp8_f32 v251, v179, v254 op_sel:[0,0,1]
	v_exp_f32_e32 v0, v106
	v_exp_f32_e32 v177, v107
	v_exp_f32_e32 v179, v108
	v_exp_f32_e32 v254, v109
	v_add_f32_e32 v219, v0, v219
	v_add_f32_e32 v219, v177, v219
	v_cvt_pk_fp8_f32 v252, v0, v177
	v_add_f32_e32 v219, v179, v219
	v_add_f32_e32 v219, v254, v219
	v_cvt_pk_fp8_f32 v252, v179, v254 op_sel:[0,0,1]
	s_waitcnt lgkmcnt(2)
	v_mfma_scale_f32_32x32x64_f8f6f4 v[82:97], v[122:129], v[130:137], v[82:97], v194, v193 op_sel_hi:[0,0,0]
	v_exp_f32_e32 v0, v110
	v_exp_f32_e32 v177, v111
	v_exp_f32_e32 v179, v112
	v_exp_f32_e32 v254, v113
	v_add_f32_e32 v219, v0, v219
	v_add_f32_e32 v219, v177, v219
	v_cvt_pk_fp8_f32 v253, v0, v177
	v_add_f32_e32 v219, v179, v219
	v_add_f32_e32 v219, v254, v219
	v_cvt_pk_fp8_f32 v253, v179, v254 op_sel:[0,0,1]
	ds_read_b128 v[122:125], v185 offset:8192
	ds_read_b128 v[126:129], v186 offset:8192
	ds_read_b128 v[114:117], v185 offset:10240
	ds_read_b128 v[118:121], v186 offset:10240
	ds_read_b128 v[106:109], v185 offset:12288
	ds_read_b128 v[110:113], v186 offset:12288
	ds_read_b128 v[98:101], v185 offset:14336
	ds_read_b128 v[102:105], v186 offset:14336
	s_waitcnt lgkmcnt(8)
	v_mfma_scale_f32_32x32x64_f8f6f4 v[66:81], v[222:229], v[130:137], v[66:81], v194, v193 op_sel_hi:[0,0,0]
	v_mov_b32_e32 v0, v219
	s_nop 1
	v_permlane32_swap_b32_e32 v219, v0
	v_add_f32_e32 v219, v219, v0
	v_fma_f32 v209, v209, v221, v219
	s_waitcnt vmcnt(0)
	ds_write_b128 v210, v[158:161]
	ds_write_b128 v211, v[162:165] offset:16384
	s_waitcnt lgkmcnt(0)
	s_barrier
	global_load_dwordx4 v[158:161], v176, s[18:19]
	global_load_dwordx4 v[162:165], v178, s[16:17]
	v_max_f32_e32 v177, v82, v83
	v_max3_f32 v177, v177, v84, v85
	v_max3_f32 v177, v177, v86, v87
	v_max3_f32 v177, v177, v88, v89
	v_max3_f32 v177, v177, v90, v91
	v_max3_f32 v177, v177, v92, v93
	v_max3_f32 v177, v177, v94, v95
	v_max3_f32 v177, v177, v96, v97
	v_add_u32_e32 v176, 0x2000, v176
	v_add_u32_e32 v178, 0x20000, v178
	v_mfma_scale_f32_32x32x64_f8f6f4 v[50:65], v[246:253], v[122:129], v[50:65], v194, v194 op_sel_hi:[0,0,0]
	v_mfma_scale_f32_32x32x64_f8f6f4 v[34:49], v[246:253], v[114:121], v[34:49], v194, v194 op_sel_hi:[0,0,0]
	v_mfma_scale_f32_32x32x64_f8f6f4 v[18:33], v[246:253], v[106:113], v[18:33], v194, v194 op_sel_hi:[0,0,0]
	v_mfma_scale_f32_32x32x64_f8f6f4 v[2:17], v[246:253], v[98:105], v[2:17], v194, v194 op_sel_hi:[0,0,0]
	v_max_f32_e32 v0, v66, v67
	v_max3_f32 v0, v0, v68, v69
	v_max3_f32 v0, v0, v70, v71
	v_max3_f32 v0, v0, v72, v73
	v_max3_f32 v0, v0, v74, v75
	v_max3_f32 v0, v0, v76, v77
	v_max3_f32 v0, v0, v78, v79
	v_max3_f32 v0, v0, v80, v81
	v_max_f32_e32 v177, v177, v0
	v_mov_b32_e32 v0, v177
	v_mov_b32_e32 v218, 1.0
	s_nop 0
	v_permlane32_swap_b32_e32 v177, v0
	v_max_f32_e32 v177, v177, v0
	v_cmp_ge_f32_e32 vcc, s90, v177
	s_cmp_eq_u64 vcc, exec
	s_cbranch_scc0 .Lmla_s1_newmax
; #define SLOAD() do { vs0 = *(const bf16x8*)(Vh + voff); vs1 = *(const bf16x8*)(Vh + voff + 32u * (unsigned)ldv); \
;     ks0 = *(const bf16x8*)(Kh + koff); ks1 = *(const bf16x8*)(Kh + koff + 32u * (unsigned)ldk); \
;     if constexpr (NR > 0) { kr = *(const bf16x8*)(Krh + kroff); kroff += 64u * 64u; } voff += 64u * (unsigned)ldv; koff += 64u * (unsigned)ldk; } while (0)
; #define SWRITE(b) do { *(bf16x8*)(V_lds + (b) * SHM_V + vst0) = vs0; *(bf16x8*)(V_lds + (b) * SHM_V + vst1) = vs1; const int kc = sc * 2;  \
;     *(bf16x8*)(K_lds + (b) * SHM_K + KSWZ(sr, kc)) = ks0; *(bf16x8*)(K_lds + (b) * SHM_K + KSWZ(32 + sr, kc)) = ks1; \
;     if constexpr (NR > 0) *(bf16x8*)(Kr_lds + (b) * SHM_KR + krst) = kr; } while (0)
; #define SLOAD() do { vs0 = *(const bf16x8*)(Vh + voff); vs1 = *(const bf16x8*)(Vh + voff + 32u * (unsigned)ldv); \
;     ks0 = *(const bf16x8*)(Kh + voff); ks1 = *(const bf16x8*)(Kh + voff + 32u * (unsigned)ldv); \
;     if constexpr (NR > 0) { kr = *(const bf16x8*)(Krh + kroff); kroff += 64u * 64u; } voff += 64u * (unsigned)ldv; } while (0)
; #define SWRITE(b) do { *(bf16x8*)(V_lds + (b) * SHM_V + vst0) = vs0; *(bf16x8*)(V_lds + (b) * SHM_V + vst0 + 8192) = vs1;  \
;     *(bf16x8*)(K_lds + (b) * SHM_K + kst0) = ks0; *(bf16x8*)(K_lds + (b) * SHM_K + kst0 + 8192) = ks1; \
;     if constexpr (NR > 0) *(bf16x8*)(Kr_lds + (b) * SHM_KR + krst) = kr; } while (0)
; #define SWRITE(b) do { *(v4i32*)(Vt_lds + (b) * 8192 + vtst) = vt; *(v4i32*)(Kn_lds + (b) * 8192 + knst) = kn; if (krw) *(v4i32*)(Kr_lds + (b) * 4096 + krst) = kr; } while (0)
; __device__ __forceinline__ void attn_unit7(const unsigned char* __restrict__ Q8, int ldq, const unsigned char* __restrict__ Kn8, int ldk, const unsigned char* __restrict__ Kr8, ...
;     ...
;   for (int j = 1; j + 1 < NT; j += 2) {
;     SLOAD();
;     qkt9(pB0, pB1, Kn_lds + 8192, Kr_lds + 4096, qf, 7.0f - m_reg, r32, hi);
;     finishSM9(pA0, pA1, alA, l_reg, p8);
;     pv8(o, Vt_lds, p8, r32, hi); partialSM9(pB0, pB1, m_reg, alB, thr_raw);
;     __syncthreads(); SWRITE(0);
;     RESC(alB); __syncthreads();
;     if (j + 2 < NT) SLOAD();
;     qkt9(pA0, pA1, Kn_lds, Kr_lds, qf, 7.0f - m_reg, r32, hi);
;     finishSM9(pB0, pB1, alB, l_reg, p8);
;     pv8(o, Vt_lds + 8192, p8, r32, hi); partialSM9(pA0, pA1, m_reg, alA, thr_raw);
;     __syncthreads(); if (j + 2 < NT) SWRITE(1);
;     RESC(alA); __syncthreads();
.Lmla_s1_cont:
	ds_read_b128 v[114:117], v215 offset:16384
	ds_read_b128 v[118:121], v216 offset:16384
	ds_read_b128 v[222:225], v215 offset:20480
	ds_read_b128 v[226:229], v216 offset:20480
	v_exp_f32_e32 v0, v82
	v_exp_f32_e32 v177, v83
	v_exp_f32_e32 v179, v84
	v_exp_f32_e32 v254, v85
	v_add_f32_e32 v219, v0, v177
	v_cvt_pk_fp8_f32 v246, v0, v177
	v_add_f32_e32 v219, v179, v219
	v_add_f32_e32 v219, v254, v219
	v_cvt_pk_fp8_f32 v246, v179, v254 op_sel:[0,0,1]
	s_waitcnt lgkmcnt(2)
	v_mfma_scale_f32_32x32x64_f8f6f4 v[114:129], v[114:121], v[146:153], v[230:245], v194, v193 op_sel_hi:[0,0,0]
	v_exp_f32_e32 v0, v86
	v_exp_f32_e32 v177, v87
	v_exp_f32_e32 v179, v88
	v_exp_f32_e32 v254, v89
	v_add_f32_e32 v219, v0, v219
	v_add_f32_e32 v219, v177, v219
	v_cvt_pk_fp8_f32 v247, v0, v177
	v_add_f32_e32 v219, v179, v219
	v_add_f32_e32 v219, v254, v219
	v_cvt_pk_fp8_f32 v247, v179, v254 op_sel:[0,0,1]
	ds_read_b128 v[82:85], v213 offset:16384
	ds_read_b128 v[86:89], v214 offset:16384
	s_waitcnt lgkmcnt(2)
	v_mfma_scale_f32_32x32x64_f8f6f4 v[98:113], v[222:229], v[146:153], v[230:245], v194, v193 op_sel_hi:[0,0,0]
	ds_read_b128 v[222:225], v213 offset:20480
	ds_read_b128 v[226:229], v214 offset:20480
	v_exp_f32_e32 v0, v90
	v_exp_f32_e32 v177, v91
	v_exp_f32_e32 v179, v92
	v_exp_f32_e32 v254, v93
	v_add_f32_e32 v219, v0, v219
	v_add_f32_e32 v219, v177, v219
	v_cvt_pk_fp8_f32 v248, v0, v177
	v_add_f32_e32 v219, v179, v219
	v_add_f32_e32 v219, v254, v219
	v_cvt_pk_fp8_f32 v248, v179, v254 op_sel:[0,0,1]
	v_exp_f32_e32 v0, v94
	v_exp_f32_e32 v177, v95
	v_exp_f32_e32 v179, v96
	v_exp_f32_e32 v254, v97
	v_add_f32_e32 v219, v0, v219
	v_add_f32_e32 v219, v177, v219
	v_cvt_pk_fp8_f32 v249, v0, v177
	v_add_f32_e32 v219, v179, v219
	v_add_f32_e32 v219, v254, v219
	v_cvt_pk_fp8_f32 v249, v179, v254 op_sel:[0,0,1]
	ds_read_b128 v[90:93], v185 offset:32768
	ds_read_b128 v[94:97], v186 offset:32768
	s_waitcnt lgkmcnt(4)
	v_mfma_scale_f32_32x32x64_f8f6f4 v[114:129], v[82:89], v[138:145], v[114:129], v194, v193 op_sel_hi:[0,0,0]
	v_exp_f32_e32 v0, v66
	v_exp_f32_e32 v177, v67
	v_exp_f32_e32 v179, v68
	v_exp_f32_e32 v254, v69
	v_add_f32_e32 v219, v0, v219
	v_add_f32_e32 v219, v177, v219
	v_cvt_pk_fp8_f32 v250, v0, v177
	v_add_f32_e32 v219, v179, v219
	v_add_f32_e32 v219, v254, v219
	v_cvt_pk_fp8_f32 v250, v179, v254 op_sel:[0,0,1]
	s_waitcnt lgkmcnt(2)
	v_mfma_scale_f32_32x32x64_f8f6f4 v[98:113], v[222:229], v[138:145], v[98:113], v194, v193 op_sel_hi:[0,0,0]
	ds_read_b128 v[222:225], v185 offset:34816
	ds_read_b128 v[226:229], v186 offset:34816
	v_exp_f32_e32 v0, v70
	v_exp_f32_e32 v177, v71
	v_exp_f32_e32 v179, v72
	v_exp_f32_e32 v254, v73
	v_add_f32_e32 v219, v0, v219
	v_add_f32_e32 v219, v177, v219
	v_cvt_pk_fp8_f32 v251, v0, v177
	v_add_f32_e32 v219, v179, v219
	v_add_f32_e32 v219, v254, v219
	v_cvt_pk_fp8_f32 v251, v179, v254 op_sel:[0,0,1]
	v_exp_f32_e32 v0, v74
	v_exp_f32_e32 v177, v75
	v_exp_f32_e32 v179, v76
	v_exp_f32_e32 v254, v77
	v_add_f32_e32 v219, v0, v219
	v_add_f32_e32 v219, v177, v219
	v_cvt_pk_fp8_f32 v252, v0, v177
	v_add_f32_e32 v219, v179, v219
	v_add_f32_e32 v219, v254, v219
	v_cvt_pk_fp8_f32 v252, v179, v254 op_sel:[0,0,1]
	s_waitcnt lgkmcnt(2)
	v_mfma_scale_f32_32x32x64_f8f6f4 v[114:129], v[90:97], v[130:137], v[114:129], v194, v193 op_sel_hi:[0,0,0]
	v_exp_f32_e32 v0, v78
	v_exp_f32_e32 v177, v79
	v_exp_f32_e32 v179, v80
	v_exp_f32_e32 v254, v81
	v_add_f32_e32 v219, v0, v219
	v_add_f32_e32 v219, v177, v219
	v_cvt_pk_fp8_f32 v253, v0, v177
	v_add_f32_e32 v219, v179, v219
	v_add_f32_e32 v219, v254, v219
	v_cvt_pk_fp8_f32 v253, v179, v254 op_sel:[0,0,1]
	ds_read_b128 v[90:93], v185 offset:43008
	ds_read_b128 v[94:97], v186 offset:43008
	ds_read_b128 v[82:85], v185 offset:45056
	ds_read_b128 v[86:89], v186 offset:45056
	ds_read_b128 v[74:77], v185 offset:47104
	ds_read_b128 v[78:81], v186 offset:47104
	ds_read_b128 v[66:69], v185 offset:49152
	ds_read_b128 v[70:73], v186 offset:49152
	s_waitcnt lgkmcnt(8)
	v_mfma_scale_f32_32x32x64_f8f6f4 v[98:113], v[222:229], v[130:137], v[98:113], v194, v193 op_sel_hi:[0,0,0]
	v_mov_b32_e32 v0, v219
	s_nop 1
	v_permlane32_swap_b32_e32 v219, v0
	v_add_f32_e32 v219, v219, v0
	v_fma_f32 v209, v209, v218, v219
	s_waitcnt vmcnt(0)
	ds_write_b128 v210, v[158:161] offset:8192
	ds_write_b128 v211, v[162:165] offset:24576
	s_waitcnt lgkmcnt(0)
	s_barrier
	global_load_dwordx4 v[158:161], v176, s[18:19]
	global_load_dwordx4 v[162:165], v178, s[16:17]
	v_max_f32_e32 v177, v114, v115
	v_max3_f32 v177, v177, v116, v117
	v_max3_f32 v177, v177, v118, v119
	v_max3_f32 v177, v177, v120, v121
	v_max3_f32 v177, v177, v122, v123
	v_max3_f32 v177, v177, v124, v125
	v_max3_f32 v177, v177, v126, v127
	v_max3_f32 v177, v177, v128, v129
	v_add_u32_e32 v176, 0x2000, v176
	v_add_u32_e32 v178, 0x20000, v178
	v_mfma_scale_f32_32x32x64_f8f6f4 v[50:65], v[246:253], v[90:97], v[50:65], v194, v194 op_sel_hi:[0,0,0]
	v_mfma_scale_f32_32x32x64_f8f6f4 v[34:49], v[246:253], v[82:89], v[34:49], v194, v194 op_sel_hi:[0,0,0]
	v_mfma_scale_f32_32x32x64_f8f6f4 v[18:33], v[246:253], v[74:81], v[18:33], v194, v194 op_sel_hi:[0,0,0]
	v_mfma_scale_f32_32x32x64_f8f6f4 v[2:17], v[246:253], v[66:73], v[2:17], v194, v194 op_sel_hi:[0,0,0]
	v_max_f32_e32 v0, v98, v99
	v_max3_f32 v0, v0, v100, v101
	v_max3_f32 v0, v0, v102, v103
	v_max3_f32 v0, v0, v104, v105
	v_max3_f32 v0, v0, v106, v107
	v_max3_f32 v0, v0, v108, v109
	v_max3_f32 v0, v0, v110, v111
	v_max3_f32 v0, v0, v112, v113
	v_max_f32_e32 v177, v177, v0
	v_mov_b32_e32 v0, v177
	v_mov_b32_e32 v221, 1.0
	s_nop 0
	v_permlane32_swap_b32_e32 v177, v0
	v_max_f32_e32 v177, v177, v0
	v_cmp_ge_f32_e32 vcc, s90, v177
	s_cmp_eq_u64 vcc, exec
	s_cbranch_scc0 .Lmla_s2_newmax
; #define SLOAD() do { vs0 = *(const bf16x8*)(Vh + voff); vs1 = *(const bf16x8*)(Vh + voff + 32u * (unsigned)ldv); \
;     ks0 = *(const bf16x8*)(Kh + koff); ks1 = *(const bf16x8*)(Kh + koff + 32u * (unsigned)ldk); \
;     if constexpr (NR > 0) { kr = *(const bf16x8*)(Krh + kroff); kroff += 64u * 64u; } voff += 64u * (unsigned)ldv; koff += 64u * (unsigned)ldk; } while (0)
; #define SWRITE(b) do { *(bf16x8*)(V_lds + (b) * SHM_V + vst0) = vs0; *(bf16x8*)(V_lds + (b) * SHM_V + vst1) = vs1; const int kc = sc * 2;  \
;     *(bf16x8*)(K_lds + (b) * SHM_K + KSWZ(sr, kc)) = ks0; *(bf16x8*)(K_lds + (b) * SHM_K + KSWZ(32 + sr, kc)) = ks1; \
;     if constexpr (NR > 0) *(bf16x8*)(Kr_lds + (b) * SHM_KR + krst) = kr; } while (0)
; #define SLOAD() do { vs0 = *(const bf16x8*)(Vh + voff); vs1 = *(const bf16x8*)(Vh + voff + 32u * (unsigned)ldv); \
;     ks0 = *(const bf16x8*)(Kh + voff); ks1 = *(const bf16x8*)(Kh + voff + 32u * (unsigned)ldv); \
;     if constexpr (NR > 0) { kr = *(const bf16x8*)(Krh + kroff); kroff += 64u * 64u; } voff += 64u * (unsigned)ldv; } while (0)
; #define SWRITE(b) do { *(bf16x8*)(V_lds + (b) * SHM_V + vst0) = vs0; *(bf16x8*)(V_lds + (b) * SHM_V + vst0 + 8192) = vs1;  \
;     *(bf16x8*)(K_lds + (b) * SHM_K + kst0) = ks0; *(bf16x8*)(K_lds + (b) * SHM_K + kst0 + 8192) = ks1; \
;     if constexpr (NR > 0) *(bf16x8*)(Kr_lds + (b) * SHM_KR + krst) = kr; } while (0)
; #define SWRITE(b) do { *(v4i32*)(Vt_lds + (b) * 8192 + vtst) = vt; *(v4i32*)(Kn_lds + (b) * 8192 + knst) = kn; if (krw) *(v4i32*)(Kr_lds + (b) * 4096 + krst) = kr; } while (0)
; __device__ __forceinline__ void attn_unit7(const unsigned char* __restrict__ Q8, int ldq, const unsigned char* __restrict__ Kn8, int ldk, const unsigned char* __restrict__ Kr8, ...
;     ...
;   for (int j = 1; j + 1 < NT; j += 2) {
;     SLOAD();
;     qkt9(pB0, pB1, Kn_lds + 8192, Kr_lds + 4096, qf, 7.0f - m_reg, r32, hi);
;     finishSM9(pA0, pA1, alA, l_reg, p8);
;     pv8(o, Vt_lds, p8, r32, hi); partialSM9(pB0, pB1, m_reg, alB, thr_raw);
;     __syncthreads(); SWRITE(0);
;     RESC(alB); __syncthreads();
;     if (j + 2 < NT) SLOAD();
;     qkt9(pA0, pA1, Kn_lds, Kr_lds, qf, 7.0f - m_reg, r32, hi);
;     finishSM9(pB0, pB1, alB, l_reg, p8);
;     pv8(o, Vt_lds + 8192, p8, r32, hi); partialSM9(pA0, pA1, m_reg, alA, thr_raw);
;     __syncthreads(); if (j + 2 < NT) SWRITE(1);
;     RESC(alA); __syncthreads();
.Lmla_s2_cont:
	ds_read_b128 v[82:85], v215 offset:24576
	ds_read_b128 v[86:89], v216 offset:24576
	ds_read_b128 v[222:225], v215 offset:28672
	ds_read_b128 v[226:229], v216 offset:28672
	v_exp_f32_e32 v0, v114
	v_exp_f32_e32 v177, v115
	v_exp_f32_e32 v179, v116
	v_exp_f32_e32 v254, v117
	v_add_f32_e32 v219, v0, v177
	v_cvt_pk_fp8_f32 v246, v0, v177
	v_add_f32_e32 v219, v179, v219
	v_add_f32_e32 v219, v254, v219
	v_cvt_pk_fp8_f32 v246, v179, v254 op_sel:[0,0,1]
	s_waitcnt lgkmcnt(2)
	v_mfma_scale_f32_32x32x64_f8f6f4 v[82:97], v[82:89], v[146:153], v[230:245], v194, v193 op_sel_hi:[0,0,0]
	v_exp_f32_e32 v0, v118
	v_exp_f32_e32 v177, v119
	v_exp_f32_e32 v179, v120
	v_exp_f32_e32 v254, v121
	v_add_f32_e32 v219, v0, v219
	v_add_f32_e32 v219, v177, v219
	v_cvt_pk_fp8_f32 v247, v0, v177
	v_add_f32_e32 v219, v179, v219
	v_add_f32_e32 v219, v254, v219
	v_cvt_pk_fp8_f32 v247, v179, v254 op_sel:[0,0,1]
	ds_read_b128 v[114:117], v213 offset:24576
	ds_read_b128 v[118:121], v214 offset:24576
	s_waitcnt lgkmcnt(2)
	v_mfma_scale_f32_32x32x64_f8f6f4 v[66:81], v[222:229], v[146:153], v[230:245], v194, v193 op_sel_hi:[0,0,0]
	ds_read_b128 v[222:225], v213 offset:28672
	ds_read_b128 v[226:229], v214 offset:28672
	v_exp_f32_e32 v0, v122
	v_exp_f32_e32 v177, v123
	v_exp_f32_e32 v179, v124
	v_exp_f32_e32 v254, v125
	v_add_f32_e32 v219, v0, v219
	v_add_f32_e32 v219, v177, v219
	v_cvt_pk_fp8_f32 v248, v0, v177
	v_add_f32_e32 v219, v179, v219
	v_add_f32_e32 v219, v254, v219
	v_cvt_pk_fp8_f32 v248, v179, v254 op_sel:[0,0,1]
	v_exp_f32_e32 v0, v126
	v_exp_f32_e32 v177, v127
	v_exp_f32_e32 v179, v128
	v_exp_f32_e32 v254, v129
	v_add_f32_e32 v219, v0, v219
	v_add_f32_e32 v219, v177, v219
	v_cvt_pk_fp8_f32 v249, v0, v177
	v_add_f32_e32 v219, v179, v219
	v_add_f32_e32 v219, v254, v219
	v_cvt_pk_fp8_f32 v249, v179, v254 op_sel:[0,0,1]
	ds_read_b128 v[122:125], v185 offset:36864
	ds_read_b128 v[126:129], v186 offset:36864
	s_waitcnt lgkmcnt(4)
	v_mfma_scale_f32_32x32x64_f8f6f4 v[82:97], v[114:121], v[138:145], v[82:97], v194, v193 op_sel_hi:[0,0,0]
	v_exp_f32_e32 v0, v98
	v_exp_f32_e32 v177, v99
	v_exp_f32_e32 v179, v100
	v_exp_f32_e32 v254, v101
	v_add_f32_e32 v219, v0, v219
	v_add_f32_e32 v219, v177, v219
	v_cvt_pk_fp8_f32 v250, v0, v177
	v_add_f32_e32 v219, v179, v219
	v_add_f32_e32 v219, v254, v219
	v_cvt_pk_fp8_f32 v250, v179, v254 op_sel:[0,0,1]
	s_waitcnt lgkmcnt(2)
	v_mfma_scale_f32_32x32x64_f8f6f4 v[66:81], v[222:229], v[138:145], v[66:81], v194, v193 op_sel_hi:[0,0,0]
	ds_read_b128 v[222:225], v185 offset:38912
	ds_read_b128 v[226:229], v186 offset:38912
	v_exp_f32_e32 v0, v102
	v_exp_f32_e32 v177, v103
	v_exp_f32_e32 v179, v104
	v_exp_f32_e32 v254, v105
	v_add_f32_e32 v219, v0, v219
	v_add_f32_e32 v219, v177, v219
	v_cvt_pk_fp8_f32 v251, v0, v177
	v_add_f32_e32 v219, v179, v219
	v_add_f32_e32 v219, v254, v219
	v_cvt_pk_fp8_f32 v251, v179, v254 op_sel:[0,0,1]
	v_exp_f32_e32 v0, v106
	v_exp_f32_e32 v177, v107
	v_exp_f32_e32 v179, v108
	v_exp_f32_e32 v254, v109
	v_add_f32_e32 v219, v0, v219
	v_add_f32_e32 v219, v177, v219
	v_cvt_pk_fp8_f32 v252, v0, v177
	v_add_f32_e32 v219, v179, v219
	v_add_f32_e32 v219, v254, v219
	v_cvt_pk_fp8_f32 v252, v179, v254 op_sel:[0,0,1]
	s_waitcnt lgkmcnt(2)
	v_mfma_scale_f32_32x32x64_f8f6f4 v[82:97], v[122:129], v[130:137], v[82:97], v194, v193 op_sel_hi:[0,0,0]
	v_exp_f32_e32 v0, v110
	v_exp_f32_e32 v177, v111
	v_exp_f32_e32 v179, v112
	v_exp_f32_e32 v254, v113
	v_add_f32_e32 v219, v0, v219
	v_add_f32_e32 v219, v177, v219
	v_cvt_pk_fp8_f32 v253, v0, v177
	v_add_f32_e32 v219, v179, v219
	v_add_f32_e32 v219, v254, v219
	v_cvt_pk_fp8_f32 v253, v179, v254 op_sel:[0,0,1]
	ds_read_b128 v[122:125], v185 offset:0
	ds_read_b128 v[126:129], v186 offset:0
	ds_read_b128 v[114:117], v185 offset:2048
	ds_read_b128 v[118:121], v186 offset:2048
	ds_read_b128 v[106:109], v185 offset:4096
	ds_read_b128 v[110:113], v186 offset:4096
	ds_read_b128 v[98:101], v185 offset:6144
	ds_read_b128 v[102:105], v186 offset:6144
	s_waitcnt lgkmcnt(8)
	v_mfma_scale_f32_32x32x64_f8f6f4 v[66:81], v[222:229], v[130:137], v[66:81], v194, v193 op_sel_hi:[0,0,0]
	v_mov_b32_e32 v0, v219
	s_nop 1
	v_permlane32_swap_b32_e32 v219, v0
	v_add_f32_e32 v219, v219, v0
	v_fma_f32 v209, v209, v221, v219
	s_waitcnt vmcnt(0)
	ds_write_b128 v210, v[158:161] offset:43008
	ds_write_b128 v211, v[162:165] offset:51200
	s_waitcnt lgkmcnt(0)
	s_barrier
	global_load_dwordx4 v[158:161], v176, s[18:19]
	global_load_dwordx4 v[162:165], v178, s[16:17]
	v_max_f32_e32 v177, v82, v83
	v_max3_f32 v177, v177, v84, v85
	v_max3_f32 v177, v177, v86, v87
	v_max3_f32 v177, v177, v88, v89
	v_max3_f32 v177, v177, v90, v91
	v_max3_f32 v177, v177, v92, v93
	v_max3_f32 v177, v177, v94, v95
	v_max3_f32 v177, v177, v96, v97
	v_add_u32_e32 v176, 0x2000, v176
	v_add_u32_e32 v178, 0x20000, v178
	v_mfma_scale_f32_32x32x64_f8f6f4 v[50:65], v[246:253], v[122:129], v[50:65], v194, v194 op_sel_hi:[0,0,0]
	v_mfma_scale_f32_32x32x64_f8f6f4 v[34:49], v[246:253], v[114:121], v[34:49], v194, v194 op_sel_hi:[0,0,0]
	v_mfma_scale_f32_32x32x64_f8f6f4 v[18:33], v[246:253], v[106:113], v[18:33], v194, v194 op_sel_hi:[0,0,0]
	v_mfma_scale_f32_32x32x64_f8f6f4 v[2:17], v[246:253], v[98:105], v[2:17], v194, v194 op_sel_hi:[0,0,0]
	v_max_f32_e32 v0, v66, v67
	v_max3_f32 v0, v0, v68, v69
	v_max3_f32 v0, v0, v70, v71
	v_max3_f32 v0, v0, v72, v73
	v_max3_f32 v0, v0, v74, v75
	v_max3_f32 v0, v0, v76, v77
	v_max3_f32 v0, v0, v78, v79
	v_max3_f32 v0, v0, v80, v81
	v_max_f32_e32 v177, v177, v0
	v_mov_b32_e32 v0, v177
	v_mov_b32_e32 v218, 1.0
	s_nop 0
	v_permlane32_swap_b32_e32 v177, v0
	v_max_f32_e32 v177, v177, v0
	v_cmp_ge_f32_e32 vcc, s90, v177
	s_cmp_eq_u64 vcc, exec
	s_cbranch_scc0 .Lmla_s3_newmax
; #define SLOAD() do { vs0 = *(const bf16x8*)(Vh + voff); vs1 = *(const bf16x8*)(Vh + voff + 32u * (unsigned)ldv); \
;     ks0 = *(const bf16x8*)(Kh + koff); ks1 = *(const bf16x8*)(Kh + koff + 32u * (unsigned)ldk); \
;     if constexpr (NR > 0) { kr = *(const bf16x8*)(Krh + kroff); kroff += 64u * 64u; } voff += 64u * (unsigned)ldv; koff += 64u * (unsigned)ldk; } while (0)
; #define SWRITE(b) do { *(bf16x8*)(V_lds + (b) * SHM_V + vst0) = vs0; *(bf16x8*)(V_lds + (b) * SHM_V + vst1) = vs1; const int kc = sc * 2;  \
;     *(bf16x8*)(K_lds + (b) * SHM_K + KSWZ(sr, kc)) = ks0; *(bf16x8*)(K_lds + (b) * SHM_K + KSWZ(32 + sr, kc)) = ks1; \
;     if constexpr (NR > 0) *(bf16x8*)(Kr_lds + (b) * SHM_KR + krst) = kr; } while (0)
; #define SLOAD() do { vs0 = *(const bf16x8*)(Vh + voff); vs1 = *(const bf16x8*)(Vh + voff + 32u * (unsigned)ldv); \
;     ks0 = *(const bf16x8*)(Kh + voff); ks1 = *(const bf16x8*)(Kh + voff + 32u * (unsigned)ldv); \
;     if constexpr (NR > 0) { kr = *(const bf16x8*)(Krh + kroff); kroff += 64u * 64u; } voff += 64u * (unsigned)ldv; } while (0)
; #define SWRITE(b) do { *(bf16x8*)(V_lds + (b) * SHM_V + vst0) = vs0; *(bf16x8*)(V_lds + (b) * SHM_V + vst0 + 8192) = vs1;  \
;     *(bf16x8*)(K_lds + (b) * SHM_K + kst0) = ks0; *(bf16x8*)(K_lds + (b) * SHM_K + kst0 + 8192) = ks1; \
;     if constexpr (NR > 0) *(bf16x8*)(Kr_lds + (b) * SHM_KR + krst) = kr; } while (0)
; #define SWRITE(b) do { *(v4i32*)(Vt_lds + (b) * 8192 + vtst) = vt; *(v4i32*)(Kn_lds + (b) * 8192 + knst) = kn; if (krw) *(v4i32*)(Kr_lds + (b) * 4096 + krst) = kr; } while (0)
; __device__ __forceinline__ void attn_unit7(const unsigned char* __restrict__ Q8, int ldq, const unsigned char* __restrict__ Kn8, int ldk, const unsigned char* __restrict__ Kr8, ...
;     ...
;   for (int j = 1; j + 1 < NT; j += 2) {
;     SLOAD();
;     qkt9(pB0, pB1, Kn_lds + 8192, Kr_lds + 4096, qf, 7.0f - m_reg, r32, hi);
;     finishSM9(pA0, pA1, alA, l_reg, p8);
;     pv8(o, Vt_lds, p8, r32, hi); partialSM9(pB0, pB1, m_reg, alB, thr_raw);
;     __syncthreads(); SWRITE(0);
;     RESC(alB); __syncthreads();
;     if (j + 2 < NT) SLOAD();
;     qkt9(pA0, pA1, Kn_lds, Kr_lds, qf, 7.0f - m_reg, r32, hi);
;     finishSM9(pB0, pB1, alB, l_reg, p8);
;     pv8(o, Vt_lds + 8192, p8, r32, hi); partialSM9(pA0, pA1, m_reg, alA, thr_raw);
;     __syncthreads(); if (j + 2 < NT) SWRITE(1);
;     RESC(alA); __syncthreads();
.Lmla_s3_cont:
	ds_read_b128 v[114:117], v215 offset:51200
	ds_read_b128 v[118:121], v216 offset:51200
	ds_read_b128 v[222:225], v215 offset:55296
	ds_read_b128 v[226:229], v216 offset:55296
	v_exp_f32_e32 v0, v82
	v_exp_f32_e32 v177, v83
	v_exp_f32_e32 v179, v84
	v_exp_f32_e32 v254, v85
	v_add_f32_e32 v219, v0, v177
	v_cvt_pk_fp8_f32 v246, v0, v177
	v_add_f32_e32 v219, v179, v219
	v_add_f32_e32 v219, v254, v219
	v_cvt_pk_fp8_f32 v246, v179, v254 op_sel:[0,0,1]
	s_waitcnt lgkmcnt(2)
	v_mfma_scale_f32_32x32x64_f8f6f4 v[114:129], v[114:121], v[146:153], v[230:245], v194, v193 op_sel_hi:[0,0,0]
	v_exp_f32_e32 v0, v86
	v_exp_f32_e32 v177, v87
	v_exp_f32_e32 v179, v88
	v_exp_f32_e32 v254, v89
	v_add_f32_e32 v219, v0, v219
	v_add_f32_e32 v219, v177, v219
	v_cvt_pk_fp8_f32 v247, v0, v177
	v_add_f32_e32 v219, v179, v219
	v_add_f32_e32 v219, v254, v219
	v_cvt_pk_fp8_f32 v247, v179, v254 op_sel:[0,0,1]
	ds_read_b128 v[82:85], v213 offset:51200
	ds_read_b128 v[86:89], v214 offset:51200
	s_waitcnt lgkmcnt(2)
	v_mfma_scale_f32_32x32x64_f8f6f4 v[98:113], v[222:229], v[146:153], v[230:245], v194, v193 op_sel_hi:[0,0,0]
	ds_read_b128 v[222:225], v213 offset:55296
	ds_read_b128 v[226:229], v214 offset:55296
	v_exp_f32_e32 v0, v90
	v_exp_f32_e32 v177, v91
	v_exp_f32_e32 v179, v92
	v_exp_f32_e32 v254, v93
	v_add_f32_e32 v219, v0, v219
	v_add_f32_e32 v219, v177, v219
	v_cvt_pk_fp8_f32 v248, v0, v177
	v_add_f32_e32 v219, v179, v219
	v_add_f32_e32 v219, v254, v219
	v_cvt_pk_fp8_f32 v248, v179, v254 op_sel:[0,0,1]
	v_exp_f32_e32 v0, v94
	v_exp_f32_e32 v177, v95
	v_exp_f32_e32 v179, v96
	v_exp_f32_e32 v254, v97
	v_add_f32_e32 v219, v0, v219
	v_add_f32_e32 v219, v177, v219
	v_cvt_pk_fp8_f32 v249, v0, v177
	v_add_f32_e32 v219, v179, v219
	v_add_f32_e32 v219, v254, v219
	v_cvt_pk_fp8_f32 v249, v179, v254 op_sel:[0,0,1]
	ds_read_b128 v[90:93], v185 offset:59392
	ds_read_b128 v[94:97], v186 offset:59392
	s_waitcnt lgkmcnt(4)
	v_mfma_scale_f32_32x32x64_f8f6f4 v[114:129], v[82:89], v[138:145], v[114:129], v194, v193 op_sel_hi:[0,0,0]
	v_exp_f32_e32 v0, v66
	v_exp_f32_e32 v177, v67
	v_exp_f32_e32 v179, v68
	v_exp_f32_e32 v254, v69
	v_add_f32_e32 v219, v0, v219
	v_add_f32_e32 v219, v177, v219
	v_cvt_pk_fp8_f32 v250, v0, v177
	v_add_f32_e32 v219, v179, v219
	v_add_f32_e32 v219, v254, v219
	v_cvt_pk_fp8_f32 v250, v179, v254 op_sel:[0,0,1]
	s_waitcnt lgkmcnt(2)
	v_mfma_scale_f32_32x32x64_f8f6f4 v[98:113], v[222:229], v[138:145], v[98:113], v194, v193 op_sel_hi:[0,0,0]
	ds_read_b128 v[222:225], v185 offset:61440
	ds_read_b128 v[226:229], v186 offset:61440
	v_exp_f32_e32 v0, v70
	v_exp_f32_e32 v177, v71
	v_exp_f32_e32 v179, v72
	v_exp_f32_e32 v254, v73
	v_add_f32_e32 v219, v0, v219
	v_add_f32_e32 v219, v177, v219
	v_cvt_pk_fp8_f32 v251, v0, v177
	v_add_f32_e32 v219, v179, v219
	v_add_f32_e32 v219, v254, v219
	v_cvt_pk_fp8_f32 v251, v179, v254 op_sel:[0,0,1]
	v_exp_f32_e32 v0, v74
	v_exp_f32_e32 v177, v75
	v_exp_f32_e32 v179, v76
	v_exp_f32_e32 v254, v77
	v_add_f32_e32 v219, v0, v219
	v_add_f32_e32 v219, v177, v219
	v_cvt_pk_fp8_f32 v252, v0, v177
	v_add_f32_e32 v219, v179, v219
	v_add_f32_e32 v219, v254, v219
	v_cvt_pk_fp8_f32 v252, v179, v254 op_sel:[0,0,1]
	s_waitcnt lgkmcnt(2)
	v_mfma_scale_f32_32x32x64_f8f6f4 v[114:129], v[90:97], v[130:137], v[114:129], v194, v193 op_sel_hi:[0,0,0]
	v_exp_f32_e32 v0, v78
	v_exp_f32_e32 v177, v79
	v_exp_f32_e32 v179, v80
	v_exp_f32_e32 v254, v81
	v_add_f32_e32 v219, v0, v219
	v_add_f32_e32 v219, v177, v219
	v_cvt_pk_fp8_f32 v253, v0, v177
	v_add_f32_e32 v219, v179, v219
	v_add_f32_e32 v219, v254, v219
	v_cvt_pk_fp8_f32 v253, v179, v254 op_sel:[0,0,1]
	ds_read_b128 v[90:93], v185 offset:8192
	ds_read_b128 v[94:97], v186 offset:8192
	ds_read_b128 v[82:85], v185 offset:10240
	ds_read_b128 v[86:89], v186 offset:10240
	ds_read_b128 v[74:77], v185 offset:12288
	ds_read_b128 v[78:81], v186 offset:12288
	ds_read_b128 v[66:69], v185 offset:14336
	ds_read_b128 v[70:73], v186 offset:14336
	s_waitcnt lgkmcnt(8)
	v_mfma_scale_f32_32x32x64_f8f6f4 v[98:113], v[222:229], v[130:137], v[98:113], v194, v193 op_sel_hi:[0,0,0]
	v_mov_b32_e32 v0, v219
	s_nop 1
	v_permlane32_swap_b32_e32 v219, v0
	v_add_f32_e32 v219, v219, v0
	v_fma_f32 v209, v209, v218, v219
	s_waitcnt vmcnt(0)
	ds_write_b128 v210, v[158:161]
	ds_write_b128 v211, v[162:165] offset:16384
	s_waitcnt lgkmcnt(0)
	s_barrier
	global_load_dwordx4 v[158:161], v176, s[18:19]
	global_load_dwordx4 v[162:165], v178, s[16:17]
	v_max_f32_e32 v177, v114, v115
	v_max3_f32 v177, v177, v116, v117
	v_max3_f32 v177, v177, v118, v119
	v_max3_f32 v177, v177, v120, v121
	v_max3_f32 v177, v177, v122, v123
	v_max3_f32 v177, v177, v124, v125
	v_max3_f32 v177, v177, v126, v127
	v_max3_f32 v177, v177, v128, v129
	v_add_u32_e32 v176, 0x2000, v176
	v_add_u32_e32 v178, 0x20000, v178
	v_mfma_scale_f32_32x32x64_f8f6f4 v[50:65], v[246:253], v[90:97], v[50:65], v194, v194 op_sel_hi:[0,0,0]
	v_mfma_scale_f32_32x32x64_f8f6f4 v[34:49], v[246:253], v[82:89], v[34:49], v194, v194 op_sel_hi:[0,0,0]
	v_mfma_scale_f32_32x32x64_f8f6f4 v[18:33], v[246:253], v[74:81], v[18:33], v194, v194 op_sel_hi:[0,0,0]
	v_mfma_scale_f32_32x32x64_f8f6f4 v[2:17], v[246:253], v[66:73], v[2:17], v194, v194 op_sel_hi:[0,0,0]
	v_max_f32_e32 v0, v98, v99
	v_max3_f32 v0, v0, v100, v101
	v_max3_f32 v0, v0, v102, v103
	v_max3_f32 v0, v0, v104, v105
	v_max3_f32 v0, v0, v106, v107
	v_max3_f32 v0, v0, v108, v109
	v_max3_f32 v0, v0, v110, v111
	v_max3_f32 v0, v0, v112, v113
	v_max_f32_e32 v177, v177, v0
	v_mov_b32_e32 v0, v177
	v_mov_b32_e32 v221, 1.0
	s_nop 0
	v_permlane32_swap_b32_e32 v177, v0
	v_max_f32_e32 v177, v177, v0
	v_cmp_ge_f32_e32 vcc, s90, v177
	s_cmp_eq_u64 vcc, exec
	s_cbranch_scc0 .Lmla_s4_newmax
; #define SLOAD() do { vs0 = *(const bf16x8*)(Vh + voff); vs1 = *(const bf16x8*)(Vh + voff + 32u * (unsigned)ldv); \
;     ks0 = *(const bf16x8*)(Kh + koff); ks1 = *(const bf16x8*)(Kh + koff + 32u * (unsigned)ldk); \
;     if constexpr (NR > 0) { kr = *(const bf16x8*)(Krh + kroff); kroff += 64u * 64u; } voff += 64u * (unsigned)ldv; koff += 64u * (unsigned)ldk; } while (0)
; #define SWRITE(b) do { *(bf16x8*)(V_lds + (b) * SHM_V + vst0) = vs0; *(bf16x8*)(V_lds + (b) * SHM_V + vst1) = vs1; const int kc = sc * 2;  \
;     *(bf16x8*)(K_lds + (b) * SHM_K + KSWZ(sr, kc)) = ks0; *(bf16x8*)(K_lds + (b) * SHM_K + KSWZ(32 + sr, kc)) = ks1; \
;     if constexpr (NR > 0) *(bf16x8*)(Kr_lds + (b) * SHM_KR + krst) = kr; } while (0)
; #define SLOAD() do { vs0 = *(const bf16x8*)(Vh + voff); vs1 = *(const bf16x8*)(Vh + voff + 32u * (unsigned)ldv); \
;     ks0 = *(const bf16x8*)(Kh + voff); ks1 = *(const bf16x8*)(Kh + voff + 32u * (unsigned)ldv); \
;     if constexpr (NR > 0) { kr = *(const bf16x8*)(Krh + kroff); kroff += 64u * 64u; } voff += 64u * (unsigned)ldv; } while (0)
; #define SWRITE(b) do { *(bf16x8*)(V_lds + (b) * SHM_V + vst0) = vs0; *(bf16x8*)(V_lds + (b) * SHM_V + vst0 + 8192) = vs1;  \
;     *(bf16x8*)(K_lds + (b) * SHM_K + kst0) = ks0; *(bf16x8*)(K_lds + (b) * SHM_K + kst0 + 8192) = ks1; \
;     if constexpr (NR > 0) *(bf16x8*)(Kr_lds + (b) * SHM_KR + krst) = kr; } while (0)
; #define SWRITE(b) do { *(v4i32*)(Vt_lds + (b) * 8192 + vtst) = vt; *(v4i32*)(Kn_lds + (b) * 8192 + knst) = kn; if (krw) *(v4i32*)(Kr_lds + (b) * 4096 + krst) = kr; } while (0)
; __device__ __forceinline__ void attn_unit7(const unsigned char* __restrict__ Q8, int ldq, const unsigned char* __restrict__ Kn8, int ldk, const unsigned char* __restrict__ Kr8, ...
;     ...
;   for (int j = 1; j + 1 < NT; j += 2) {
;     SLOAD();
;     qkt9(pB0, pB1, Kn_lds + 8192, Kr_lds + 4096, qf, 7.0f - m_reg, r32, hi);
;     finishSM9(pA0, pA1, alA, l_reg, p8);
;     pv8(o, Vt_lds, p8, r32, hi); partialSM9(pB0, pB1, m_reg, alB, thr_raw);
;     __syncthreads(); SWRITE(0);
;     RESC(alB); __syncthreads();
;     if (j + 2 < NT) SLOAD();
;     qkt9(pA0, pA1, Kn_lds, Kr_lds, qf, 7.0f - m_reg, r32, hi);
;     finishSM9(pB0, pB1, alB, l_reg, p8);
;     pv8(o, Vt_lds + 8192, p8, r32, hi); partialSM9(pA0, pA1, m_reg, alA, thr_raw);
;     __syncthreads(); if (j + 2 < NT) SWRITE(1);
;     RESC(alA); __syncthreads();
.Lmla_s4_cont:
	ds_read_b128 v[82:85], v215 offset:16384
	ds_read_b128 v[86:89], v216 offset:16384
	ds_read_b128 v[222:225], v215 offset:20480
	ds_read_b128 v[226:229], v216 offset:20480
	v_exp_f32_e32 v0, v114
	v_exp_f32_e32 v177, v115
	v_exp_f32_e32 v179, v116
	v_exp_f32_e32 v254, v117
	v_add_f32_e32 v219, v0, v177
	v_cvt_pk_fp8_f32 v246, v0, v177
	v_add_f32_e32 v219, v179, v219
	v_add_f32_e32 v219, v254, v219
	v_cvt_pk_fp8_f32 v246, v179, v254 op_sel:[0,0,1]
	s_waitcnt lgkmcnt(2)
	v_mfma_scale_f32_32x32x64_f8f6f4 v[82:97], v[82:89], v[146:153], v[230:245], v194, v193 op_sel_hi:[0,0,0]
	v_exp_f32_e32 v0, v118
	v_exp_f32_e32 v177, v119
	v_exp_f32_e32 v179, v120
	v_exp_f32_e32 v254, v121
	v_add_f32_e32 v219, v0, v219
	v_add_f32_e32 v219, v177, v219
	v_cvt_pk_fp8_f32 v247, v0, v177
	v_add_f32_e32 v219, v179, v219
	v_add_f32_e32 v219, v254, v219
	v_cvt_pk_fp8_f32 v247, v179, v254 op_sel:[0,0,1]
	ds_read_b128 v[114:117], v213 offset:16384
	ds_read_b128 v[118:121], v214 offset:16384
	s_waitcnt lgkmcnt(2)
	v_mfma_scale_f32_32x32x64_f8f6f4 v[66:81], v[222:229], v[146:153], v[230:245], v194, v193 op_sel_hi:[0,0,0]
	ds_read_b128 v[222:225], v213 offset:20480
	ds_read_b128 v[226:229], v214 offset:20480
	v_exp_f32_e32 v0, v122
	v_exp_f32_e32 v177, v123
	v_exp_f32_e32 v179, v124
	v_exp_f32_e32 v254, v125
	v_add_f32_e32 v219, v0, v219
	v_add_f32_e32 v219, v177, v219
	v_cvt_pk_fp8_f32 v248, v0, v177
	v_add_f32_e32 v219, v179, v219
	v_add_f32_e32 v219, v254, v219
	v_cvt_pk_fp8_f32 v248, v179, v254 op_sel:[0,0,1]
	v_exp_f32_e32 v0, v126
	v_exp_f32_e32 v177, v127
	v_exp_f32_e32 v179, v128
	v_exp_f32_e32 v254, v129
	v_add_f32_e32 v219, v0, v219
	v_add_f32_e32 v219, v177, v219
	v_cvt_pk_fp8_f32 v249, v0, v177
	v_add_f32_e32 v219, v179, v219
	v_add_f32_e32 v219, v254, v219
	v_cvt_pk_fp8_f32 v249, v179, v254 op_sel:[0,0,1]
	ds_read_b128 v[122:125], v185 offset:32768
	ds_read_b128 v[126:129], v186 offset:32768
	s_waitcnt lgkmcnt(4)
	v_mfma_scale_f32_32x32x64_f8f6f4 v[82:97], v[114:121], v[138:145], v[82:97], v194, v193 op_sel_hi:[0,0,0]
	v_exp_f32_e32 v0, v98
	v_exp_f32_e32 v177, v99
	v_exp_f32_e32 v179, v100
	v_exp_f32_e32 v254, v101
	v_add_f32_e32 v219, v0, v219
	v_add_f32_e32 v219, v177, v219
	v_cvt_pk_fp8_f32 v250, v0, v177
	v_add_f32_e32 v219, v179, v219
	v_add_f32_e32 v219, v254, v219
	v_cvt_pk_fp8_f32 v250, v179, v254 op_sel:[0,0,1]
	s_waitcnt lgkmcnt(2)
	v_mfma_scale_f32_32x32x64_f8f6f4 v[66:81], v[222:229], v[138:145], v[66:81], v194, v193 op_sel_hi:[0,0,0]
	ds_read_b128 v[222:225], v185 offset:34816
	ds_read_b128 v[226:229], v186 offset:34816
	v_exp_f32_e32 v0, v102
	v_exp_f32_e32 v177, v103
	v_exp_f32_e32 v179, v104
	v_exp_f32_e32 v254, v105
	v_add_f32_e32 v219, v0, v219
	v_add_f32_e32 v219, v177, v219
	v_cvt_pk_fp8_f32 v251, v0, v177
	v_add_f32_e32 v219, v179, v219
	v_add_f32_e32 v219, v254, v219
	v_cvt_pk_fp8_f32 v251, v179, v254 op_sel:[0,0,1]
	v_exp_f32_e32 v0, v106
	v_exp_f32_e32 v177, v107
	v_exp_f32_e32 v179, v108
	v_exp_f32_e32 v254, v109
	v_add_f32_e32 v219, v0, v219
	v_add_f32_e32 v219, v177, v219
	v_cvt_pk_fp8_f32 v252, v0, v177
	v_add_f32_e32 v219, v179, v219
	v_add_f32_e32 v219, v254, v219
	v_cvt_pk_fp8_f32 v252, v179, v254 op_sel:[0,0,1]
	s_waitcnt lgkmcnt(2)
	v_mfma_scale_f32_32x32x64_f8f6f4 v[82:97], v[122:129], v[130:137], v[82:97], v194, v193 op_sel_hi:[0,0,0]
	v_exp_f32_e32 v0, v110
	v_exp_f32_e32 v177, v111
	v_exp_f32_e32 v179, v112
	v_exp_f32_e32 v254, v113
	v_add_f32_e32 v219, v0, v219
	v_add_f32_e32 v219, v177, v219
	v_cvt_pk_fp8_f32 v253, v0, v177
	v_add_f32_e32 v219, v179, v219
	v_add_f32_e32 v219, v254, v219
	v_cvt_pk_fp8_f32 v253, v179, v254 op_sel:[0,0,1]
	ds_read_b128 v[122:125], v185 offset:43008
	ds_read_b128 v[126:129], v186 offset:43008
	ds_read_b128 v[114:117], v185 offset:45056
	ds_read_b128 v[118:121], v186 offset:45056
	ds_read_b128 v[106:109], v185 offset:47104
	ds_read_b128 v[110:113], v186 offset:47104
	ds_read_b128 v[98:101], v185 offset:49152
	ds_read_b128 v[102:105], v186 offset:49152
	s_waitcnt lgkmcnt(8)
	v_mfma_scale_f32_32x32x64_f8f6f4 v[66:81], v[222:229], v[130:137], v[66:81], v194, v193 op_sel_hi:[0,0,0]
	v_mov_b32_e32 v0, v219
	s_nop 1
	v_permlane32_swap_b32_e32 v219, v0
	v_add_f32_e32 v219, v219, v0
	v_fma_f32 v209, v209, v221, v219
	s_waitcnt vmcnt(0)
	ds_write_b128 v210, v[158:161] offset:8192
	ds_write_b128 v211, v[162:165] offset:24576
	s_waitcnt lgkmcnt(0)
	s_barrier
	global_load_dwordx4 v[158:161], v176, s[18:19]
	global_load_dwordx4 v[162:165], v178, s[16:17]
	v_max_f32_e32 v177, v82, v83
	v_max3_f32 v177, v177, v84, v85
	v_max3_f32 v177, v177, v86, v87
	v_max3_f32 v177, v177, v88, v89
	v_max3_f32 v177, v177, v90, v91
	v_max3_f32 v177, v177, v92, v93
	v_max3_f32 v177, v177, v94, v95
	v_max3_f32 v177, v177, v96, v97
	v_add_u32_e32 v176, 0x2000, v176
	v_add_u32_e32 v178, 0x20000, v178
	v_mfma_scale_f32_32x32x64_f8f6f4 v[50:65], v[246:253], v[122:129], v[50:65], v194, v194 op_sel_hi:[0,0,0]
	v_mfma_scale_f32_32x32x64_f8f6f4 v[34:49], v[246:253], v[114:121], v[34:49], v194, v194 op_sel_hi:[0,0,0]
	v_mfma_scale_f32_32x32x64_f8f6f4 v[18:33], v[246:253], v[106:113], v[18:33], v194, v194 op_sel_hi:[0,0,0]
	v_mfma_scale_f32_32x32x64_f8f6f4 v[2:17], v[246:253], v[98:105], v[2:17], v194, v194 op_sel_hi:[0,0,0]
	v_max_f32_e32 v0, v66, v67
	v_max3_f32 v0, v0, v68, v69
	v_max3_f32 v0, v0, v70, v71
	v_max3_f32 v0, v0, v72, v73
	v_max3_f32 v0, v0, v74, v75
	v_max3_f32 v0, v0, v76, v77
	v_max3_f32 v0, v0, v78, v79
	v_max3_f32 v0, v0, v80, v81
	v_max_f32_e32 v177, v177, v0
	v_mov_b32_e32 v0, v177
	v_mov_b32_e32 v218, 1.0
	s_nop 0
	v_permlane32_swap_b32_e32 v177, v0
	v_max_f32_e32 v177, v177, v0
	v_cmp_ge_f32_e32 vcc, s90, v177
	s_cmp_eq_u64 vcc, exec
	s_cbranch_scc0 .Lmla_s5_newmax
; #define SLOAD() do { vs0 = *(const bf16x8*)(Vh + voff); vs1 = *(const bf16x8*)(Vh + voff + 32u * (unsigned)ldv); \
;     ks0 = *(const bf16x8*)(Kh + koff); ks1 = *(const bf16x8*)(Kh + koff + 32u * (unsigned)ldk); \
;     if constexpr (NR > 0) { kr = *(const bf16x8*)(Krh + kroff); kroff += 64u * 64u; } voff += 64u * (unsigned)ldv; koff += 64u * (unsigned)ldk; } while (0)
; #define SWRITE(b) do { *(bf16x8*)(V_lds + (b) * SHM_V + vst0) = vs0; *(bf16x8*)(V_lds + (b) * SHM_V + vst1) = vs1; const int kc = sc * 2;  \
;     *(bf16x8*)(K_lds + (b) * SHM_K + KSWZ(sr, kc)) = ks0; *(bf16x8*)(K_lds + (b) * SHM_K + KSWZ(32 + sr, kc)) = ks1; \
;     if constexpr (NR > 0) *(bf16x8*)(Kr_lds + (b) * SHM_KR + krst) = kr; } while (0)
; #define SLOAD() do { vs0 = *(const bf16x8*)(Vh + voff); vs1 = *(const bf16x8*)(Vh + voff + 32u * (unsigned)ldv); \
;     ks0 = *(const bf16x8*)(Kh + voff); ks1 = *(const bf16x8*)(Kh + voff + 32u * (unsigned)ldv); \
;     if constexpr (NR > 0) { kr = *(const bf16x8*)(Krh + kroff); kroff += 64u * 64u; } voff += 64u * (unsigned)ldv; } while (0)
; #define SWRITE(b) do { *(bf16x8*)(V_lds + (b) * SHM_V + vst0) = vs0; *(bf16x8*)(V_lds + (b) * SHM_V + vst0 + 8192) = vs1;  \
;     *(bf16x8*)(K_lds + (b) * SHM_K + kst0) = ks0; *(bf16x8*)(K_lds + (b) * SHM_K + kst0 + 8192) = ks1; \
;     if constexpr (NR > 0) *(bf16x8*)(Kr_lds + (b) * SHM_KR + krst) = kr; } while (0)
; #define RESC(a) do { if (__any((a) < 1.f)) { if (hi == 0) al_l[r32] = (a); asm volatile("s_waitcnt lgkmcnt(0)" ::: "memory"); \
;     _Pragma("unroll") for (int d = 0; d < 4; ++d) _Pragma("unroll") for (int r = 0; r < 16; ++r) o[d][r] *= al_l[crow(r, hi)]; } } while (0)
; __device__ __forceinline__ void attn_unit7(const unsigned char* __restrict__ Q8, int ldq, const unsigned char* __restrict__ Kn8, int ldk, const unsigned char* __restrict__ Kr8, ...
;     ...
;     if (j + 2 < NT) SLOAD();
;     qkt9(pA0, pA1, Kn_lds, Kr_lds, qf, 7.0f - m_reg, r32, hi);
;     finishSM9(pB0, pB1, alB, l_reg, p8);
;     pv8(o, Vt_lds + 8192, p8, r32, hi); partialSM9(pA0, pA1, m_reg, alA, thr_raw);
;     __syncthreads(); if (j + 2 < NT) SWRITE(1);
;     RESC(alA); __syncthreads();
;   }
;   qkt9(pB0, pB1, Kn_lds + 8192, Kr_lds + 4096, qf, 7.0f - m_reg, r32, hi);
.Lmla_s5_cont:
	s_add_i32 s30, s30, 1
	s_cmpk_lt_u32 s30, 42
	s_cbranch_scc1 .Lmla_stag_loop
	ds_read_b128 v[114:117], v215 offset:24576
	ds_read_b128 v[118:121], v216 offset:24576
	ds_read_b128 v[222:225], v215 offset:28672
	ds_read_b128 v[226:229], v216 offset:28672
	v_exp_f32_e32 v0, v82
	v_exp_f32_e32 v177, v83
	v_exp_f32_e32 v179, v84
	v_exp_f32_e32 v254, v85
	v_add_f32_e32 v219, v0, v177
	v_cvt_pk_fp8_f32 v246, v0, v177
	v_add_f32_e32 v219, v179, v219
	v_add_f32_e32 v219, v254, v219
	v_cvt_pk_fp8_f32 v246, v179, v254 op_sel:[0,0,1]
	s_waitcnt lgkmcnt(2)
	v_mfma_scale_f32_32x32x64_f8f6f4 v[114:129], v[114:121], v[146:153], v[230:245], v194, v193 op_sel_hi:[0,0,0]
	v_exp_f32_e32 v0, v86
	v_exp_f32_e32 v177, v87
	v_exp_f32_e32 v179, v88
	v_exp_f32_e32 v254, v89
	v_add_f32_e32 v219, v0, v219
	v_add_f32_e32 v219, v177, v219
	v_cvt_pk_fp8_f32 v247, v0, v177
	v_add_f32_e32 v219, v179, v219
	v_add_f32_e32 v219, v254, v219
	v_cvt_pk_fp8_f32 v247, v179, v254 op_sel:[0,0,1]
	ds_read_b128 v[82:85], v213 offset:24576
	ds_read_b128 v[86:89], v214 offset:24576
	s_waitcnt lgkmcnt(2)
	v_mfma_scale_f32_32x32x64_f8f6f4 v[98:113], v[222:229], v[146:153], v[230:245], v194, v193 op_sel_hi:[0,0,0]
	ds_read_b128 v[222:225], v213 offset:28672
	ds_read_b128 v[226:229], v214 offset:28672
	v_exp_f32_e32 v0, v90
	v_exp_f32_e32 v177, v91
	v_exp_f32_e32 v179, v92
	v_exp_f32_e32 v254, v93
	v_add_f32_e32 v219, v0, v219
	v_add_f32_e32 v219, v177, v219
	v_cvt_pk_fp8_f32 v248, v0, v177
	v_add_f32_e32 v219, v179, v219
	v_add_f32_e32 v219, v254, v219
	v_cvt_pk_fp8_f32 v248, v179, v254 op_sel:[0,0,1]
	v_exp_f32_e32 v0, v94
	v_exp_f32_e32 v177, v95
	v_exp_f32_e32 v179, v96
	v_exp_f32_e32 v254, v97
	v_add_f32_e32 v219, v0, v219
	v_add_f32_e32 v219, v177, v219
	v_cvt_pk_fp8_f32 v249, v0, v177
	v_add_f32_e32 v219, v179, v219
	v_add_f32_e32 v219, v254, v219
	v_cvt_pk_fp8_f32 v249, v179, v254 op_sel:[0,0,1]
	ds_read_b128 v[90:93], v185 offset:36864
	ds_read_b128 v[94:97], v186 offset:36864
	s_waitcnt lgkmcnt(4)
	v_mfma_scale_f32_32x32x64_f8f6f4 v[114:129], v[82:89], v[138:145], v[114:129], v194, v193 op_sel_hi:[0,0,0]
	v_exp_f32_e32 v0, v66
	v_exp_f32_e32 v177, v67
	v_exp_f32_e32 v179, v68
	v_exp_f32_e32 v254, v69
	v_add_f32_e32 v219, v0, v219
	v_add_f32_e32 v219, v177, v219
	v_cvt_pk_fp8_f32 v250, v0, v177
	v_add_f32_e32 v219, v179, v219
	v_add_f32_e32 v219, v254, v219
	v_cvt_pk_fp8_f32 v250, v179, v254 op_sel:[0,0,1]
	s_waitcnt lgkmcnt(2)
	v_mfma_scale_f32_32x32x64_f8f6f4 v[98:113], v[222:229], v[138:145], v[98:113], v194, v193 op_sel_hi:[0,0,0]
	ds_read_b128 v[222:225], v185 offset:38912
	ds_read_b128 v[226:229], v186 offset:38912
	v_exp_f32_e32 v0, v70
	v_exp_f32_e32 v177, v71
	v_exp_f32_e32 v179, v72
	v_exp_f32_e32 v254, v73
	v_add_f32_e32 v219, v0, v219
	v_add_f32_e32 v219, v177, v219
	v_cvt_pk_fp8_f32 v251, v0, v177
	v_add_f32_e32 v219, v179, v219
	v_add_f32_e32 v219, v254, v219
	v_cvt_pk_fp8_f32 v251, v179, v254 op_sel:[0,0,1]
	v_exp_f32_e32 v0, v74
	v_exp_f32_e32 v177, v75
	v_exp_f32_e32 v179, v76
	v_exp_f32_e32 v254, v77
	v_add_f32_e32 v219, v0, v219
	v_add_f32_e32 v219, v177, v219
	v_cvt_pk_fp8_f32 v252, v0, v177
	v_add_f32_e32 v219, v179, v219
	v_add_f32_e32 v219, v254, v219
	v_cvt_pk_fp8_f32 v252, v179, v254 op_sel:[0,0,1]
	s_waitcnt lgkmcnt(2)
	v_mfma_scale_f32_32x32x64_f8f6f4 v[114:129], v[90:97], v[130:137], v[114:129], v194, v193 op_sel_hi:[0,0,0]
	v_exp_f32_e32 v0, v78
	v_exp_f32_e32 v177, v79
	v_exp_f32_e32 v179, v80
	v_exp_f32_e32 v254, v81
	v_add_f32_e32 v219, v0, v219
	v_add_f32_e32 v219, v177, v219
	v_cvt_pk_fp8_f32 v253, v0, v177
	v_add_f32_e32 v219, v179, v219
	v_add_f32_e32 v219, v254, v219
	v_cvt_pk_fp8_f32 v253, v179, v254 op_sel:[0,0,1]
	ds_read_b128 v[90:93], v185 offset:0
	ds_read_b128 v[94:97], v186 offset:0
	ds_read_b128 v[82:85], v185 offset:2048
	ds_read_b128 v[86:89], v186 offset:2048
	ds_read_b128 v[74:77], v185 offset:4096
	ds_read_b128 v[78:81], v186 offset:4096
	ds_read_b128 v[66:69], v185 offset:6144
	ds_read_b128 v[70:73], v186 offset:6144
	s_waitcnt lgkmcnt(8)
	v_mfma_scale_f32_32x32x64_f8f6f4 v[98:113], v[222:229], v[130:137], v[98:113], v194, v193 op_sel_hi:[0,0,0]
	v_mov_b32_e32 v0, v219
	s_nop 1
	v_permlane32_swap_b32_e32 v219, v0
	v_add_f32_e32 v219, v219, v0
	v_fma_f32 v209, v209, v218, v219
	s_waitcnt vmcnt(0)
	ds_write_b128 v210, v[158:161] offset:43008
	ds_write_b128 v211, v[162:165] offset:51200
	s_waitcnt lgkmcnt(0)
	s_barrier
	global_load_dwordx4 v[158:161], v176, s[18:19]
	global_load_dwordx4 v[162:165], v178, s[16:17]
	v_max_f32_e32 v177, v114, v115
	v_max3_f32 v177, v177, v116, v117
	v_max3_f32 v177, v177, v118, v119
	v_max3_f32 v177, v177, v120, v121
	v_max3_f32 v177, v177, v122, v123
	v_max3_f32 v177, v177, v124, v125
	v_max3_f32 v177, v177, v126, v127
	v_max3_f32 v177, v177, v128, v129
	v_add_u32_e32 v176, 0x2000, v176
	v_add_u32_e32 v178, 0x20000, v178
	v_mfma_scale_f32_32x32x64_f8f6f4 v[50:65], v[246:253], v[90:97], v[50:65], v194, v194 op_sel_hi:[0,0,0]
	v_mfma_scale_f32_32x32x64_f8f6f4 v[34:49], v[246:253], v[82:89], v[34:49], v194, v194 op_sel_hi:[0,0,0]
	v_mfma_scale_f32_32x32x64_f8f6f4 v[18:33], v[246:253], v[74:81], v[18:33], v194, v194 op_sel_hi:[0,0,0]
	v_mfma_scale_f32_32x32x64_f8f6f4 v[2:17], v[246:253], v[66:73], v[2:17], v194, v194 op_sel_hi:[0,0,0]
	v_max_f32_e32 v0, v98, v99
	v_max3_f32 v0, v0, v100, v101
	v_max3_f32 v0, v0, v102, v103
	v_max3_f32 v0, v0, v104, v105
	v_max3_f32 v0, v0, v106, v107
	v_max3_f32 v0, v0, v108, v109
	v_max3_f32 v0, v0, v110, v111
	v_max3_f32 v0, v0, v112, v113
	v_max_f32_e32 v177, v177, v0
	v_mov_b32_e32 v0, v177
	v_mov_b32_e32 v221, 1.0
	s_nop 0
	v_permlane32_swap_b32_e32 v177, v0
	v_max_f32_e32 v177, v177, v0
	v_cmp_ge_f32_e32 vcc, s90, v177
	s_cmp_eq_u64 vcc, exec
	s_cbranch_scc0 .Lmla_q0_newmax
; #define SWRITE(b) do { *(bf16x8*)(V_lds + (b) * SHM_V + vst0) = vs0; *(bf16x8*)(V_lds + (b) * SHM_V + vst1) = vs1; const int kc = sc * 2;  \
;     *(bf16x8*)(K_lds + (b) * SHM_K + KSWZ(sr, kc)) = ks0; *(bf16x8*)(K_lds + (b) * SHM_K + KSWZ(32 + sr, kc)) = ks1; \
;     if constexpr (NR > 0) *(bf16x8*)(Kr_lds + (b) * SHM_KR + krst) = kr; } while (0)
; #define SWRITE(b) do { *(bf16x8*)(V_lds + (b) * SHM_V + vst0) = vs0; *(bf16x8*)(V_lds + (b) * SHM_V + vst0 + 8192) = vs1;  \
;     *(bf16x8*)(K_lds + (b) * SHM_K + kst0) = ks0; *(bf16x8*)(K_lds + (b) * SHM_K + kst0 + 8192) = ks1; \
;     if constexpr (NR > 0) *(bf16x8*)(Kr_lds + (b) * SHM_KR + krst) = kr; } while (0)
; #define RESC(a) do { if (__any((a) < 1.f)) { if (hi == 0) al_l[r32] = (a); asm volatile("s_waitcnt lgkmcnt(0)" ::: "memory"); \
;     _Pragma("unroll") for (int d = 0; d < 4; ++d) _Pragma("unroll") for (int r = 0; r < 16; ++r) o[d][r] *= al_l[crow(r, hi)]; } } while (0)
; #define SWRITE(b) do { *(bf16x8*)(V_lds + (b) * 16384 + vst0) = vs0; *(bf16x8*)(V_lds + (b) * 16384 + vst0 + 8192) = vs1;  \
;     *(v4i32*)(Kn_lds + (b) * 8192 + knst) = kn; if (krw) *(v4i32*)(Kr_lds + (b) * 4096 + krst) = kr; } while (0)
; #define RESC(a) do { if (__any((a) < 1.f)) { if (hi == 0) al_l[r32] = (a); asm volatile("s_waitcnt lgkmcnt(0)" ::: "memory"); \
;     _Pragma("unroll") for (int d = 0; d < 4; ++d) _Pragma("unroll") for (int r = 0; r < 16; ++r) o[d][r] *= al_l[crow(r, hi)]; } } while (0)
; #define SWRITE(b) do { *(v4i32*)(Vt_lds + (b) * 8192 + vtst) = vt; *(v4i32*)(Kn_lds + (b) * 8192 + knst) = kn; if (krw) *(v4i32*)(Kr_lds + (b) * 4096 + krst) = kr; } while (0)
; __device__ __forceinline__ void attn_unit7(const unsigned char* __restrict__ Q8, int ldq, const unsigned char* __restrict__ Kn8, int ldk, const unsigned char* __restrict__ Kr8, ...
;     ...
;     qkt9(pA0, pA1, Kn_lds, Kr_lds, qf, 7.0f - m_reg, r32, hi);
;     finishSM9(pB0, pB1, alB, l_reg, p8);
;     pv8(o, Vt_lds + 8192, p8, r32, hi); partialSM9(pA0, pA1, m_reg, alA, thr_raw);
;     __syncthreads(); if (j + 2 < NT) SWRITE(1);
;     RESC(alA); __syncthreads();
;   }
;   qkt9(pB0, pB1, Kn_lds + 8192, Kr_lds + 4096, qf, 7.0f - m_reg, r32, hi);
;   finishSM9(pA0, pA1, alA, l_reg, p8);
.Lmla_q0_cont:
	ds_read_b128 v[82:85], v215 offset:51200
	ds_read_b128 v[86:89], v216 offset:51200
	ds_read_b128 v[222:225], v215 offset:55296
	ds_read_b128 v[226:229], v216 offset:55296
	v_exp_f32_e32 v0, v114
	v_exp_f32_e32 v177, v115
	v_exp_f32_e32 v179, v116
	v_exp_f32_e32 v254, v117
	v_add_f32_e32 v219, v0, v177
	v_cvt_pk_fp8_f32 v246, v0, v177
	v_add_f32_e32 v219, v179, v219
	v_add_f32_e32 v219, v254, v219
	v_cvt_pk_fp8_f32 v246, v179, v254 op_sel:[0,0,1]
	s_waitcnt lgkmcnt(2)
	v_mfma_scale_f32_32x32x64_f8f6f4 v[82:97], v[82:89], v[146:153], v[230:245], v194, v193 op_sel_hi:[0,0,0]
	v_exp_f32_e32 v0, v118
	v_exp_f32_e32 v177, v119
	v_exp_f32_e32 v179, v120
	v_exp_f32_e32 v254, v121
	v_add_f32_e32 v219, v0, v219
	v_add_f32_e32 v219, v177, v219
	v_cvt_pk_fp8_f32 v247, v0, v177
	v_add_f32_e32 v219, v179, v219
	v_add_f32_e32 v219, v254, v219
	v_cvt_pk_fp8_f32 v247, v179, v254 op_sel:[0,0,1]
	ds_read_b128 v[114:117], v213 offset:51200
	ds_read_b128 v[118:121], v214 offset:51200
	s_waitcnt lgkmcnt(2)
	v_mfma_scale_f32_32x32x64_f8f6f4 v[66:81], v[222:229], v[146:153], v[230:245], v194, v193 op_sel_hi:[0,0,0]
	ds_read_b128 v[222:225], v213 offset:55296
	ds_read_b128 v[226:229], v214 offset:55296
	v_exp_f32_e32 v0, v122
	v_exp_f32_e32 v177, v123
	v_exp_f32_e32 v179, v124
	v_exp_f32_e32 v254, v125
	v_add_f32_e32 v219, v0, v219
	v_add_f32_e32 v219, v177, v219
	v_cvt_pk_fp8_f32 v248, v0, v177
	v_add_f32_e32 v219, v179, v219
	v_add_f32_e32 v219, v254, v219
	v_cvt_pk_fp8_f32 v248, v179, v254 op_sel:[0,0,1]
	v_exp_f32_e32 v0, v126
	v_exp_f32_e32 v177, v127
	v_exp_f32_e32 v179, v128
	v_exp_f32_e32 v254, v129
	v_add_f32_e32 v219, v0, v219
	v_add_f32_e32 v219, v177, v219
	v_cvt_pk_fp8_f32 v249, v0, v177
	v_add_f32_e32 v219, v179, v219
	v_add_f32_e32 v219, v254, v219
	v_cvt_pk_fp8_f32 v249, v179, v254 op_sel:[0,0,1]
	ds_read_b128 v[122:125], v185 offset:59392
	ds_read_b128 v[126:129], v186 offset:59392
	s_waitcnt lgkmcnt(4)
	v_mfma_scale_f32_32x32x64_f8f6f4 v[82:97], v[114:121], v[138:145], v[82:97], v194, v193 op_sel_hi:[0,0,0]
	v_exp_f32_e32 v0, v98
	v_exp_f32_e32 v177, v99
	v_exp_f32_e32 v179, v100
	v_exp_f32_e32 v254, v101
	v_add_f32_e32 v219, v0, v219
	v_add_f32_e32 v219, v177, v219
	v_cvt_pk_fp8_f32 v250, v0, v177
	v_add_f32_e32 v219, v179, v219
	v_add_f32_e32 v219, v254, v219
	v_cvt_pk_fp8_f32 v250, v179, v254 op_sel:[0,0,1]
	s_waitcnt lgkmcnt(2)
	v_mfma_scale_f32_32x32x64_f8f6f4 v[66:81], v[222:229], v[138:145], v[66:81], v194, v193 op_sel_hi:[0,0,0]
	ds_read_b128 v[222:225], v185 offset:61440
	ds_read_b128 v[226:229], v186 offset:61440
	v_exp_f32_e32 v0, v102
	v_exp_f32_e32 v177, v103
	v_exp_f32_e32 v179, v104
	v_exp_f32_e32 v254, v105
	v_add_f32_e32 v219, v0, v219
	v_add_f32_e32 v219, v177, v219
	v_cvt_pk_fp8_f32 v251, v0, v177
	v_add_f32_e32 v219, v179, v219
	v_add_f32_e32 v219, v254, v219
	v_cvt_pk_fp8_f32 v251, v179, v254 op_sel:[0,0,1]
	v_exp_f32_e32 v0, v106
	v_exp_f32_e32 v177, v107
	v_exp_f32_e32 v179, v108
	v_exp_f32_e32 v254, v109
	v_add_f32_e32 v219, v0, v219
	v_add_f32_e32 v219, v177, v219
	v_cvt_pk_fp8_f32 v252, v0, v177
	v_add_f32_e32 v219, v179, v219
	v_add_f32_e32 v219, v254, v219
	v_cvt_pk_fp8_f32 v252, v179, v254 op_sel:[0,0,1]
	s_waitcnt lgkmcnt(2)
	v_mfma_scale_f32_32x32x64_f8f6f4 v[82:97], v[122:129], v[130:137], v[82:97], v194, v193 op_sel_hi:[0,0,0]
	v_exp_f32_e32 v0, v110
	v_exp_f32_e32 v177, v111
	v_exp_f32_e32 v179, v112
	v_exp_f32_e32 v254, v113
	v_add_f32_e32 v219, v0, v219
	v_add_f32_e32 v219, v177, v219
	v_cvt_pk_fp8_f32 v253, v0, v177
	v_add_f32_e32 v219, v179, v219
	v_add_f32_e32 v219, v254, v219
	v_cvt_pk_fp8_f32 v253, v179, v254 op_sel:[0,0,1]
	ds_read_b128 v[122:125], v185 offset:8192
	ds_read_b128 v[126:129], v186 offset:8192
	ds_read_b128 v[114:117], v185 offset:10240
	ds_read_b128 v[118:121], v186 offset:10240
	ds_read_b128 v[106:109], v185 offset:12288
	ds_read_b128 v[110:113], v186 offset:12288
	ds_read_b128 v[98:101], v185 offset:14336
	ds_read_b128 v[102:105], v186 offset:14336
	s_waitcnt lgkmcnt(8)
	v_mfma_scale_f32_32x32x64_f8f6f4 v[66:81], v[222:229], v[130:137], v[66:81], v194, v193 op_sel_hi:[0,0,0]
	v_mov_b32_e32 v0, v219
	s_nop 1
	v_permlane32_swap_b32_e32 v219, v0
	v_add_f32_e32 v219, v219, v0
	v_fma_f32 v209, v209, v221, v219
	s_waitcnt vmcnt(0)
	ds_write_b128 v210, v[158:161]
	ds_write_b128 v211, v[162:165] offset:16384
	s_waitcnt lgkmcnt(0)
	s_barrier
	v_max_f32_e32 v177, v82, v83
	v_max3_f32 v177, v177, v84, v85
	v_max3_f32 v177, v177, v86, v87
	v_max3_f32 v177, v177, v88, v89
	v_max3_f32 v177, v177, v90, v91
	v_max3_f32 v177, v177, v92, v93
	v_max3_f32 v177, v177, v94, v95
	v_max3_f32 v177, v177, v96, v97
	v_mfma_scale_f32_32x32x64_f8f6f4 v[50:65], v[246:253], v[122:129], v[50:65], v194, v194 op_sel_hi:[0,0,0]
	v_mfma_scale_f32_32x32x64_f8f6f4 v[34:49], v[246:253], v[114:121], v[34:49], v194, v194 op_sel_hi:[0,0,0]
	v_mfma_scale_f32_32x32x64_f8f6f4 v[18:33], v[246:253], v[106:113], v[18:33], v194, v194 op_sel_hi:[0,0,0]
	v_mfma_scale_f32_32x32x64_f8f6f4 v[2:17], v[246:253], v[98:105], v[2:17], v194, v194 op_sel_hi:[0,0,0]
	v_max_f32_e32 v0, v66, v67
	v_max3_f32 v0, v0, v68, v69
	v_max3_f32 v0, v0, v70, v71
	v_max3_f32 v0, v0, v72, v73
	v_max3_f32 v0, v0, v74, v75
	v_max3_f32 v0, v0, v76, v77
	v_max3_f32 v0, v0, v78, v79
	v_max3_f32 v0, v0, v80, v81
	v_max_f32_e32 v177, v177, v0
	v_mov_b32_e32 v0, v177
	v_mov_b32_e32 v218, 1.0
	s_nop 0
	v_permlane32_swap_b32_e32 v177, v0
	v_max_f32_e32 v177, v177, v0
	v_cmp_ge_f32_e32 vcc, s90, v177
	s_cmp_eq_u64 vcc, exec
	s_cbranch_scc0 .Lmla_q1_newmax
.Lmla_q1_cont:
	v_mov_b32_e32 v0, v218
	s_branch .LBB0_1343
